# GEMM K-loops (all 9 instances): counted lgkmcnt waits inside each compute segment so MFMAs start as their fragments land (was lgkmcnt(0) before the first MFMA); on top of v53
# baseline (speedup 1.0000x reference)
.LBB0_135:
	ds_read_b128 v[170:173], v154
	ds_read_b128 v[174:177], v154 offset:1024
	ds_read_b128 v[186:189], v154 offset:2048
	ds_read_b128 v[190:193], v154 offset:3072
	s_add_u32 s24, s22, 0xfffc0080
	s_addc_u32 s25, s23, -1
	s_cmp_eq_u32 s86, 12
	s_cselect_b32 s73, s7, s25
	s_cselect_b32 s72, s9, s24
	s_cselect_b32 s25, s15, s85
	s_cselect_b32 s24, s83, s84
	v_lshl_add_u64 v[158:159], s[22:23], 0, v[138:139]
	s_add_i32 m0, s21, 0xc000
	ds_read_b128 v[196:199], v155
	ds_read_b128 v[200:203], v155 offset:1024
	ds_read_b128 v[204:207], v155 offset:2048
	ds_read_b128 v[208:211], v155 offset:3072
	ds_read_b128 v[212:215], v155 offset:4096
	ds_read_b128 v[216:219], v155 offset:5120
	ds_read_b128 v[220:223], v155 offset:6144
	ds_read_b128 v[224:227], v155 offset:7168
	global_load_lds_dwordx4 v[158:159], off
	v_lshl_add_u64 v[158:159], s[22:23], 0, v[140:141]
	s_add_i32 m0, s21, 0xe000
	s_nop 0
	global_load_lds_dwordx4 v[158:159], off
	s_waitcnt lgkmcnt(8)
	s_barrier
	s_nop 0
	s_setprio 1
	s_waitcnt lgkmcnt(7)
	v_mfma_f32_16x16x32_bf16 v[124:127], v[170:173], v[196:199], v[124:127]
	v_mfma_f32_16x16x32_bf16 v[120:123], v[186:189], v[196:199], v[120:123]
	s_waitcnt lgkmcnt(5)
	v_mfma_f32_16x16x32_bf16 v[108:111], v[170:173], v[204:207], v[108:111]
	v_mfma_f32_16x16x32_bf16 v[104:107], v[186:189], v[204:207], v[104:107]
	s_waitcnt lgkmcnt(3)
	v_mfma_f32_16x16x32_bf16 v[92:95], v[170:173], v[212:215], v[92:95]
	v_mfma_f32_16x16x32_bf16 v[88:91], v[186:189], v[212:215], v[88:91]
	s_waitcnt lgkmcnt(1)
	v_mfma_f32_16x16x32_bf16 v[76:79], v[170:173], v[220:223], v[76:79]
	v_mfma_f32_16x16x32_bf16 v[72:75], v[186:189], v[220:223], v[72:75]
	v_mfma_f32_16x16x32_bf16 v[124:127], v[174:177], v[200:203], v[124:127]
	v_mfma_f32_16x16x32_bf16 v[120:123], v[190:193], v[200:203], v[120:123]
	v_mfma_f32_16x16x32_bf16 v[108:111], v[174:177], v[208:211], v[108:111]
	v_mfma_f32_16x16x32_bf16 v[104:107], v[190:193], v[208:211], v[104:107]
	v_mfma_f32_16x16x32_bf16 v[92:95], v[174:177], v[216:219], v[92:95]
	v_mfma_f32_16x16x32_bf16 v[88:91], v[190:193], v[216:219], v[88:91]
	s_waitcnt lgkmcnt(0)
	v_mfma_f32_16x16x32_bf16 v[76:79], v[174:177], v[224:227], v[76:79]
	v_mfma_f32_16x16x32_bf16 v[72:75], v[190:193], v[224:227], v[72:75]
	s_setprio 0
	s_barrier
	s_add_i32 s28, s79, s27
	v_lshl_add_u64 v[158:159], s[24:25], 0, v[134:135]
	s_mov_b32 m0, s28
	ds_read_b128 v[228:231], v156
	ds_read_b128 v[232:235], v156 offset:1024
	ds_read_b128 v[236:239], v156 offset:2048
	ds_read_b128 v[240:243], v156 offset:3072
	global_load_lds_dwordx4 v[158:159], off
	v_lshl_add_u64 v[178:179], s[24:25], 0, v[130:131]
	s_add_i32 m0, s28, 0x2000
	s_nop 0
	global_load_lds_dwordx4 v[178:179], off
	s_barrier
	s_nop 0
	s_setprio 1
	s_waitcnt lgkmcnt(3)
	v_mfma_f32_16x16x32_bf16 v[116:119], v[228:231], v[196:199], v[116:119]
	s_waitcnt lgkmcnt(1)
	v_mfma_f32_16x16x32_bf16 v[112:115], v[236:239], v[196:199], v[112:115]
	v_mfma_f32_16x16x32_bf16 v[100:103], v[228:231], v[204:207], v[100:103]
	v_mfma_f32_16x16x32_bf16 v[96:99], v[236:239], v[204:207], v[96:99]
	v_mfma_f32_16x16x32_bf16 v[84:87], v[228:231], v[212:215], v[84:87]
	v_mfma_f32_16x16x32_bf16 v[80:83], v[236:239], v[212:215], v[80:83]
	v_mfma_f32_16x16x32_bf16 v[68:71], v[228:231], v[220:223], v[68:71]
	v_mfma_f32_16x16x32_bf16 v[64:67], v[236:239], v[220:223], v[64:67]
	v_mfma_f32_16x16x32_bf16 v[116:119], v[232:235], v[200:203], v[116:119]
	s_waitcnt lgkmcnt(0)
	v_mfma_f32_16x16x32_bf16 v[112:115], v[240:243], v[200:203], v[112:115]
	v_mfma_f32_16x16x32_bf16 v[100:103], v[232:235], v[208:211], v[100:103]
	v_mfma_f32_16x16x32_bf16 v[96:99], v[240:243], v[208:211], v[96:99]
	v_mfma_f32_16x16x32_bf16 v[84:87], v[232:235], v[216:219], v[84:87]
	v_mfma_f32_16x16x32_bf16 v[80:83], v[240:243], v[216:219], v[80:83]
	v_mfma_f32_16x16x32_bf16 v[68:71], v[232:235], v[224:227], v[68:71]
	v_mfma_f32_16x16x32_bf16 v[64:67], v[240:243], v[224:227], v[64:67]
	s_setprio 0
	s_mov_b32 m0, s21
	v_lshl_add_u64 v[244:245], s[72:73], 0, v[136:137]
	s_barrier
	ds_read_b128 v[196:199], v155 offset:16384
	ds_read_b128 v[200:203], v155 offset:17408
	ds_read_b128 v[204:207], v155 offset:18432
	ds_read_b128 v[208:211], v155 offset:19456
	ds_read_b128 v[212:215], v155 offset:20480
	ds_read_b128 v[216:219], v155 offset:21504
	ds_read_b128 v[220:223], v155 offset:22528
	ds_read_b128 v[224:227], v155 offset:23552
	global_load_lds_dwordx4 v[244:245], off
	v_lshl_add_u64 v[246:247], s[72:73], 0, v[132:133]
	s_mov_b32 m0, s64
	s_nop 0
	global_load_lds_dwordx4 v[246:247], off
	s_barrier
	s_nop 0
	s_setprio 1
	s_waitcnt lgkmcnt(7)
	v_mfma_f32_16x16x32_bf16 v[60:63], v[170:173], v[196:199], v[60:63]
	v_mfma_f32_16x16x32_bf16 v[56:59], v[186:189], v[196:199], v[56:59]
	s_waitcnt lgkmcnt(5)
	v_mfma_f32_16x16x32_bf16 v[44:47], v[170:173], v[204:207], v[44:47]
	v_mfma_f32_16x16x32_bf16 v[40:43], v[186:189], v[204:207], v[40:43]
	s_waitcnt lgkmcnt(3)
	v_mfma_f32_16x16x32_bf16 v[28:31], v[170:173], v[212:215], v[28:31]
	v_mfma_f32_16x16x32_bf16 v[24:27], v[186:189], v[212:215], v[24:27]
	s_waitcnt lgkmcnt(1)
	v_mfma_f32_16x16x32_bf16 v[12:15], v[170:173], v[220:223], v[12:15]
	v_mfma_f32_16x16x32_bf16 v[8:11], v[186:189], v[220:223], v[8:11]
	v_mfma_f32_16x16x32_bf16 v[60:63], v[174:177], v[200:203], v[60:63]
	v_mfma_f32_16x16x32_bf16 v[56:59], v[190:193], v[200:203], v[56:59]
	v_mfma_f32_16x16x32_bf16 v[44:47], v[174:177], v[208:211], v[44:47]
	v_mfma_f32_16x16x32_bf16 v[40:43], v[190:193], v[208:211], v[40:43]
	v_mfma_f32_16x16x32_bf16 v[28:31], v[174:177], v[216:219], v[28:31]
	v_mfma_f32_16x16x32_bf16 v[24:27], v[190:193], v[216:219], v[24:27]
	s_waitcnt lgkmcnt(0)
	v_mfma_f32_16x16x32_bf16 v[12:15], v[174:177], v[224:227], v[12:15]
	v_mfma_f32_16x16x32_bf16 v[8:11], v[190:193], v[224:227], v[8:11]
	s_setprio 0
	s_barrier
	s_add_u32 s28, s24, 0x40000
	s_addc_u32 s29, s25, 0
	s_add_i32 s87, s80, s27
	v_lshl_add_u64 v[170:171], s[28:29], 0, v[134:135]
	s_mov_b32 m0, s87
	s_nop 0
	global_load_lds_dwordx4 v[170:171], off
	v_lshl_add_u64 v[170:171], s[28:29], 0, v[130:131]
	s_add_i32 m0, s87, 0x2000
	s_nop 0
	global_load_lds_dwordx4 v[170:171], off
	s_waitcnt vmcnt(6)
	s_barrier
	s_setprio 1
	v_mfma_f32_16x16x32_bf16 v[52:55], v[228:231], v[196:199], v[52:55]
	v_mfma_f32_16x16x32_bf16 v[48:51], v[236:239], v[196:199], v[48:51]
	v_mfma_f32_16x16x32_bf16 v[36:39], v[228:231], v[204:207], v[36:39]
	v_mfma_f32_16x16x32_bf16 v[32:35], v[236:239], v[204:207], v[32:35]
	v_mfma_f32_16x16x32_bf16 v[20:23], v[228:231], v[212:215], v[20:23]
	v_mfma_f32_16x16x32_bf16 v[16:19], v[236:239], v[212:215], v[16:19]
	v_mfma_f32_16x16x32_bf16 v[4:7], v[228:231], v[220:223], v[4:7]
	v_mfma_f32_16x16x32_bf16 v[0:3], v[236:239], v[220:223], v[0:3]
	v_mfma_f32_16x16x32_bf16 v[52:55], v[232:235], v[200:203], v[52:55]
	v_mfma_f32_16x16x32_bf16 v[48:51], v[240:243], v[200:203], v[48:51]
	v_mfma_f32_16x16x32_bf16 v[36:39], v[232:235], v[208:211], v[36:39]
	v_mfma_f32_16x16x32_bf16 v[32:35], v[240:243], v[208:211], v[32:35]
	v_mfma_f32_16x16x32_bf16 v[20:23], v[232:235], v[216:219], v[20:23]
	v_mfma_f32_16x16x32_bf16 v[16:19], v[240:243], v[216:219], v[16:19]
	v_mfma_f32_16x16x32_bf16 v[4:7], v[232:235], v[224:227], v[4:7]
	v_mfma_f32_16x16x32_bf16 v[0:3], v[240:243], v[224:227], v[0:3]
	s_setprio 0
	s_add_i32 s87, 0, 0x18000
	v_add_u32_e32 v157, s87, v152
	s_barrier
	ds_read_b128 v[170:173], v157
	ds_read_b128 v[174:177], v157 offset:1024
	ds_read_b128 v[186:189], v157 offset:2048
	ds_read_b128 v[190:193], v157 offset:3072
	s_add_u32 s28, s72, 0x40000
	s_addc_u32 s29, s73, 0
	s_mov_b32 m0, s65
	v_lshl_add_u64 v[228:229], s[28:29], 0, v[136:137]
	ds_read_b128 v[196:199], v155 offset:32768
	ds_read_b128 v[200:203], v155 offset:33792
	ds_read_b128 v[204:207], v155 offset:34816
	ds_read_b128 v[208:211], v155 offset:35840
	ds_read_b128 v[212:215], v155 offset:36864
	ds_read_b128 v[216:219], v155 offset:37888
	ds_read_b128 v[220:223], v155 offset:38912
	ds_read_b128 v[224:227], v155 offset:39936
	global_load_lds_dwordx4 v[228:229], off
	v_lshl_add_u64 v[228:229], s[28:29], 0, v[132:133]
	s_mov_b32 m0, s70
	s_nop 0
	global_load_lds_dwordx4 v[228:229], off
	s_waitcnt lgkmcnt(8)
	s_barrier
	s_nop 0
	s_setprio 1
	s_waitcnt lgkmcnt(7)
	v_mfma_f32_16x16x32_bf16 v[124:127], v[170:173], v[196:199], v[124:127]
	v_mfma_f32_16x16x32_bf16 v[120:123], v[186:189], v[196:199], v[120:123]
	s_waitcnt lgkmcnt(5)
	v_mfma_f32_16x16x32_bf16 v[108:111], v[170:173], v[204:207], v[108:111]
	v_mfma_f32_16x16x32_bf16 v[104:107], v[186:189], v[204:207], v[104:107]
	s_waitcnt lgkmcnt(3)
	v_mfma_f32_16x16x32_bf16 v[92:95], v[170:173], v[212:215], v[92:95]
	v_mfma_f32_16x16x32_bf16 v[88:91], v[186:189], v[212:215], v[88:91]
	s_waitcnt lgkmcnt(1)
	v_mfma_f32_16x16x32_bf16 v[76:79], v[170:173], v[220:223], v[76:79]
	v_mfma_f32_16x16x32_bf16 v[72:75], v[186:189], v[220:223], v[72:75]
	v_mfma_f32_16x16x32_bf16 v[124:127], v[174:177], v[200:203], v[124:127]
	v_mfma_f32_16x16x32_bf16 v[120:123], v[190:193], v[200:203], v[120:123]
	v_mfma_f32_16x16x32_bf16 v[108:111], v[174:177], v[208:211], v[108:111]
	v_mfma_f32_16x16x32_bf16 v[104:107], v[190:193], v[208:211], v[104:107]
	v_mfma_f32_16x16x32_bf16 v[92:95], v[174:177], v[216:219], v[92:95]
	v_mfma_f32_16x16x32_bf16 v[88:91], v[190:193], v[216:219], v[88:91]
	s_waitcnt lgkmcnt(0)
	v_mfma_f32_16x16x32_bf16 v[76:79], v[174:177], v[224:227], v[76:79]
	v_mfma_f32_16x16x32_bf16 v[72:75], v[190:193], v[224:227], v[72:75]
	s_setprio 0
	s_barrier
	s_add_i32 s28, 0, 0x1c000
	s_add_i32 s29, s87, s27
	v_add_u32_e32 v157, s28, v152
	v_lshl_add_u64 v[158:159], v[158:159], 0, s[0:1]
	s_mov_b32 m0, s29
	ds_read_b128 v[228:231], v157
	ds_read_b128 v[232:235], v157 offset:1024
	ds_read_b128 v[236:239], v157 offset:2048
	ds_read_b128 v[240:243], v157 offset:3072
	global_load_lds_dwordx4 v[158:159], off
	v_lshl_add_u64 v[158:159], v[178:179], 0, s[0:1]
	s_add_i32 m0, s29, 0x2000
	s_nop 0
	global_load_lds_dwordx4 v[158:159], off
	s_barrier
	s_nop 0
	s_setprio 1
	s_waitcnt lgkmcnt(3)
	v_mfma_f32_16x16x32_bf16 v[116:119], v[228:231], v[196:199], v[116:119]
	s_waitcnt lgkmcnt(1)
	v_mfma_f32_16x16x32_bf16 v[112:115], v[236:239], v[196:199], v[112:115]
	v_mfma_f32_16x16x32_bf16 v[100:103], v[228:231], v[204:207], v[100:103]
	v_mfma_f32_16x16x32_bf16 v[96:99], v[236:239], v[204:207], v[96:99]
	v_mfma_f32_16x16x32_bf16 v[84:87], v[228:231], v[212:215], v[84:87]
	v_mfma_f32_16x16x32_bf16 v[80:83], v[236:239], v[212:215], v[80:83]
	v_mfma_f32_16x16x32_bf16 v[68:71], v[228:231], v[220:223], v[68:71]
	v_mfma_f32_16x16x32_bf16 v[64:67], v[236:239], v[220:223], v[64:67]
	v_mfma_f32_16x16x32_bf16 v[116:119], v[232:235], v[200:203], v[116:119]
	s_waitcnt lgkmcnt(0)
	v_mfma_f32_16x16x32_bf16 v[112:115], v[240:243], v[200:203], v[112:115]
	v_mfma_f32_16x16x32_bf16 v[100:103], v[232:235], v[208:211], v[100:103]
	v_mfma_f32_16x16x32_bf16 v[96:99], v[240:243], v[208:211], v[96:99]
	v_mfma_f32_16x16x32_bf16 v[84:87], v[232:235], v[216:219], v[84:87]
	v_mfma_f32_16x16x32_bf16 v[80:83], v[240:243], v[216:219], v[80:83]
	v_mfma_f32_16x16x32_bf16 v[68:71], v[232:235], v[224:227], v[68:71]
	v_mfma_f32_16x16x32_bf16 v[64:67], v[240:243], v[224:227], v[64:67]
	s_setprio 0
	s_mov_b32 m0, s75
	v_lshl_add_u64 v[158:159], v[244:245], 0, s[0:1]
	s_barrier
	ds_read_b128 v[196:199], v155 offset:49152
	ds_read_b128 v[200:203], v155 offset:50176
	ds_read_b128 v[204:207], v155 offset:51200
	ds_read_b128 v[208:211], v155 offset:52224
	ds_read_b128 v[212:215], v155 offset:53248
	ds_read_b128 v[216:219], v155 offset:54272
	ds_read_b128 v[220:223], v155 offset:55296
	ds_read_b128 v[224:227], v155 offset:56320
	global_load_lds_dwordx4 v[158:159], off
	v_lshl_add_u64 v[158:159], v[246:247], 0, s[0:1]
	s_mov_b32 m0, s76
	s_nop 0
	global_load_lds_dwordx4 v[158:159], off
	s_barrier
	s_nop 0
	s_setprio 1
	s_waitcnt lgkmcnt(7)
	v_mfma_f32_16x16x32_bf16 v[60:63], v[170:173], v[196:199], v[60:63]
	v_mfma_f32_16x16x32_bf16 v[56:59], v[186:189], v[196:199], v[56:59]
	s_waitcnt lgkmcnt(5)
	v_mfma_f32_16x16x32_bf16 v[44:47], v[170:173], v[204:207], v[44:47]
	v_mfma_f32_16x16x32_bf16 v[40:43], v[186:189], v[204:207], v[40:43]
	s_waitcnt lgkmcnt(3)
	v_mfma_f32_16x16x32_bf16 v[28:31], v[170:173], v[212:215], v[28:31]
	v_mfma_f32_16x16x32_bf16 v[24:27], v[186:189], v[212:215], v[24:27]
	s_waitcnt lgkmcnt(1)
	v_mfma_f32_16x16x32_bf16 v[12:15], v[170:173], v[220:223], v[12:15]
	v_mfma_f32_16x16x32_bf16 v[8:11], v[186:189], v[220:223], v[8:11]
	v_mfma_f32_16x16x32_bf16 v[60:63], v[174:177], v[200:203], v[60:63]
	v_mfma_f32_16x16x32_bf16 v[56:59], v[190:193], v[200:203], v[56:59]
	v_mfma_f32_16x16x32_bf16 v[44:47], v[174:177], v[208:211], v[44:47]
	v_mfma_f32_16x16x32_bf16 v[40:43], v[190:193], v[208:211], v[40:43]
	v_mfma_f32_16x16x32_bf16 v[28:31], v[174:177], v[216:219], v[28:31]
	v_mfma_f32_16x16x32_bf16 v[24:27], v[190:193], v[216:219], v[24:27]
	s_waitcnt lgkmcnt(0)
	v_mfma_f32_16x16x32_bf16 v[12:15], v[174:177], v[224:227], v[12:15]
	v_mfma_f32_16x16x32_bf16 v[8:11], v[190:193], v[224:227], v[8:11]
	s_setprio 0
	s_barrier
	s_add_u32 s24, s24, 0x40080
	s_addc_u32 s25, s25, 0
	s_add_i32 s28, s28, s27
	v_lshl_add_u64 v[158:159], s[24:25], 0, v[134:135]
	s_mov_b32 m0, s28
	s_nop 0
	global_load_lds_dwordx4 v[158:159], off
	v_lshl_add_u64 v[158:159], s[24:25], 0, v[130:131]
	s_add_i32 m0, s28, 0x2000
	s_nop 0
	global_load_lds_dwordx4 v[158:159], off
	s_waitcnt vmcnt(6)
	s_barrier
	s_setprio 1
	v_mfma_f32_16x16x32_bf16 v[52:55], v[228:231], v[196:199], v[52:55]
	v_mfma_f32_16x16x32_bf16 v[48:51], v[236:239], v[196:199], v[48:51]
	v_mfma_f32_16x16x32_bf16 v[36:39], v[228:231], v[204:207], v[36:39]
	v_mfma_f32_16x16x32_bf16 v[32:35], v[236:239], v[204:207], v[32:35]
	v_mfma_f32_16x16x32_bf16 v[20:23], v[228:231], v[212:215], v[20:23]
	v_mfma_f32_16x16x32_bf16 v[16:19], v[236:239], v[212:215], v[16:19]
	v_mfma_f32_16x16x32_bf16 v[4:7], v[228:231], v[220:223], v[4:7]
	v_mfma_f32_16x16x32_bf16 v[0:3], v[236:239], v[220:223], v[0:3]
	v_mfma_f32_16x16x32_bf16 v[52:55], v[232:235], v[200:203], v[52:55]
	v_mfma_f32_16x16x32_bf16 v[48:51], v[240:243], v[200:203], v[48:51]
	v_mfma_f32_16x16x32_bf16 v[36:39], v[232:235], v[208:211], v[36:39]
	v_mfma_f32_16x16x32_bf16 v[32:35], v[240:243], v[208:211], v[32:35]
	v_mfma_f32_16x16x32_bf16 v[20:23], v[232:235], v[216:219], v[20:23]
	v_mfma_f32_16x16x32_bf16 v[16:19], v[240:243], v[216:219], v[16:19]
	v_mfma_f32_16x16x32_bf16 v[4:7], v[232:235], v[224:227], v[4:7]
	v_mfma_f32_16x16x32_bf16 v[0:3], v[240:243], v[224:227], v[0:3]
	s_setprio 0
	s_add_i32 s86, s86, 2
	s_add_u32 s22, s22, 0x100
	s_addc_u32 s23, s23, 0
	s_add_u32 s84, s84, 0x100
	s_addc_u32 s85, s85, 0
	s_cmp_gt_u32 s86, 13
	s_barrier
	s_cbranch_scc0 .LBB0_135
	v_mul_f32_e32 v169, 0xbfb8aa3b, v124
	v_mul_f32_e32 v170, 0xbfb8aa3b, v120
	v_exp_f32_e32 v169, v169
	v_exp_f32_e32 v171, v170
	v_mul_f32_e32 v170, 0xbfb8aa3b, v125
	v_exp_f32_e32 v172, v170
	v_add_f32_e32 v169, 1.0, v169
	v_rcp_f32_e32 v170, v169
	v_add_f32_e32 v169, 1.0, v171
	v_add_f32_e32 v171, 1.0, v172
	v_rcp_f32_e32 v171, v171
	v_mul_f32_e32 v172, 0xbfb8aa3b, v121
	v_exp_f32_e32 v173, v172
	v_rcp_f32_e32 v172, v169
	v_pk_mul_f32 v[124:125], v[124:125], v[170:171]
	v_mul_f32_e32 v169, 0xbfb8aa3b, v127
	v_pk_mul_f32 v[116:117], v[124:125], v[116:117]
	v_add_f32_e32 v124, 1.0, v173
	v_mul_f32_e32 v125, 0xbfb8aa3b, v122
	v_rcp_f32_e32 v173, v124
	v_mul_f32_e32 v124, 0xbfb8aa3b, v126
	v_exp_f32_e32 v125, v125
	v_exp_f32_e32 v124, v124
	v_exp_f32_e32 v169, v169
	v_mul_f32_e32 v170, 0xbfb8aa3b, v123
	v_exp_f32_e32 v171, v170
	v_add_f32_e32 v125, 1.0, v125
	v_add_f32_e32 v124, 1.0, v124
	v_rcp_f32_e32 v170, v125
	v_add_f32_e32 v125, 1.0, v169
	v_rcp_f32_e32 v124, v124
	v_rcp_f32_e32 v125, v125
	v_add_f32_e32 v169, 1.0, v171
	v_rcp_f32_e32 v171, v169
	v_pk_mul_f32 v[120:121], v[120:121], v[172:173]
	v_lshl_or_b32 v158, s82, 7, v153
	v_pk_mul_f32 v[112:113], v[120:121], v[112:113]
	v_pk_mul_f32 v[120:121], v[126:127], v[124:125]
	v_lshl_add_u32 v157, s20, 8, v145
	v_pk_mul_f32 v[118:119], v[120:121], v[118:119]
	v_pk_mul_f32 v[120:121], v[122:123], v[170:171]
	v_ashrrev_i32_e32 v159, 31, v158
	v_pk_mul_f32 v[114:115], v[120:121], v[114:115]
	v_cvt_pk_bf16_f32 v116, v116, v117
	v_cvt_pk_bf16_f32 v117, v118, v119
	v_cvt_pk_bf16_f32 v118, v112, v113
	v_mov_b64_e32 v[112:113], s[58:59]
	v_cvt_pk_bf16_f32 v119, v114, v115
	v_mad_i64_i32 v[120:121], s[22:23], v157, s81, v[112:113]
	v_lshlrev_b64 v[114:115], 1, v[158:159]
	v_lshl_add_u64 v[120:121], v[120:121], 0, v[114:115]
	global_store_dwordx4 v[120:121], v[116:119], off
	s_and_b64 vcc, exec, s[4:5]
	s_mov_b32 s82, s14
	v_mul_f32_e32 v116, 0xbfb8aa3b, v108
	v_mul_f32_e32 v117, 0xbfb8aa3b, v104
	v_mul_f32_e32 v118, 0xbfb8aa3b, v109
	v_exp_f32_e32 v116, v116
	v_exp_f32_e32 v117, v117
	v_exp_f32_e32 v118, v118
	s_mov_b32 s20, s8
	v_add_f32_e32 v116, 1.0, v116
	v_add_f32_e32 v119, 1.0, v117
	v_add_f32_e32 v117, 1.0, v118
	v_rcp_f32_e32 v116, v116
	v_rcp_f32_e32 v117, v117
	v_mul_f32_e32 v118, 0xbfb8aa3b, v105
	v_exp_f32_e32 v120, v118
	v_rcp_f32_e32 v118, v119
	v_pk_mul_f32 v[108:109], v[108:109], v[116:117]
	v_mul_f32_e32 v116, 0xbfb8aa3b, v111
	v_pk_mul_f32 v[100:101], v[108:109], v[100:101]
	v_add_f32_e32 v108, 1.0, v120
	v_rcp_f32_e32 v119, v108
	v_mul_f32_e32 v109, 0xbfb8aa3b, v106
	v_mul_f32_e32 v108, 0xbfb8aa3b, v110
	v_exp_f32_e32 v109, v109
	v_exp_f32_e32 v108, v108
	v_exp_f32_e32 v117, v116
	v_mul_f32_e32 v116, 0xbfb8aa3b, v107
	v_pk_mul_f32 v[104:105], v[104:105], v[118:119]
	v_exp_f32_e32 v118, v116
	v_add_f32_e32 v109, 1.0, v109
	v_add_f32_e32 v108, 1.0, v108
	v_rcp_f32_e32 v116, v109
	v_add_f32_e32 v109, 1.0, v117
	v_rcp_f32_e32 v108, v108
	v_rcp_f32_e32 v109, v109
	v_add_f32_e32 v117, 1.0, v118
	v_rcp_f32_e32 v117, v117
	v_pk_mul_f32 v[104:105], v[104:105], v[96:97]
	v_pk_mul_f32 v[96:97], v[110:111], v[108:109]
	s_mov_b64 s[24:25], s[18:19]
	v_pk_mul_f32 v[102:103], v[96:97], v[102:103]
	v_pk_mul_f32 v[96:97], v[106:107], v[116:117]
	s_nop 0
	v_pk_mul_f32 v[106:107], v[96:97], v[98:99]
	v_cvt_pk_bf16_f32 v96, v100, v101
	v_or_b32_e32 v100, 16, v157
	v_mad_i64_i32 v[100:101], s[22:23], v100, s81, v[112:113]
	v_cvt_pk_bf16_f32 v97, v102, v103
	v_cvt_pk_bf16_f32 v98, v104, v105
	v_cvt_pk_bf16_f32 v99, v106, v107
	v_lshl_add_u64 v[100:101], v[100:101], 0, v[114:115]
	global_store_dwordx4 v[100:101], v[96:99], off
	s_nop 1
	v_mul_f32_e32 v96, 0xbfb8aa3b, v92
	v_mul_f32_e32 v97, 0xbfb8aa3b, v88
	v_mul_f32_e32 v98, 0xbfb8aa3b, v93
	v_exp_f32_e32 v96, v96
	v_exp_f32_e32 v97, v97
	v_exp_f32_e32 v98, v98
	v_add_f32_e32 v96, 1.0, v96
	v_add_f32_e32 v99, 1.0, v97
	v_add_f32_e32 v97, 1.0, v98
	v_rcp_f32_e32 v96, v96
	v_rcp_f32_e32 v97, v97
	v_mul_f32_e32 v98, 0xbfb8aa3b, v89
	v_exp_f32_e32 v100, v98
	v_rcp_f32_e32 v98, v99
	v_pk_mul_f32 v[92:93], v[92:93], v[96:97]
	v_mul_f32_e32 v96, 0xbfb8aa3b, v95
	v_pk_mul_f32 v[84:85], v[92:93], v[84:85]
	v_add_f32_e32 v92, 1.0, v100
	v_rcp_f32_e32 v99, v92
	v_mul_f32_e32 v93, 0xbfb8aa3b, v90
	v_mul_f32_e32 v92, 0xbfb8aa3b, v94
	v_exp_f32_e32 v93, v93
	v_exp_f32_e32 v92, v92
	v_exp_f32_e32 v97, v96
	v_mul_f32_e32 v96, 0xbfb8aa3b, v91
	v_pk_mul_f32 v[88:89], v[88:89], v[98:99]
	v_exp_f32_e32 v98, v96
	v_add_f32_e32 v93, 1.0, v93
	v_add_f32_e32 v92, 1.0, v92
	v_rcp_f32_e32 v96, v93
	v_add_f32_e32 v93, 1.0, v97
	v_rcp_f32_e32 v92, v92
	v_rcp_f32_e32 v93, v93
	v_add_f32_e32 v97, 1.0, v98
	v_rcp_f32_e32 v97, v97
	v_pk_mul_f32 v[88:89], v[88:89], v[80:81]
	v_pk_mul_f32 v[80:81], v[94:95], v[92:93]
	s_nop 0
	v_pk_mul_f32 v[86:87], v[80:81], v[86:87]
	v_pk_mul_f32 v[80:81], v[90:91], v[96:97]
	s_nop 0
	v_pk_mul_f32 v[90:91], v[80:81], v[82:83]
	v_cvt_pk_bf16_f32 v80, v84, v85
	v_or_b32_e32 v84, 32, v157
	v_mad_i64_i32 v[84:85], s[22:23], v84, s81, v[112:113]
	v_cvt_pk_bf16_f32 v81, v86, v87
	v_cvt_pk_bf16_f32 v82, v88, v89
	v_cvt_pk_bf16_f32 v83, v90, v91
	v_lshl_add_u64 v[84:85], v[84:85], 0, v[114:115]
	global_store_dwordx4 v[84:85], v[80:83], off
	s_nop 1
	v_mul_f32_e32 v80, 0xbfb8aa3b, v76
	v_mul_f32_e32 v81, 0xbfb8aa3b, v72
	v_mul_f32_e32 v82, 0xbfb8aa3b, v77
	v_exp_f32_e32 v80, v80
	v_exp_f32_e32 v81, v81
	v_exp_f32_e32 v82, v82
	v_add_f32_e32 v80, 1.0, v80
	v_add_f32_e32 v83, 1.0, v81
	v_add_f32_e32 v81, 1.0, v82
	v_rcp_f32_e32 v80, v80
	v_rcp_f32_e32 v81, v81
	v_mul_f32_e32 v82, 0xbfb8aa3b, v73
	v_exp_f32_e32 v84, v82
	v_rcp_f32_e32 v82, v83
	v_pk_mul_f32 v[76:77], v[76:77], v[80:81]
	v_mul_f32_e32 v80, 0xbfb8aa3b, v79
	v_pk_mul_f32 v[68:69], v[76:77], v[68:69]
	v_add_f32_e32 v76, 1.0, v84
	v_rcp_f32_e32 v83, v76
	v_mul_f32_e32 v77, 0xbfb8aa3b, v74
	v_mul_f32_e32 v76, 0xbfb8aa3b, v78
	v_exp_f32_e32 v77, v77
	v_exp_f32_e32 v76, v76
	v_exp_f32_e32 v81, v80
	v_mul_f32_e32 v80, 0xbfb8aa3b, v75
	v_pk_mul_f32 v[72:73], v[72:73], v[82:83]
	v_exp_f32_e32 v82, v80
	v_add_f32_e32 v77, 1.0, v77
	v_add_f32_e32 v76, 1.0, v76
	v_rcp_f32_e32 v80, v77
	v_add_f32_e32 v77, 1.0, v81
	v_rcp_f32_e32 v76, v76
	v_rcp_f32_e32 v77, v77
	v_add_f32_e32 v81, 1.0, v82
	v_rcp_f32_e32 v81, v81
	v_pk_mul_f32 v[72:73], v[72:73], v[64:65]
	v_pk_mul_f32 v[64:65], v[78:79], v[76:77]
	s_nop 0
	v_pk_mul_f32 v[70:71], v[64:65], v[70:71]
	v_pk_mul_f32 v[64:65], v[74:75], v[80:81]
	s_nop 0
	v_pk_mul_f32 v[74:75], v[64:65], v[66:67]
	v_cvt_pk_bf16_f32 v64, v68, v69
	v_or_b32_e32 v68, 48, v157
	v_mad_i64_i32 v[68:69], s[22:23], v68, s81, v[112:113]
	v_cvt_pk_bf16_f32 v65, v70, v71
	v_cvt_pk_bf16_f32 v66, v72, v73
	v_cvt_pk_bf16_f32 v67, v74, v75
	v_lshl_add_u64 v[68:69], v[68:69], 0, v[114:115]
	global_store_dwordx4 v[68:69], v[64:67], off
	v_add_u32_e32 v68, 0x80, v157
	s_nop 0
	v_mul_f32_e32 v64, 0xbfb8aa3b, v60
	v_mul_f32_e32 v65, 0xbfb8aa3b, v56
	v_mul_f32_e32 v66, 0xbfb8aa3b, v61
	v_exp_f32_e32 v64, v64
	v_exp_f32_e32 v65, v65
	v_exp_f32_e32 v66, v66
	v_add_f32_e32 v64, 1.0, v64
	v_add_f32_e32 v67, 1.0, v65
	v_add_f32_e32 v65, 1.0, v66
	v_rcp_f32_e32 v64, v64
	v_rcp_f32_e32 v65, v65
	v_mul_f32_e32 v66, 0xbfb8aa3b, v57
	v_exp_f32_e32 v69, v66
	v_rcp_f32_e32 v66, v67
	v_pk_mul_f32 v[60:61], v[60:61], v[64:65]
	v_mul_f32_e32 v64, 0xbfb8aa3b, v63
	v_pk_mul_f32 v[52:53], v[60:61], v[52:53]
	v_add_f32_e32 v60, 1.0, v69
	v_rcp_f32_e32 v67, v60
	v_mul_f32_e32 v61, 0xbfb8aa3b, v58
	v_mul_f32_e32 v60, 0xbfb8aa3b, v62
	v_exp_f32_e32 v61, v61
	v_exp_f32_e32 v60, v60
	v_exp_f32_e32 v65, v64
	v_mul_f32_e32 v64, 0xbfb8aa3b, v59
	v_pk_mul_f32 v[56:57], v[56:57], v[66:67]
	v_exp_f32_e32 v66, v64
	v_add_f32_e32 v61, 1.0, v61
	v_add_f32_e32 v60, 1.0, v60
	v_rcp_f32_e32 v64, v61
	v_add_f32_e32 v61, 1.0, v65
	v_rcp_f32_e32 v60, v60
	v_rcp_f32_e32 v61, v61
	v_add_f32_e32 v65, 1.0, v66
	v_rcp_f32_e32 v65, v65
	v_pk_mul_f32 v[56:57], v[56:57], v[48:49]
	v_pk_mul_f32 v[48:49], v[62:63], v[60:61]
	s_nop 0
	v_pk_mul_f32 v[54:55], v[48:49], v[54:55]
	v_pk_mul_f32 v[48:49], v[58:59], v[64:65]
	s_nop 0
	v_pk_mul_f32 v[58:59], v[48:49], v[50:51]
	v_cvt_pk_bf16_f32 v48, v52, v53
	v_mad_i64_i32 v[52:53], s[22:23], v68, s81, v[112:113]
	v_cvt_pk_bf16_f32 v49, v54, v55
	v_cvt_pk_bf16_f32 v50, v56, v57
	v_cvt_pk_bf16_f32 v51, v58, v59
	v_lshl_add_u64 v[52:53], v[52:53], 0, v[114:115]
	global_store_dwordx4 v[52:53], v[48:51], off
	s_nop 1
	v_mul_f32_e32 v48, 0xbfb8aa3b, v44
	v_mul_f32_e32 v49, 0xbfb8aa3b, v40
	v_mul_f32_e32 v50, 0xbfb8aa3b, v45
	v_exp_f32_e32 v48, v48
	v_exp_f32_e32 v49, v49
	v_exp_f32_e32 v50, v50
	v_add_f32_e32 v48, 1.0, v48
	v_add_f32_e32 v51, 1.0, v49
	v_add_f32_e32 v49, 1.0, v50
	v_rcp_f32_e32 v48, v48
	v_rcp_f32_e32 v49, v49
	v_mul_f32_e32 v50, 0xbfb8aa3b, v41
	v_exp_f32_e32 v52, v50
	v_rcp_f32_e32 v50, v51
	v_pk_mul_f32 v[44:45], v[44:45], v[48:49]
	v_mul_f32_e32 v48, 0xbfb8aa3b, v47
	v_pk_mul_f32 v[36:37], v[44:45], v[36:37]
	v_add_f32_e32 v44, 1.0, v52
	v_rcp_f32_e32 v51, v44
	v_mul_f32_e32 v45, 0xbfb8aa3b, v42
	v_mul_f32_e32 v44, 0xbfb8aa3b, v46
	v_exp_f32_e32 v45, v45
	v_exp_f32_e32 v44, v44
	v_exp_f32_e32 v49, v48
	v_mul_f32_e32 v48, 0xbfb8aa3b, v43
	v_pk_mul_f32 v[40:41], v[40:41], v[50:51]
	v_exp_f32_e32 v50, v48
	v_add_f32_e32 v45, 1.0, v45
	v_add_f32_e32 v44, 1.0, v44
	v_rcp_f32_e32 v48, v45
	v_add_f32_e32 v45, 1.0, v49
	v_rcp_f32_e32 v44, v44
	v_rcp_f32_e32 v45, v45
	v_add_f32_e32 v49, 1.0, v50
	v_rcp_f32_e32 v49, v49
	v_pk_mul_f32 v[40:41], v[40:41], v[32:33]
	v_pk_mul_f32 v[32:33], v[46:47], v[44:45]
	s_nop 0
	v_pk_mul_f32 v[38:39], v[32:33], v[38:39]
	v_pk_mul_f32 v[32:33], v[42:43], v[48:49]
	s_nop 0
	v_pk_mul_f32 v[42:43], v[32:33], v[34:35]
	v_cvt_pk_bf16_f32 v32, v36, v37
	v_add_u32_e32 v36, 0x90, v157
	v_mad_i64_i32 v[36:37], s[22:23], v36, s81, v[112:113]
	v_cvt_pk_bf16_f32 v33, v38, v39
	v_cvt_pk_bf16_f32 v34, v40, v41
	v_cvt_pk_bf16_f32 v35, v42, v43
	v_lshl_add_u64 v[36:37], v[36:37], 0, v[114:115]
	global_store_dwordx4 v[36:37], v[32:35], off
	s_nop 1
	v_mul_f32_e32 v32, 0xbfb8aa3b, v28
	v_mul_f32_e32 v33, 0xbfb8aa3b, v24
	v_mul_f32_e32 v34, 0xbfb8aa3b, v29
	v_exp_f32_e32 v32, v32
	v_exp_f32_e32 v33, v33
	v_exp_f32_e32 v34, v34
	v_add_f32_e32 v32, 1.0, v32
	v_add_f32_e32 v35, 1.0, v33
	v_add_f32_e32 v33, 1.0, v34
	v_rcp_f32_e32 v32, v32
	v_rcp_f32_e32 v33, v33
	v_mul_f32_e32 v34, 0xbfb8aa3b, v25
	v_exp_f32_e32 v36, v34
	v_rcp_f32_e32 v34, v35
	v_pk_mul_f32 v[28:29], v[28:29], v[32:33]
	v_mul_f32_e32 v32, 0xbfb8aa3b, v31
	v_pk_mul_f32 v[20:21], v[28:29], v[20:21]
	v_add_f32_e32 v28, 1.0, v36
	v_rcp_f32_e32 v35, v28
	v_mul_f32_e32 v29, 0xbfb8aa3b, v26
	v_mul_f32_e32 v28, 0xbfb8aa3b, v30
	v_exp_f32_e32 v29, v29
	v_exp_f32_e32 v28, v28
	v_exp_f32_e32 v33, v32
	v_mul_f32_e32 v32, 0xbfb8aa3b, v27
	v_pk_mul_f32 v[24:25], v[24:25], v[34:35]
	v_exp_f32_e32 v34, v32
	v_add_f32_e32 v29, 1.0, v29
	v_add_f32_e32 v28, 1.0, v28
	v_rcp_f32_e32 v32, v29
	v_add_f32_e32 v29, 1.0, v33
	v_rcp_f32_e32 v28, v28
	v_rcp_f32_e32 v29, v29
	v_add_f32_e32 v33, 1.0, v34
	v_rcp_f32_e32 v33, v33
	v_pk_mul_f32 v[24:25], v[24:25], v[16:17]
	v_pk_mul_f32 v[16:17], v[30:31], v[28:29]
	s_nop 0
	v_pk_mul_f32 v[22:23], v[16:17], v[22:23]
	v_pk_mul_f32 v[16:17], v[26:27], v[32:33]
	s_nop 0
	v_pk_mul_f32 v[26:27], v[16:17], v[18:19]
	v_cvt_pk_bf16_f32 v16, v20, v21
	v_add_u32_e32 v20, 0xa0, v157
	v_mad_i64_i32 v[20:21], s[22:23], v20, s81, v[112:113]
	v_cvt_pk_bf16_f32 v17, v22, v23
	v_cvt_pk_bf16_f32 v18, v24, v25
	v_cvt_pk_bf16_f32 v19, v26, v27
	v_lshl_add_u64 v[20:21], v[20:21], 0, v[114:115]
	global_store_dwordx4 v[20:21], v[16:19], off
	s_nop 1
	v_mul_f32_e32 v16, 0xbfb8aa3b, v12
	v_mul_f32_e32 v17, 0xbfb8aa3b, v8
	v_mul_f32_e32 v18, 0xbfb8aa3b, v13
	v_exp_f32_e32 v16, v16
	v_exp_f32_e32 v17, v17
	v_exp_f32_e32 v18, v18
	v_add_f32_e32 v16, 1.0, v16
	v_add_f32_e32 v19, 1.0, v17
	v_add_f32_e32 v17, 1.0, v18
	v_rcp_f32_e32 v16, v16
	v_rcp_f32_e32 v17, v17
	v_mul_f32_e32 v18, 0xbfb8aa3b, v9
	v_exp_f32_e32 v20, v18
	v_rcp_f32_e32 v18, v19
	v_pk_mul_f32 v[12:13], v[12:13], v[16:17]
	v_mul_f32_e32 v16, 0xbfb8aa3b, v15
	v_pk_mul_f32 v[4:5], v[12:13], v[4:5]
	v_add_f32_e32 v12, 1.0, v20
	v_rcp_f32_e32 v19, v12
	v_mul_f32_e32 v13, 0xbfb8aa3b, v10
	v_mul_f32_e32 v12, 0xbfb8aa3b, v14
	v_exp_f32_e32 v13, v13
	v_exp_f32_e32 v12, v12
	v_exp_f32_e32 v17, v16
	v_mul_f32_e32 v16, 0xbfb8aa3b, v11
	v_pk_mul_f32 v[8:9], v[8:9], v[18:19]
	v_exp_f32_e32 v18, v16
	v_add_f32_e32 v13, 1.0, v13
	v_add_f32_e32 v12, 1.0, v12
	v_rcp_f32_e32 v16, v13
	v_add_f32_e32 v13, 1.0, v17
	v_rcp_f32_e32 v12, v12
	v_rcp_f32_e32 v13, v13
	v_add_f32_e32 v17, 1.0, v18
	v_rcp_f32_e32 v17, v17
	v_pk_mul_f32 v[8:9], v[8:9], v[0:1]
	v_pk_mul_f32 v[0:1], v[14:15], v[12:13]
	s_nop 0
	v_pk_mul_f32 v[6:7], v[0:1], v[6:7]
	v_pk_mul_f32 v[0:1], v[10:11], v[16:17]
	s_nop 0
	v_pk_mul_f32 v[10:11], v[0:1], v[2:3]
	v_cvt_pk_bf16_f32 v0, v4, v5
	v_add_u32_e32 v4, 0xb0, v157
	v_mad_i64_i32 v[4:5], s[22:23], v4, s81, v[112:113]
	v_cvt_pk_bf16_f32 v1, v6, v7
	v_cvt_pk_bf16_f32 v2, v8, v9
	v_cvt_pk_bf16_f32 v3, v10, v11
	v_lshl_add_u64 v[4:5], v[4:5], 0, v[114:115]
	s_mov_b64 s[22:23], s[16:17]
	global_store_dwordx4 v[4:5], v[0:3], off
	s_cbranch_vccz .LBB0_132
	s_waitcnt vmcnt(0)
	s_cmpk_gt_u32 s26, 0xff
	s_cbranch_scc1 .LBB0_139
	s_barrier

.LBB0_203:
	ds_read_b128 v[170:173], v154
	ds_read_b128 v[174:177], v154 offset:1024
	ds_read_b128 v[186:189], v154 offset:2048
	ds_read_b128 v[190:193], v154 offset:3072
	s_add_u32 s20, s18, 0xfff50080
	s_addc_u32 s21, s19, -1
	s_cmp_eq_u32 s89, 40
	s_cselect_b32 s23, s1, s21
	s_cselect_b32 s22, s0, s20
	s_cselect_b32 s21, s7, s88
	s_cselect_b32 s20, s6, s87
	v_lshl_add_u64 v[158:159], s[18:19], 0, v[138:139]
	s_add_i32 m0, s64, 0xc000
	ds_read_b128 v[196:199], v155
	ds_read_b128 v[200:203], v155 offset:1024
	ds_read_b128 v[204:207], v155 offset:2048
	ds_read_b128 v[208:211], v155 offset:3072
	ds_read_b128 v[212:215], v155 offset:4096
	ds_read_b128 v[216:219], v155 offset:5120
	ds_read_b128 v[220:223], v155 offset:6144
	ds_read_b128 v[224:227], v155 offset:7168
	global_load_lds_dwordx4 v[158:159], off
	v_lshl_add_u64 v[158:159], s[18:19], 0, v[140:141]
	s_add_i32 m0, s64, 0xe000
	s_nop 0
	global_load_lds_dwordx4 v[158:159], off
	s_waitcnt lgkmcnt(8)
	s_barrier
	s_nop 0
	s_setprio 1
	s_waitcnt lgkmcnt(7)
	v_mfma_f32_16x16x32_bf16 v[124:127], v[170:173], v[196:199], v[124:127]
	v_mfma_f32_16x16x32_bf16 v[120:123], v[186:189], v[196:199], v[120:123]
	s_waitcnt lgkmcnt(5)
	v_mfma_f32_16x16x32_bf16 v[116:119], v[170:173], v[204:207], v[116:119]
	v_mfma_f32_16x16x32_bf16 v[112:115], v[186:189], v[204:207], v[112:115]
	s_waitcnt lgkmcnt(3)
	v_mfma_f32_16x16x32_bf16 v[100:103], v[170:173], v[212:215], v[100:103]
	v_mfma_f32_16x16x32_bf16 v[96:99], v[186:189], v[212:215], v[96:99]
	s_waitcnt lgkmcnt(1)
	v_mfma_f32_16x16x32_bf16 v[84:87], v[170:173], v[220:223], v[84:87]
	v_mfma_f32_16x16x32_bf16 v[80:83], v[186:189], v[220:223], v[80:83]
	v_mfma_f32_16x16x32_bf16 v[124:127], v[174:177], v[200:203], v[124:127]
	v_mfma_f32_16x16x32_bf16 v[120:123], v[190:193], v[200:203], v[120:123]
	v_mfma_f32_16x16x32_bf16 v[116:119], v[174:177], v[208:211], v[116:119]
	v_mfma_f32_16x16x32_bf16 v[112:115], v[190:193], v[208:211], v[112:115]
	v_mfma_f32_16x16x32_bf16 v[100:103], v[174:177], v[216:219], v[100:103]
	v_mfma_f32_16x16x32_bf16 v[96:99], v[190:193], v[216:219], v[96:99]
	s_waitcnt lgkmcnt(0)
	v_mfma_f32_16x16x32_bf16 v[84:87], v[174:177], v[224:227], v[84:87]
	v_mfma_f32_16x16x32_bf16 v[80:83], v[190:193], v[224:227], v[80:83]
	s_setprio 0
	s_barrier
	s_add_i32 s28, s78, s27
	v_lshl_add_u64 v[158:159], s[20:21], 0, v[134:135]
	s_mov_b32 m0, s28
	ds_read_b128 v[228:231], v156
	ds_read_b128 v[232:235], v156 offset:1024
	ds_read_b128 v[236:239], v156 offset:2048
	ds_read_b128 v[240:243], v156 offset:3072
	global_load_lds_dwordx4 v[158:159], off
	v_lshl_add_u64 v[178:179], s[20:21], 0, v[130:131]
	s_add_i32 m0, s28, 0x2000
	s_nop 0
	global_load_lds_dwordx4 v[178:179], off
	s_barrier
	s_nop 0
	s_setprio 1
	s_waitcnt lgkmcnt(3)
	v_mfma_f32_16x16x32_bf16 v[108:111], v[228:231], v[196:199], v[108:111]
	s_waitcnt lgkmcnt(1)
	v_mfma_f32_16x16x32_bf16 v[104:107], v[236:239], v[196:199], v[104:107]
	v_mfma_f32_16x16x32_bf16 v[92:95], v[228:231], v[204:207], v[92:95]
	v_mfma_f32_16x16x32_bf16 v[88:91], v[236:239], v[204:207], v[88:91]
	v_mfma_f32_16x16x32_bf16 v[76:79], v[228:231], v[212:215], v[76:79]
	v_mfma_f32_16x16x32_bf16 v[72:75], v[236:239], v[212:215], v[72:75]
	v_mfma_f32_16x16x32_bf16 v[68:71], v[228:231], v[220:223], v[68:71]
	v_mfma_f32_16x16x32_bf16 v[64:67], v[236:239], v[220:223], v[64:67]
	v_mfma_f32_16x16x32_bf16 v[108:111], v[232:235], v[200:203], v[108:111]
	s_waitcnt lgkmcnt(0)
	v_mfma_f32_16x16x32_bf16 v[104:107], v[240:243], v[200:203], v[104:107]
	v_mfma_f32_16x16x32_bf16 v[92:95], v[232:235], v[208:211], v[92:95]
	v_mfma_f32_16x16x32_bf16 v[88:91], v[240:243], v[208:211], v[88:91]
	v_mfma_f32_16x16x32_bf16 v[76:79], v[232:235], v[216:219], v[76:79]
	v_mfma_f32_16x16x32_bf16 v[72:75], v[240:243], v[216:219], v[72:75]
	v_mfma_f32_16x16x32_bf16 v[68:71], v[232:235], v[224:227], v[68:71]
	v_mfma_f32_16x16x32_bf16 v[64:67], v[240:243], v[224:227], v[64:67]
	s_setprio 0
	s_mov_b32 m0, s64
	v_lshl_add_u64 v[244:245], s[22:23], 0, v[136:137]
	s_barrier
	ds_read_b128 v[196:199], v155 offset:16384
	ds_read_b128 v[200:203], v155 offset:17408
	ds_read_b128 v[204:207], v155 offset:18432
	ds_read_b128 v[208:211], v155 offset:19456
	ds_read_b128 v[212:215], v155 offset:20480
	ds_read_b128 v[216:219], v155 offset:21504
	ds_read_b128 v[220:223], v155 offset:22528
	ds_read_b128 v[224:227], v155 offset:23552
	global_load_lds_dwordx4 v[244:245], off
	v_lshl_add_u64 v[246:247], s[22:23], 0, v[132:133]
	s_mov_b32 m0, s65
	s_nop 0
	global_load_lds_dwordx4 v[246:247], off
	s_barrier
	s_nop 0
	s_setprio 1
	s_waitcnt lgkmcnt(7)
	v_mfma_f32_16x16x32_bf16 v[60:63], v[170:173], v[196:199], v[60:63]
	v_mfma_f32_16x16x32_bf16 v[56:59], v[186:189], v[196:199], v[56:59]
	s_waitcnt lgkmcnt(5)
	v_mfma_f32_16x16x32_bf16 v[52:55], v[170:173], v[204:207], v[52:55]
	v_mfma_f32_16x16x32_bf16 v[48:51], v[186:189], v[204:207], v[48:51]
	s_waitcnt lgkmcnt(3)
	v_mfma_f32_16x16x32_bf16 v[36:39], v[170:173], v[212:215], v[36:39]
	v_mfma_f32_16x16x32_bf16 v[32:35], v[186:189], v[212:215], v[32:35]
	s_waitcnt lgkmcnt(1)
	v_mfma_f32_16x16x32_bf16 v[20:23], v[170:173], v[220:223], v[20:23]
	v_mfma_f32_16x16x32_bf16 v[16:19], v[186:189], v[220:223], v[16:19]
	v_mfma_f32_16x16x32_bf16 v[60:63], v[174:177], v[200:203], v[60:63]
	v_mfma_f32_16x16x32_bf16 v[56:59], v[190:193], v[200:203], v[56:59]
	v_mfma_f32_16x16x32_bf16 v[52:55], v[174:177], v[208:211], v[52:55]
	v_mfma_f32_16x16x32_bf16 v[48:51], v[190:193], v[208:211], v[48:51]
	v_mfma_f32_16x16x32_bf16 v[36:39], v[174:177], v[216:219], v[36:39]
	v_mfma_f32_16x16x32_bf16 v[32:35], v[190:193], v[216:219], v[32:35]
	s_waitcnt lgkmcnt(0)
	v_mfma_f32_16x16x32_bf16 v[20:23], v[174:177], v[224:227], v[20:23]
	v_mfma_f32_16x16x32_bf16 v[16:19], v[190:193], v[224:227], v[16:19]
	s_setprio 0
	s_barrier
	s_add_u32 s28, s20, 0xb0000
	s_addc_u32 s29, s21, 0
	s_add_i32 s90, s79, s27
	v_lshl_add_u64 v[170:171], s[28:29], 0, v[134:135]
	s_mov_b32 m0, s90
	s_nop 0
	global_load_lds_dwordx4 v[170:171], off
	v_lshl_add_u64 v[170:171], s[28:29], 0, v[130:131]
	s_add_i32 m0, s90, 0x2000
	s_nop 0
	global_load_lds_dwordx4 v[170:171], off
	s_waitcnt vmcnt(6)
	s_barrier
	s_setprio 1
	v_mfma_f32_16x16x32_bf16 v[44:47], v[228:231], v[196:199], v[44:47]
	v_mfma_f32_16x16x32_bf16 v[40:43], v[236:239], v[196:199], v[40:43]
	v_mfma_f32_16x16x32_bf16 v[28:31], v[228:231], v[204:207], v[28:31]
	v_mfma_f32_16x16x32_bf16 v[24:27], v[236:239], v[204:207], v[24:27]
	v_mfma_f32_16x16x32_bf16 v[12:15], v[228:231], v[212:215], v[12:15]
	v_mfma_f32_16x16x32_bf16 v[8:11], v[236:239], v[212:215], v[8:11]
	v_mfma_f32_16x16x32_bf16 v[4:7], v[228:231], v[220:223], v[4:7]
	v_mfma_f32_16x16x32_bf16 v[0:3], v[236:239], v[220:223], v[0:3]
	v_mfma_f32_16x16x32_bf16 v[44:47], v[232:235], v[200:203], v[44:47]
	v_mfma_f32_16x16x32_bf16 v[40:43], v[240:243], v[200:203], v[40:43]
	v_mfma_f32_16x16x32_bf16 v[28:31], v[232:235], v[208:211], v[28:31]
	v_mfma_f32_16x16x32_bf16 v[24:27], v[240:243], v[208:211], v[24:27]
	v_mfma_f32_16x16x32_bf16 v[12:15], v[232:235], v[216:219], v[12:15]
	v_mfma_f32_16x16x32_bf16 v[8:11], v[240:243], v[216:219], v[8:11]
	v_mfma_f32_16x16x32_bf16 v[4:7], v[232:235], v[224:227], v[4:7]
	v_mfma_f32_16x16x32_bf16 v[0:3], v[240:243], v[224:227], v[0:3]
	s_setprio 0
	s_add_i32 s28, 0, 0x18000
	v_add_u32_e32 v157, s28, v152
	s_barrier
	ds_read_b128 v[170:173], v157
	ds_read_b128 v[174:177], v157 offset:1024
	ds_read_b128 v[186:189], v157 offset:2048
	ds_read_b128 v[190:193], v157 offset:3072
	s_add_u32 s22, s22, 0xb0000
	s_addc_u32 s23, s23, 0
	s_mov_b32 m0, s70
	v_lshl_add_u64 v[228:229], s[22:23], 0, v[136:137]
	ds_read_b128 v[196:199], v155 offset:32768
	ds_read_b128 v[200:203], v155 offset:33792
	ds_read_b128 v[204:207], v155 offset:34816
	ds_read_b128 v[208:211], v155 offset:35840
	ds_read_b128 v[212:215], v155 offset:36864
	ds_read_b128 v[216:219], v155 offset:37888
	ds_read_b128 v[220:223], v155 offset:38912
	ds_read_b128 v[224:227], v155 offset:39936
	global_load_lds_dwordx4 v[228:229], off
	v_lshl_add_u64 v[228:229], s[22:23], 0, v[132:133]
	s_mov_b32 m0, s71
	s_nop 0
	global_load_lds_dwordx4 v[228:229], off
	s_waitcnt lgkmcnt(8)
	s_barrier
	s_nop 0
	s_setprio 1
	s_waitcnt lgkmcnt(7)
	v_mfma_f32_16x16x32_bf16 v[124:127], v[170:173], v[196:199], v[124:127]
	v_mfma_f32_16x16x32_bf16 v[120:123], v[186:189], v[196:199], v[120:123]
	s_waitcnt lgkmcnt(5)
	v_mfma_f32_16x16x32_bf16 v[116:119], v[170:173], v[204:207], v[116:119]
	v_mfma_f32_16x16x32_bf16 v[112:115], v[186:189], v[204:207], v[112:115]
	s_waitcnt lgkmcnt(3)
	v_mfma_f32_16x16x32_bf16 v[100:103], v[170:173], v[212:215], v[100:103]
	v_mfma_f32_16x16x32_bf16 v[96:99], v[186:189], v[212:215], v[96:99]
	s_waitcnt lgkmcnt(1)
	v_mfma_f32_16x16x32_bf16 v[84:87], v[170:173], v[220:223], v[84:87]
	v_mfma_f32_16x16x32_bf16 v[80:83], v[186:189], v[220:223], v[80:83]
	v_mfma_f32_16x16x32_bf16 v[124:127], v[174:177], v[200:203], v[124:127]
	v_mfma_f32_16x16x32_bf16 v[120:123], v[190:193], v[200:203], v[120:123]
	v_mfma_f32_16x16x32_bf16 v[116:119], v[174:177], v[208:211], v[116:119]
	v_mfma_f32_16x16x32_bf16 v[112:115], v[190:193], v[208:211], v[112:115]
	v_mfma_f32_16x16x32_bf16 v[100:103], v[174:177], v[216:219], v[100:103]
	v_mfma_f32_16x16x32_bf16 v[96:99], v[190:193], v[216:219], v[96:99]
	s_waitcnt lgkmcnt(0)
	v_mfma_f32_16x16x32_bf16 v[84:87], v[174:177], v[224:227], v[84:87]
	v_mfma_f32_16x16x32_bf16 v[80:83], v[190:193], v[224:227], v[80:83]
	s_setprio 0
	s_barrier
	s_add_i32 s22, 0, 0x1c000
	s_add_i32 s23, s28, s27
	v_add_u32_e32 v157, s22, v152
	v_lshl_add_u64 v[158:159], v[158:159], 0, s[8:9]
	s_mov_b32 m0, s23
	ds_read_b128 v[228:231], v157
	ds_read_b128 v[232:235], v157 offset:1024
	ds_read_b128 v[236:239], v157 offset:2048
	ds_read_b128 v[240:243], v157 offset:3072
	global_load_lds_dwordx4 v[158:159], off
	v_lshl_add_u64 v[158:159], v[178:179], 0, s[8:9]
	s_add_i32 m0, s23, 0x2000
	s_nop 0
	global_load_lds_dwordx4 v[158:159], off
	s_barrier
	s_nop 0
	s_setprio 1
	s_waitcnt lgkmcnt(3)
	v_mfma_f32_16x16x32_bf16 v[108:111], v[228:231], v[196:199], v[108:111]
	s_waitcnt lgkmcnt(1)
	v_mfma_f32_16x16x32_bf16 v[104:107], v[236:239], v[196:199], v[104:107]
	v_mfma_f32_16x16x32_bf16 v[92:95], v[228:231], v[204:207], v[92:95]
	v_mfma_f32_16x16x32_bf16 v[88:91], v[236:239], v[204:207], v[88:91]
	v_mfma_f32_16x16x32_bf16 v[76:79], v[228:231], v[212:215], v[76:79]
	v_mfma_f32_16x16x32_bf16 v[72:75], v[236:239], v[212:215], v[72:75]
	v_mfma_f32_16x16x32_bf16 v[68:71], v[228:231], v[220:223], v[68:71]
	v_mfma_f32_16x16x32_bf16 v[64:67], v[236:239], v[220:223], v[64:67]
	v_mfma_f32_16x16x32_bf16 v[108:111], v[232:235], v[200:203], v[108:111]
	s_waitcnt lgkmcnt(0)
	v_mfma_f32_16x16x32_bf16 v[104:107], v[240:243], v[200:203], v[104:107]
	v_mfma_f32_16x16x32_bf16 v[92:95], v[232:235], v[208:211], v[92:95]
	v_mfma_f32_16x16x32_bf16 v[88:91], v[240:243], v[208:211], v[88:91]
	v_mfma_f32_16x16x32_bf16 v[76:79], v[232:235], v[216:219], v[76:79]
	v_mfma_f32_16x16x32_bf16 v[72:75], v[240:243], v[216:219], v[72:75]
	v_mfma_f32_16x16x32_bf16 v[68:71], v[232:235], v[224:227], v[68:71]
	v_mfma_f32_16x16x32_bf16 v[64:67], v[240:243], v[224:227], v[64:67]
	s_setprio 0
	s_mov_b32 m0, s74
	v_lshl_add_u64 v[158:159], v[244:245], 0, s[8:9]
	s_barrier
	ds_read_b128 v[196:199], v155 offset:49152
	ds_read_b128 v[200:203], v155 offset:50176
	ds_read_b128 v[204:207], v155 offset:51200
	ds_read_b128 v[208:211], v155 offset:52224
	ds_read_b128 v[212:215], v155 offset:53248
	ds_read_b128 v[216:219], v155 offset:54272
	ds_read_b128 v[220:223], v155 offset:55296
	ds_read_b128 v[224:227], v155 offset:56320
	global_load_lds_dwordx4 v[158:159], off
	v_lshl_add_u64 v[158:159], v[246:247], 0, s[8:9]
	s_mov_b32 m0, s75
	s_nop 0
	global_load_lds_dwordx4 v[158:159], off
	s_barrier
	s_nop 0
	s_setprio 1
	s_waitcnt lgkmcnt(7)
	v_mfma_f32_16x16x32_bf16 v[60:63], v[170:173], v[196:199], v[60:63]
	v_mfma_f32_16x16x32_bf16 v[56:59], v[186:189], v[196:199], v[56:59]
	s_waitcnt lgkmcnt(5)
	v_mfma_f32_16x16x32_bf16 v[52:55], v[170:173], v[204:207], v[52:55]
	v_mfma_f32_16x16x32_bf16 v[48:51], v[186:189], v[204:207], v[48:51]
	s_waitcnt lgkmcnt(3)
	v_mfma_f32_16x16x32_bf16 v[36:39], v[170:173], v[212:215], v[36:39]
	v_mfma_f32_16x16x32_bf16 v[32:35], v[186:189], v[212:215], v[32:35]
	s_waitcnt lgkmcnt(1)
	v_mfma_f32_16x16x32_bf16 v[20:23], v[170:173], v[220:223], v[20:23]
	v_mfma_f32_16x16x32_bf16 v[16:19], v[186:189], v[220:223], v[16:19]
	v_mfma_f32_16x16x32_bf16 v[60:63], v[174:177], v[200:203], v[60:63]
	v_mfma_f32_16x16x32_bf16 v[56:59], v[190:193], v[200:203], v[56:59]
	v_mfma_f32_16x16x32_bf16 v[52:55], v[174:177], v[208:211], v[52:55]
	v_mfma_f32_16x16x32_bf16 v[48:51], v[190:193], v[208:211], v[48:51]
	v_mfma_f32_16x16x32_bf16 v[36:39], v[174:177], v[216:219], v[36:39]
	v_mfma_f32_16x16x32_bf16 v[32:35], v[190:193], v[216:219], v[32:35]
	s_waitcnt lgkmcnt(0)
	v_mfma_f32_16x16x32_bf16 v[20:23], v[174:177], v[224:227], v[20:23]
	v_mfma_f32_16x16x32_bf16 v[16:19], v[190:193], v[224:227], v[16:19]
	s_setprio 0
	s_barrier
	s_add_u32 s20, s20, 0xb0080
	s_addc_u32 s21, s21, 0
	s_add_i32 s22, s22, s27
	v_lshl_add_u64 v[158:159], s[20:21], 0, v[134:135]
	s_mov_b32 m0, s22
	s_nop 0
	global_load_lds_dwordx4 v[158:159], off
	v_lshl_add_u64 v[158:159], s[20:21], 0, v[130:131]
	s_add_i32 m0, s22, 0x2000
	s_nop 0
	global_load_lds_dwordx4 v[158:159], off
	s_waitcnt vmcnt(6)
	s_barrier
	s_setprio 1
	v_mfma_f32_16x16x32_bf16 v[44:47], v[228:231], v[196:199], v[44:47]
	v_mfma_f32_16x16x32_bf16 v[40:43], v[236:239], v[196:199], v[40:43]
	v_mfma_f32_16x16x32_bf16 v[28:31], v[228:231], v[204:207], v[28:31]
	v_mfma_f32_16x16x32_bf16 v[24:27], v[236:239], v[204:207], v[24:27]
	v_mfma_f32_16x16x32_bf16 v[12:15], v[228:231], v[212:215], v[12:15]
	v_mfma_f32_16x16x32_bf16 v[8:11], v[236:239], v[212:215], v[8:11]
	v_mfma_f32_16x16x32_bf16 v[4:7], v[228:231], v[220:223], v[4:7]
	v_mfma_f32_16x16x32_bf16 v[0:3], v[236:239], v[220:223], v[0:3]
	v_mfma_f32_16x16x32_bf16 v[44:47], v[232:235], v[200:203], v[44:47]
	v_mfma_f32_16x16x32_bf16 v[40:43], v[240:243], v[200:203], v[40:43]
	v_mfma_f32_16x16x32_bf16 v[28:31], v[232:235], v[208:211], v[28:31]
	v_mfma_f32_16x16x32_bf16 v[24:27], v[240:243], v[208:211], v[24:27]
	v_mfma_f32_16x16x32_bf16 v[12:15], v[232:235], v[216:219], v[12:15]
	v_mfma_f32_16x16x32_bf16 v[8:11], v[240:243], v[216:219], v[8:11]
	v_mfma_f32_16x16x32_bf16 v[4:7], v[232:235], v[224:227], v[4:7]
	v_mfma_f32_16x16x32_bf16 v[0:3], v[240:243], v[224:227], v[0:3]
	s_setprio 0
	s_add_i32 s89, s89, 2
	s_add_u32 s87, s87, 0x100
	s_addc_u32 s88, s88, 0
	s_add_u32 s18, s18, 0x100
	s_addc_u32 s19, s19, 0
	s_cmp_gt_u32 s89, 41
	s_barrier
	s_cbranch_scc0 .LBB0_203
	s_cmp_eq_u32 s81, 0
	s_mov_b32 s18, 0x3222000
	s_cselect_b32 s18, s18, 0x19a22000
	s_add_u32 s18, s34, s18
	v_lshl_or_b32 v158, s86, 8, v153
	v_lshl_add_u32 v170, s83, 8, v145
	s_addc_u32 s19, s35, 0
	v_ashrrev_i32_e32 v159, 31, v158
	v_ashrrev_i32_e32 v171, 31, v170
	v_lshl_add_u64 v[158:159], v[158:159], 1, s[18:19]
	v_lshlrev_b64 v[172:173], 11, v[170:171]
	v_lshl_add_u64 v[172:173], v[158:159], 0, v[172:173]
	s_mov_b64 s[18:19], 0x40000
	v_cvt_pk_bf16_f32 v68, v68, v69
	v_cvt_pk_bf16_f32 v69, v70, v71
	v_cvt_pk_bf16_f32 v70, v64, v65
	v_lshl_add_u64 v[64:65], v[172:173], 0, s[18:19]
	s_mov_b32 s18, 0x40000
	v_cvt_pk_bf16_f32 v60, v60, v61
	v_cvt_pk_bf16_f32 v61, v62, v63
	v_cvt_pk_bf16_f32 v62, v56, v57
	v_add_co_u32_e32 v56, vcc, s18, v172
	v_cvt_pk_bf16_f32 v44, v44, v45
	v_cvt_pk_bf16_f32 v45, v46, v47
	v_cvt_pk_bf16_f32 v46, v40, v41
	v_cvt_pk_bf16_f32 v47, v42, v43
	s_mov_b64 s[18:19], 0x48000
	v_addc_co_u32_e32 v57, vcc, 0, v173, vcc
	global_store_dwordx4 v[64:65], v[44:47], off offset:256
	v_cvt_pk_bf16_f32 v28, v28, v29
	v_cvt_pk_bf16_f32 v29, v30, v31
	v_lshl_add_u64 v[44:45], v[172:173], 0, s[18:19]
	s_mov_b32 s18, 0x48000
	v_add_co_u32_e32 v46, vcc, s18, v172
	v_cvt_pk_bf16_f32 v30, v24, v25
	v_cvt_pk_bf16_f32 v31, v26, v27
	s_mov_b64 s[18:19], 0x50000
	v_cvt_pk_bf16_f32 v108, v108, v109
	v_cvt_pk_bf16_f32 v109, v110, v111
	v_cvt_pk_bf16_f32 v110, v104, v105
	v_or_b32_e32 v104, 16, v170
	v_addc_co_u32_e32 v47, vcc, 0, v173, vcc
	global_store_dwordx4 v[44:45], v[28:31], off offset:256
	v_ashrrev_i32_e32 v105, 31, v104
	v_cvt_pk_bf16_f32 v92, v92, v93
	v_lshl_add_u64 v[28:29], v[172:173], 0, s[18:19]
	s_mov_b32 s18, 0x50000
	v_cvt_pk_bf16_f32 v93, v94, v95
	v_cvt_pk_bf16_f32 v94, v88, v89
	v_or_b32_e32 v88, 32, v170
	v_add_co_u32_e32 v30, vcc, s18, v172
	v_cvt_pk_bf16_f32 v111, v106, v107
	v_lshlrev_b64 v[104:105], 11, v[104:105]
	v_ashrrev_i32_e32 v89, 31, v88
	v_cvt_pk_bf16_f32 v76, v76, v77
	v_cvt_pk_bf16_f32 v77, v78, v79
	v_cvt_pk_bf16_f32 v78, v72, v73
	v_or_b32_e32 v72, 48, v170
	v_addc_co_u32_e32 v31, vcc, 0, v173, vcc
	v_cvt_pk_bf16_f32 v12, v12, v13
	v_cvt_pk_bf16_f32 v13, v14, v15
	v_cvt_pk_bf16_f32 v14, v8, v9
	v_cvt_pk_bf16_f32 v15, v10, v11
	global_store_dwordx4 v[172:173], v[108:111], off offset:256
	v_cvt_pk_bf16_f32 v95, v90, v91
	v_lshlrev_b64 v[88:89], 11, v[88:89]
	v_lshl_add_u64 v[108:109], v[158:159], 0, v[104:105]
	v_ashrrev_i32_e32 v73, 31, v72
	global_store_dwordx4 v[28:29], v[12:15], off offset:256
	global_store_dwordx4 v[108:109], v[92:95], off offset:256
	v_cvt_pk_bf16_f32 v79, v74, v75
	v_add_co_u32_e32 v14, vcc, s80, v172
	v_lshl_add_u64 v[92:93], v[158:159], 0, v[88:89]
	v_lshlrev_b64 v[72:73], 11, v[72:73]
	v_addc_co_u32_e32 v15, vcc, 0, v173, vcc
	v_cvt_pk_bf16_f32 v124, v124, v125
	v_cvt_pk_bf16_f32 v125, v126, v127
	v_cvt_pk_bf16_f32 v126, v120, v121
	v_cvt_pk_bf16_f32 v127, v122, v123
	v_cvt_pk_bf16_f32 v104, v116, v117
	v_cvt_pk_bf16_f32 v105, v118, v119
	v_cvt_pk_bf16_f32 v106, v112, v113
	v_cvt_pk_bf16_f32 v107, v114, v115
	v_cvt_pk_bf16_f32 v88, v100, v101
	v_cvt_pk_bf16_f32 v89, v102, v103
	v_cvt_pk_bf16_f32 v90, v96, v97
	v_cvt_pk_bf16_f32 v91, v98, v99
	global_store_dwordx4 v[92:93], v[76:79], off offset:256
	v_cvt_pk_bf16_f32 v74, v80, v81
	v_cvt_pk_bf16_f32 v75, v82, v83
	v_lshl_add_u64 v[76:77], v[158:159], 0, v[72:73]
	v_cvt_pk_bf16_f32 v72, v84, v85
	v_cvt_pk_bf16_f32 v73, v86, v87
	v_cvt_pk_bf16_f32 v71, v66, v67
	v_cvt_pk_bf16_f32 v63, v58, v59
	v_cvt_pk_bf16_f32 v40, v52, v53
	v_cvt_pk_bf16_f32 v41, v54, v55
	v_cvt_pk_bf16_f32 v42, v48, v49
	v_cvt_pk_bf16_f32 v43, v50, v51
	v_cvt_pk_bf16_f32 v24, v36, v37
	v_cvt_pk_bf16_f32 v25, v38, v39
	v_cvt_pk_bf16_f32 v26, v32, v33
	v_cvt_pk_bf16_f32 v27, v34, v35
	v_lshl_add_u64 v[12:13], v[172:173], 0, s[16:17]
	v_cvt_pk_bf16_f32 v8, v20, v21
	v_cvt_pk_bf16_f32 v9, v22, v23
	v_cvt_pk_bf16_f32 v10, v16, v17
	v_cvt_pk_bf16_f32 v11, v18, v19
	v_cvt_pk_bf16_f32 v4, v4, v5
	v_cvt_pk_bf16_f32 v5, v6, v7
	v_cvt_pk_bf16_f32 v6, v0, v1
	v_cvt_pk_bf16_f32 v7, v2, v3
	s_and_b64 vcc, exec, s[4:5]
	s_mov_b32 s81, s82
	s_mov_b32 s86, s84
	s_mov_b32 s83, s85
	s_mov_b64 s[18:19], s[6:7]
	s_mov_b64 s[20:21], s[0:1]
	global_store_dwordx4 v[172:173], v[124:127], off
	global_store_dwordx4 v[108:109], v[104:107], off
	global_store_dwordx4 v[92:93], v[88:91], off
	global_store_dwordx4 v[76:77], v[72:75], off
	global_store_dwordx4 v[76:77], v[68:71], off offset:256
	global_store_dwordx4 v[56:57], v[60:63], off
	global_store_dwordx4 v[46:47], v[40:43], off
	global_store_dwordx4 v[30:31], v[24:27], off
	global_store_dwordx4 v[14:15], v[8:11], off
	global_store_dwordx4 v[12:13], v[4:7], off offset:256
	s_cbranch_vccz .LBB0_196
	s_waitcnt vmcnt(0)
	s_cmpk_gt_u32 s24, 0xff
	s_cbranch_scc1 .LBB0_207
	s_barrier

.LBB0_394:
	ds_read_b128 v[24:27], v155
	ds_read_b128 v[28:31], v155 offset:1024
	ds_read_b128 v[40:43], v155 offset:2048
	ds_read_b128 v[48:51], v155 offset:3072
	s_add_u32 s27, s8, 0xfffc0080
	s_addc_u32 s28, s9, -1
	s_cmp_eq_u32 s26, 12
	s_cselect_b32 s73, s1, s28
	s_cselect_b32 s72, s4, s27
	s_cselect_b32 s53, s5, s25
	s_cselect_b32 s52, s21, s23
	v_lshl_add_u64 v[226:227], s[8:9], 0, v[168:169]
	s_add_i32 m0, s55, 0xc000
	ds_read_b128 v[176:179], v165
	ds_read_b128 v[198:201], v165 offset:1024
	ds_read_b128 v[202:205], v165 offset:2048
	ds_read_b128 v[206:209], v165 offset:3072
	ds_read_b128 v[210:213], v165 offset:4096
	ds_read_b128 v[214:217], v165 offset:5120
	ds_read_b128 v[218:221], v165 offset:6144
	ds_read_b128 v[222:225], v165 offset:7168
	global_load_lds_dwordx4 v[226:227], off
	v_lshl_add_u64 v[226:227], s[8:9], 0, v[170:171]
	s_add_i32 m0, s55, 0xe000
	s_nop 0
	global_load_lds_dwordx4 v[226:227], off
	s_waitcnt lgkmcnt(8)
	s_barrier
	s_nop 0
	s_setprio 1
	s_waitcnt lgkmcnt(7)
	v_mfma_f32_16x16x32_bf16 v[140:143], v[24:27], v[176:179], v[140:143]
	v_mfma_f32_16x16x32_bf16 v[136:139], v[40:43], v[176:179], v[136:139]
	s_waitcnt lgkmcnt(5)
	v_mfma_f32_16x16x32_bf16 v[124:127], v[24:27], v[202:205], v[124:127]
	v_mfma_f32_16x16x32_bf16 v[120:123], v[40:43], v[202:205], v[120:123]
	s_waitcnt lgkmcnt(3)
	v_mfma_f32_16x16x32_bf16 v[108:111], v[24:27], v[210:213], v[108:111]
	v_mfma_f32_16x16x32_bf16 v[104:107], v[40:43], v[210:213], v[104:107]
	s_waitcnt lgkmcnt(1)
	v_mfma_f32_16x16x32_bf16 v[92:95], v[24:27], v[218:221], v[92:95]
	v_mfma_f32_16x16x32_bf16 v[88:91], v[40:43], v[218:221], v[88:91]
	v_mfma_f32_16x16x32_bf16 v[140:143], v[28:31], v[198:201], v[140:143]
	v_mfma_f32_16x16x32_bf16 v[136:139], v[48:51], v[198:201], v[136:139]
	v_mfma_f32_16x16x32_bf16 v[124:127], v[28:31], v[206:209], v[124:127]
	v_mfma_f32_16x16x32_bf16 v[120:123], v[48:51], v[206:209], v[120:123]
	v_mfma_f32_16x16x32_bf16 v[108:111], v[28:31], v[214:217], v[108:111]
	v_mfma_f32_16x16x32_bf16 v[104:107], v[48:51], v[214:217], v[104:107]
	s_waitcnt lgkmcnt(0)
	v_mfma_f32_16x16x32_bf16 v[92:95], v[28:31], v[222:225], v[92:95]
	v_mfma_f32_16x16x32_bf16 v[88:91], v[48:51], v[222:225], v[88:91]
	s_setprio 0
	s_barrier
	s_add_i32 s27, s89, s78
	v_lshl_add_u64 v[242:243], s[52:53], 0, v[158:159]
	s_mov_b32 m0, s27
	ds_read_b128 v[226:229], v196
	ds_read_b128 v[230:233], v196 offset:1024
	ds_read_b128 v[234:237], v196 offset:2048
	ds_read_b128 v[238:241], v196 offset:3072
	global_load_lds_dwordx4 v[242:243], off
	v_lshl_add_u64 v[244:245], s[52:53], 0, v[162:163]
	s_add_i32 m0, s27, 0x2000
	s_nop 0
	global_load_lds_dwordx4 v[244:245], off
	s_barrier
	s_nop 0
	s_setprio 1
	s_waitcnt lgkmcnt(3)
	v_mfma_f32_16x16x32_bf16 v[132:135], v[226:229], v[176:179], v[132:135]
	s_waitcnt lgkmcnt(1)
	v_mfma_f32_16x16x32_bf16 v[128:131], v[234:237], v[176:179], v[128:131]
	v_mfma_f32_16x16x32_bf16 v[116:119], v[226:229], v[202:205], v[116:119]
	v_mfma_f32_16x16x32_bf16 v[112:115], v[234:237], v[202:205], v[112:115]
	v_mfma_f32_16x16x32_bf16 v[100:103], v[226:229], v[210:213], v[100:103]
	v_mfma_f32_16x16x32_bf16 v[96:99], v[234:237], v[210:213], v[96:99]
	v_mfma_f32_16x16x32_bf16 v[84:87], v[226:229], v[218:221], v[84:87]
	v_mfma_f32_16x16x32_bf16 v[80:83], v[234:237], v[218:221], v[80:83]
	v_mfma_f32_16x16x32_bf16 v[132:135], v[230:233], v[198:201], v[132:135]
	s_waitcnt lgkmcnt(0)
	v_mfma_f32_16x16x32_bf16 v[128:131], v[238:241], v[198:201], v[128:131]
	v_mfma_f32_16x16x32_bf16 v[116:119], v[230:233], v[206:209], v[116:119]
	v_mfma_f32_16x16x32_bf16 v[112:115], v[238:241], v[206:209], v[112:115]
	v_mfma_f32_16x16x32_bf16 v[100:103], v[230:233], v[214:217], v[100:103]
	v_mfma_f32_16x16x32_bf16 v[96:99], v[238:241], v[214:217], v[96:99]
	v_mfma_f32_16x16x32_bf16 v[84:87], v[230:233], v[222:225], v[84:87]
	v_mfma_f32_16x16x32_bf16 v[80:83], v[238:241], v[222:225], v[80:83]
	s_setprio 0
	s_mov_b32 m0, s55
	v_lshl_add_u64 v[246:247], s[72:73], 0, v[156:157]
	s_barrier
	ds_read_b128 v[176:179], v165 offset:16384
	ds_read_b128 v[198:201], v165 offset:17408
	ds_read_b128 v[202:205], v165 offset:18432
	ds_read_b128 v[206:209], v165 offset:19456
	ds_read_b128 v[210:213], v165 offset:20480
	ds_read_b128 v[214:217], v165 offset:21504
	ds_read_b128 v[218:221], v165 offset:22528
	ds_read_b128 v[222:225], v165 offset:23552
	global_load_lds_dwordx4 v[246:247], off
	v_lshl_add_u64 v[248:249], s[72:73], 0, v[160:161]
	s_mov_b32 m0, s79
	s_nop 0
	global_load_lds_dwordx4 v[248:249], off
	s_barrier
	s_nop 0
	s_setprio 1
	s_waitcnt lgkmcnt(7)
	v_mfma_f32_16x16x32_bf16 v[76:79], v[24:27], v[176:179], v[76:79]
	v_mfma_f32_16x16x32_bf16 v[72:75], v[40:43], v[176:179], v[72:75]
	s_waitcnt lgkmcnt(5)
	v_mfma_f32_16x16x32_bf16 v[60:63], v[24:27], v[202:205], v[60:63]
	v_mfma_f32_16x16x32_bf16 v[56:59], v[40:43], v[202:205], v[56:59]
	s_waitcnt lgkmcnt(3)
	v_mfma_f32_16x16x32_bf16 v[36:39], v[24:27], v[210:213], v[36:39]
	v_mfma_f32_16x16x32_bf16 v[32:35], v[40:43], v[210:213], v[32:35]
	s_waitcnt lgkmcnt(1)
	v_mfma_f32_16x16x32_bf16 v[12:15], v[24:27], v[218:221], v[12:15]
	v_mfma_f32_16x16x32_bf16 v[8:11], v[40:43], v[218:221], v[8:11]
	v_mfma_f32_16x16x32_bf16 v[76:79], v[28:31], v[198:201], v[76:79]
	v_mfma_f32_16x16x32_bf16 v[72:75], v[48:51], v[198:201], v[72:75]
	v_mfma_f32_16x16x32_bf16 v[60:63], v[28:31], v[206:209], v[60:63]
	v_mfma_f32_16x16x32_bf16 v[56:59], v[48:51], v[206:209], v[56:59]
	v_mfma_f32_16x16x32_bf16 v[36:39], v[28:31], v[214:217], v[36:39]
	v_mfma_f32_16x16x32_bf16 v[32:35], v[48:51], v[214:217], v[32:35]
	s_waitcnt lgkmcnt(0)
	v_mfma_f32_16x16x32_bf16 v[12:15], v[28:31], v[222:225], v[12:15]
	v_mfma_f32_16x16x32_bf16 v[8:11], v[48:51], v[222:225], v[8:11]
	s_setprio 0
	s_barrier
	s_add_u32 s28, s52, 0x40000
	s_addc_u32 s29, s53, 0
	s_add_i32 s27, s90, s78
	v_lshl_add_u64 v[24:25], s[28:29], 0, v[158:159]
	s_mov_b32 m0, s27
	s_nop 0
	global_load_lds_dwordx4 v[24:25], off
	v_lshl_add_u64 v[24:25], s[28:29], 0, v[162:163]
	s_add_i32 m0, s27, 0x2000
	s_nop 0
	global_load_lds_dwordx4 v[24:25], off
	s_waitcnt vmcnt(6)
	s_barrier
	s_setprio 1
	v_mfma_f32_16x16x32_bf16 v[44:47], v[234:237], v[202:205], v[44:47]
	v_mfma_f32_16x16x32_bf16 v[20:23], v[226:229], v[210:213], v[20:23]
	v_mfma_f32_16x16x32_bf16 v[16:19], v[234:237], v[210:213], v[16:19]
	v_mfma_f32_16x16x32_bf16 v[4:7], v[226:229], v[218:221], v[4:7]
	v_mfma_f32_16x16x32_bf16 v[0:3], v[234:237], v[218:221], v[0:3]
	v_mfma_f32_16x16x32_bf16 v[24:27], v[226:229], v[176:179], v[68:71]
	v_mfma_f32_16x16x32_bf16 v[28:31], v[234:237], v[176:179], v[64:67]
	v_mfma_f32_16x16x32_bf16 v[40:43], v[226:229], v[202:205], v[52:55]
	v_mfma_f32_16x16x32_bf16 v[44:47], v[238:241], v[206:209], v[44:47]
	v_mfma_f32_16x16x32_bf16 v[20:23], v[230:233], v[214:217], v[20:23]
	v_mfma_f32_16x16x32_bf16 v[16:19], v[238:241], v[214:217], v[16:19]
	v_mfma_f32_16x16x32_bf16 v[4:7], v[230:233], v[222:225], v[4:7]
	v_mfma_f32_16x16x32_bf16 v[0:3], v[238:241], v[222:225], v[0:3]
	v_mfma_f32_16x16x32_bf16 v[24:27], v[230:233], v[198:201], v[24:27]
	v_mfma_f32_16x16x32_bf16 v[28:31], v[238:241], v[198:201], v[28:31]
	v_mfma_f32_16x16x32_bf16 v[40:43], v[230:233], v[206:209], v[40:43]
	s_setprio 0
	s_add_i32 s27, 0, 0x18000
	v_add_u32_e32 v68, s27, v151
	s_barrier
	ds_read_b128 v[48:51], v68
	ds_read_b128 v[52:55], v68 offset:1024
	ds_read_b128 v[64:67], v68 offset:2048
	ds_read_b128 v[68:71], v68 offset:3072
	s_add_u32 s28, s72, 0x40000
	s_addc_u32 s29, s73, 0
	s_mov_b32 m0, s80
	v_lshl_add_u64 v[226:227], s[28:29], 0, v[156:157]
	ds_read_b128 v[176:179], v165 offset:32768
	ds_read_b128 v[198:201], v165 offset:33792
	ds_read_b128 v[202:205], v165 offset:34816
	ds_read_b128 v[206:209], v165 offset:35840
	ds_read_b128 v[210:213], v165 offset:36864
	ds_read_b128 v[214:217], v165 offset:37888
	ds_read_b128 v[218:221], v165 offset:38912
	ds_read_b128 v[222:225], v165 offset:39936
	global_load_lds_dwordx4 v[226:227], off
	v_lshl_add_u64 v[226:227], s[28:29], 0, v[160:161]
	s_mov_b32 m0, s81
	s_nop 0
	global_load_lds_dwordx4 v[226:227], off
	s_waitcnt lgkmcnt(8)
	s_barrier
	s_nop 0
	s_setprio 1
	s_waitcnt lgkmcnt(7)
	v_mfma_f32_16x16x32_bf16 v[140:143], v[48:51], v[176:179], v[140:143]
	v_mfma_f32_16x16x32_bf16 v[136:139], v[64:67], v[176:179], v[136:139]
	s_waitcnt lgkmcnt(5)
	v_mfma_f32_16x16x32_bf16 v[124:127], v[48:51], v[202:205], v[124:127]
	v_mfma_f32_16x16x32_bf16 v[120:123], v[64:67], v[202:205], v[120:123]
	s_waitcnt lgkmcnt(3)
	v_mfma_f32_16x16x32_bf16 v[108:111], v[48:51], v[210:213], v[108:111]
	v_mfma_f32_16x16x32_bf16 v[104:107], v[64:67], v[210:213], v[104:107]
	s_waitcnt lgkmcnt(1)
	v_mfma_f32_16x16x32_bf16 v[92:95], v[48:51], v[218:221], v[92:95]
	v_mfma_f32_16x16x32_bf16 v[88:91], v[64:67], v[218:221], v[88:91]
	v_mfma_f32_16x16x32_bf16 v[140:143], v[52:55], v[198:201], v[140:143]
	v_mfma_f32_16x16x32_bf16 v[136:139], v[68:71], v[198:201], v[136:139]
	v_mfma_f32_16x16x32_bf16 v[124:127], v[52:55], v[206:209], v[124:127]
	v_mfma_f32_16x16x32_bf16 v[120:123], v[68:71], v[206:209], v[120:123]
	v_mfma_f32_16x16x32_bf16 v[108:111], v[52:55], v[214:217], v[108:111]
	v_mfma_f32_16x16x32_bf16 v[104:107], v[68:71], v[214:217], v[104:107]
	s_waitcnt lgkmcnt(0)
	v_mfma_f32_16x16x32_bf16 v[92:95], v[52:55], v[222:225], v[92:95]
	v_mfma_f32_16x16x32_bf16 v[88:91], v[68:71], v[222:225], v[88:91]
	s_setprio 0
	s_barrier
	s_add_i32 s33, 0, 0x1c000
	s_add_i32 s27, s27, s78
	v_add_u32_e32 v238, s33, v151
	v_lshl_add_u64 v[242:243], v[242:243], 0, s[18:19]
	s_mov_b32 m0, s27
	ds_read_b128 v[226:229], v238
	ds_read_b128 v[230:233], v238 offset:1024
	ds_read_b128 v[234:237], v238 offset:2048
	ds_read_b128 v[238:241], v238 offset:3072
	global_load_lds_dwordx4 v[242:243], off
	v_lshl_add_u64 v[242:243], v[244:245], 0, s[18:19]
	s_add_i32 m0, s27, 0x2000
	s_nop 0
	global_load_lds_dwordx4 v[242:243], off
	s_barrier
	s_nop 0
	s_setprio 1
	s_waitcnt lgkmcnt(3)
	v_mfma_f32_16x16x32_bf16 v[132:135], v[226:229], v[176:179], v[132:135]
	s_waitcnt lgkmcnt(1)
	v_mfma_f32_16x16x32_bf16 v[128:131], v[234:237], v[176:179], v[128:131]
	v_mfma_f32_16x16x32_bf16 v[116:119], v[226:229], v[202:205], v[116:119]
	v_mfma_f32_16x16x32_bf16 v[112:115], v[234:237], v[202:205], v[112:115]
	v_mfma_f32_16x16x32_bf16 v[100:103], v[226:229], v[210:213], v[100:103]
	v_mfma_f32_16x16x32_bf16 v[96:99], v[234:237], v[210:213], v[96:99]
	v_mfma_f32_16x16x32_bf16 v[84:87], v[226:229], v[218:221], v[84:87]
	v_mfma_f32_16x16x32_bf16 v[80:83], v[234:237], v[218:221], v[80:83]
	v_mfma_f32_16x16x32_bf16 v[132:135], v[230:233], v[198:201], v[132:135]
	s_waitcnt lgkmcnt(0)
	v_mfma_f32_16x16x32_bf16 v[128:131], v[238:241], v[198:201], v[128:131]
	v_mfma_f32_16x16x32_bf16 v[116:119], v[230:233], v[206:209], v[116:119]
	v_mfma_f32_16x16x32_bf16 v[112:115], v[238:241], v[206:209], v[112:115]
	v_mfma_f32_16x16x32_bf16 v[100:103], v[230:233], v[214:217], v[100:103]
	v_mfma_f32_16x16x32_bf16 v[96:99], v[238:241], v[214:217], v[96:99]
	v_mfma_f32_16x16x32_bf16 v[84:87], v[230:233], v[222:225], v[84:87]
	v_mfma_f32_16x16x32_bf16 v[80:83], v[238:241], v[222:225], v[80:83]
	s_setprio 0
	s_mov_b32 m0, s83
	v_lshl_add_u64 v[242:243], v[246:247], 0, s[18:19]
	s_barrier
	ds_read_b128 v[176:179], v165 offset:49152
	ds_read_b128 v[198:201], v165 offset:50176
	ds_read_b128 v[202:205], v165 offset:51200
	ds_read_b128 v[206:209], v165 offset:52224
	ds_read_b128 v[210:213], v165 offset:53248
	ds_read_b128 v[214:217], v165 offset:54272
	ds_read_b128 v[218:221], v165 offset:55296
	ds_read_b128 v[222:225], v165 offset:56320
	global_load_lds_dwordx4 v[242:243], off
	v_lshl_add_u64 v[242:243], v[248:249], 0, s[18:19]
	s_mov_b32 m0, s84
	s_nop 0
	global_load_lds_dwordx4 v[242:243], off
	s_barrier
	s_nop 0
	s_setprio 1
	s_waitcnt lgkmcnt(7)
	v_mfma_f32_16x16x32_bf16 v[76:79], v[48:51], v[176:179], v[76:79]
	v_mfma_f32_16x16x32_bf16 v[72:75], v[64:67], v[176:179], v[72:75]
	s_waitcnt lgkmcnt(5)
	v_mfma_f32_16x16x32_bf16 v[60:63], v[48:51], v[202:205], v[60:63]
	v_mfma_f32_16x16x32_bf16 v[56:59], v[64:67], v[202:205], v[56:59]
	s_waitcnt lgkmcnt(3)
	v_mfma_f32_16x16x32_bf16 v[36:39], v[48:51], v[210:213], v[36:39]
	v_mfma_f32_16x16x32_bf16 v[32:35], v[64:67], v[210:213], v[32:35]
	s_waitcnt lgkmcnt(1)
	v_mfma_f32_16x16x32_bf16 v[12:15], v[48:51], v[218:221], v[12:15]
	v_mfma_f32_16x16x32_bf16 v[8:11], v[64:67], v[218:221], v[8:11]
	v_mfma_f32_16x16x32_bf16 v[76:79], v[52:55], v[198:201], v[76:79]
	v_mfma_f32_16x16x32_bf16 v[72:75], v[68:71], v[198:201], v[72:75]
	v_mfma_f32_16x16x32_bf16 v[60:63], v[52:55], v[206:209], v[60:63]
	v_mfma_f32_16x16x32_bf16 v[56:59], v[68:71], v[206:209], v[56:59]
	v_mfma_f32_16x16x32_bf16 v[36:39], v[52:55], v[214:217], v[36:39]
	v_mfma_f32_16x16x32_bf16 v[32:35], v[68:71], v[214:217], v[32:35]
	s_waitcnt lgkmcnt(0)
	v_mfma_f32_16x16x32_bf16 v[12:15], v[52:55], v[222:225], v[12:15]
	v_mfma_f32_16x16x32_bf16 v[8:11], v[68:71], v[222:225], v[8:11]
	s_setprio 0
	s_barrier
	s_add_u32 s28, s52, 0x40080
	s_addc_u32 s29, s53, 0
	s_add_i32 s27, s33, s78
	v_lshl_add_u64 v[48:49], s[28:29], 0, v[158:159]
	s_mov_b32 m0, s27
	s_nop 0
	global_load_lds_dwordx4 v[48:49], off
	v_lshl_add_u64 v[48:49], s[28:29], 0, v[162:163]
	s_add_i32 m0, s27, 0x2000
	s_nop 0
	global_load_lds_dwordx4 v[48:49], off
	s_waitcnt vmcnt(6)
	s_barrier
	s_setprio 1
	v_mfma_f32_16x16x32_bf16 v[24:27], v[226:229], v[176:179], v[24:27]
	v_mfma_f32_16x16x32_bf16 v[68:71], v[230:233], v[198:201], v[24:27]
	v_mfma_f32_16x16x32_bf16 v[24:27], v[234:237], v[176:179], v[28:31]
	v_mfma_f32_16x16x32_bf16 v[64:67], v[238:241], v[198:201], v[24:27]
	v_mfma_f32_16x16x32_bf16 v[24:27], v[226:229], v[202:205], v[40:43]
	v_mfma_f32_16x16x32_bf16 v[52:55], v[230:233], v[206:209], v[24:27]
	v_mfma_f32_16x16x32_bf16 v[24:27], v[234:237], v[202:205], v[44:47]
	v_mfma_f32_16x16x32_bf16 v[20:23], v[226:229], v[210:213], v[20:23]
	v_mfma_f32_16x16x32_bf16 v[16:19], v[234:237], v[210:213], v[16:19]
	v_mfma_f32_16x16x32_bf16 v[4:7], v[226:229], v[218:221], v[4:7]
	v_mfma_f32_16x16x32_bf16 v[0:3], v[234:237], v[218:221], v[0:3]
	v_mfma_f32_16x16x32_bf16 v[44:47], v[238:241], v[206:209], v[24:27]
	v_mfma_f32_16x16x32_bf16 v[20:23], v[230:233], v[214:217], v[20:23]
	v_mfma_f32_16x16x32_bf16 v[16:19], v[238:241], v[214:217], v[16:19]
	v_mfma_f32_16x16x32_bf16 v[4:7], v[230:233], v[222:225], v[4:7]
	v_mfma_f32_16x16x32_bf16 v[0:3], v[238:241], v[222:225], v[0:3]
	s_setprio 0
	s_add_i32 s26, s26, 2
	s_add_u32 s8, s8, 0x100
	s_addc_u32 s9, s9, 0
	s_add_u32 s23, s23, 0x100
	s_addc_u32 s25, s25, 0
	s_cmp_gt_u32 s26, 13
	s_barrier
	s_cbranch_scc0 .LBB0_394
	s_cmp_gt_i32 s0, 3
	s_mov_b64 s[8:9], -1
	s_cbranch_scc0 .LBB0_410
	s_add_i32 s1, s0, -4
	s_cmp_lt_u32 s1, 2
	s_mov_b64 s[8:9], 0
	s_cbranch_scc1 .LBB0_406
	s_lshr_b32 s1, s1, 1
	s_cmp_lt_i32 s1, 2
	s_mov_b32 s21, 2
	s_cbranch_scc1 .LBB0_408
	s_cmp_lt_i32 s1, 3
	s_mov_b64 s[52:53], -1
	s_cbranch_scc1 .LBB0_404
	s_cmp_lg_u32 s1, 3
	s_cbranch_scc0 .LBB0_401
	s_mov_b64 s[52:53], 0

.LBB0_822:
	ds_read_b128 v[168:171], v143
	ds_read_b128 v[172:175], v143 offset:1024
	ds_read_b128 v[176:179], v143 offset:2048
	ds_read_b128 v[194:197], v143 offset:3072
	s_add_u32 s28, s50, 0xfffc0180
	s_addc_u32 s29, s51, -1
	s_cmp_eq_u32 s81, 4
	s_cselect_b32 s55, s25, s29
	s_cselect_b32 s54, s78, s28
	s_cselect_b32 s53, s23, s80
	s_cselect_b32 s52, s45, s79
	v_lshl_add_u64 v[230:231], s[50:51], 0, v[132:133]
	s_add_i32 m0, s19, 0xc000
	ds_read_b128 v[198:201], v145
	ds_read_b128 v[202:205], v145 offset:1024
	ds_read_b128 v[206:209], v145 offset:2048
	ds_read_b128 v[210:213], v145 offset:3072
	ds_read_b128 v[214:217], v145 offset:4096
	ds_read_b128 v[218:221], v145 offset:5120
	ds_read_b128 v[222:225], v145 offset:6144
	ds_read_b128 v[226:229], v145 offset:7168
	global_load_lds_dwordx4 v[230:231], off
	v_lshl_add_u64 v[230:231], s[50:51], 0, v[134:135]
	s_add_i32 m0, s19, 0xe000
	s_nop 0
	global_load_lds_dwordx4 v[230:231], off
	s_waitcnt lgkmcnt(8)
	s_barrier
	s_nop 0
	s_setprio 1
	s_waitcnt lgkmcnt(7)
	v_mfma_f32_16x16x32_bf16 v[124:127], v[168:171], v[198:201], v[124:127]
	v_mfma_f32_16x16x32_bf16 v[120:123], v[176:179], v[198:201], v[120:123]
	s_waitcnt lgkmcnt(5)
	v_mfma_f32_16x16x32_bf16 v[116:119], v[168:171], v[206:209], v[116:119]
	v_mfma_f32_16x16x32_bf16 v[112:115], v[176:179], v[206:209], v[112:115]
	s_waitcnt lgkmcnt(3)
	v_mfma_f32_16x16x32_bf16 v[100:103], v[168:171], v[214:217], v[100:103]
	v_mfma_f32_16x16x32_bf16 v[96:99], v[176:179], v[214:217], v[96:99]
	s_waitcnt lgkmcnt(1)
	v_mfma_f32_16x16x32_bf16 v[84:87], v[168:171], v[222:225], v[84:87]
	v_mfma_f32_16x16x32_bf16 v[80:83], v[176:179], v[222:225], v[80:83]
	v_mfma_f32_16x16x32_bf16 v[124:127], v[172:175], v[202:205], v[124:127]
	v_mfma_f32_16x16x32_bf16 v[120:123], v[194:197], v[202:205], v[120:123]
	v_mfma_f32_16x16x32_bf16 v[116:119], v[172:175], v[210:213], v[116:119]
	v_mfma_f32_16x16x32_bf16 v[112:115], v[194:197], v[210:213], v[112:115]
	v_mfma_f32_16x16x32_bf16 v[100:103], v[172:175], v[218:221], v[100:103]
	v_mfma_f32_16x16x32_bf16 v[96:99], v[194:197], v[218:221], v[96:99]
	s_waitcnt lgkmcnt(0)
	v_mfma_f32_16x16x32_bf16 v[84:87], v[172:175], v[226:229], v[84:87]
	v_mfma_f32_16x16x32_bf16 v[80:83], v[194:197], v[226:229], v[80:83]
	s_setprio 0
	s_barrier
	s_add_i32 s28, s71, s6
	v_lshl_add_u64 v[246:247], s[52:53], 0, v[130:131]
	s_mov_b32 m0, s28
	ds_read_b128 v[230:233], v151
	ds_read_b128 v[234:237], v151 offset:1024
	ds_read_b128 v[238:241], v151 offset:2048
	ds_read_b128 v[242:245], v151 offset:3072
	global_load_lds_dwordx4 v[246:247], off
	v_lshl_add_u64 v[248:249], s[52:53], 0, v[128:129]
	s_add_i32 m0, s28, 0x2000
	s_nop 0
	global_load_lds_dwordx4 v[248:249], off
	s_barrier
	s_nop 0
	s_setprio 1
	s_waitcnt lgkmcnt(3)
	v_mfma_f32_16x16x32_bf16 v[108:111], v[230:233], v[198:201], v[108:111]
	s_waitcnt lgkmcnt(1)
	v_mfma_f32_16x16x32_bf16 v[104:107], v[238:241], v[198:201], v[104:107]
	v_mfma_f32_16x16x32_bf16 v[92:95], v[230:233], v[206:209], v[92:95]
	v_mfma_f32_16x16x32_bf16 v[88:91], v[238:241], v[206:209], v[88:91]
	v_mfma_f32_16x16x32_bf16 v[76:79], v[230:233], v[214:217], v[76:79]
	v_mfma_f32_16x16x32_bf16 v[72:75], v[238:241], v[214:217], v[72:75]
	v_mfma_f32_16x16x32_bf16 v[68:71], v[230:233], v[222:225], v[68:71]
	v_mfma_f32_16x16x32_bf16 v[64:67], v[238:241], v[222:225], v[64:67]
	v_mfma_f32_16x16x32_bf16 v[108:111], v[234:237], v[202:205], v[108:111]
	s_waitcnt lgkmcnt(0)
	v_mfma_f32_16x16x32_bf16 v[104:107], v[242:245], v[202:205], v[104:107]
	v_mfma_f32_16x16x32_bf16 v[92:95], v[234:237], v[210:213], v[92:95]
	v_mfma_f32_16x16x32_bf16 v[88:91], v[242:245], v[210:213], v[88:91]
	v_mfma_f32_16x16x32_bf16 v[76:79], v[234:237], v[218:221], v[76:79]
	v_mfma_f32_16x16x32_bf16 v[72:75], v[242:245], v[218:221], v[72:75]
	v_mfma_f32_16x16x32_bf16 v[68:71], v[234:237], v[226:229], v[68:71]
	v_mfma_f32_16x16x32_bf16 v[64:67], v[242:245], v[226:229], v[64:67]
	s_setprio 0
	s_mov_b32 m0, s19
	v_lshl_add_u64 v[250:251], s[54:55], 0, v[156:157]
	s_barrier
	ds_read_b128 v[198:201], v145 offset:16384
	ds_read_b128 v[202:205], v145 offset:17408
	ds_read_b128 v[206:209], v145 offset:18432
	ds_read_b128 v[210:213], v145 offset:19456
	ds_read_b128 v[214:217], v145 offset:20480
	ds_read_b128 v[218:221], v145 offset:21504
	ds_read_b128 v[222:225], v145 offset:22528
	ds_read_b128 v[226:229], v145 offset:23552
	global_load_lds_dwordx4 v[250:251], off
	v_lshl_add_u64 v[252:253], s[54:55], 0, v[160:161]
	s_mov_b32 m0, s21
	s_nop 0
	global_load_lds_dwordx4 v[252:253], off
	s_barrier
	s_nop 0
	s_setprio 1
	s_waitcnt lgkmcnt(7)
	v_mfma_f32_16x16x32_bf16 v[60:63], v[168:171], v[198:201], v[60:63]
	v_mfma_f32_16x16x32_bf16 v[56:59], v[176:179], v[198:201], v[56:59]
	s_waitcnt lgkmcnt(5)
	v_mfma_f32_16x16x32_bf16 v[52:55], v[168:171], v[206:209], v[52:55]
	v_mfma_f32_16x16x32_bf16 v[48:51], v[176:179], v[206:209], v[48:51]
	s_waitcnt lgkmcnt(3)
	v_mfma_f32_16x16x32_bf16 v[36:39], v[168:171], v[214:217], v[36:39]
	v_mfma_f32_16x16x32_bf16 v[32:35], v[176:179], v[214:217], v[32:35]
	s_waitcnt lgkmcnt(1)
	v_mfma_f32_16x16x32_bf16 v[20:23], v[168:171], v[222:225], v[20:23]
	v_mfma_f32_16x16x32_bf16 v[16:19], v[176:179], v[222:225], v[16:19]
	v_mfma_f32_16x16x32_bf16 v[60:63], v[172:175], v[202:205], v[60:63]
	v_mfma_f32_16x16x32_bf16 v[56:59], v[194:197], v[202:205], v[56:59]
	v_mfma_f32_16x16x32_bf16 v[52:55], v[172:175], v[210:213], v[52:55]
	v_mfma_f32_16x16x32_bf16 v[48:51], v[194:197], v[210:213], v[48:51]
	v_mfma_f32_16x16x32_bf16 v[36:39], v[172:175], v[218:221], v[36:39]
	v_mfma_f32_16x16x32_bf16 v[32:35], v[194:197], v[218:221], v[32:35]
	s_waitcnt lgkmcnt(0)
	v_mfma_f32_16x16x32_bf16 v[20:23], v[172:175], v[226:229], v[20:23]
	v_mfma_f32_16x16x32_bf16 v[16:19], v[194:197], v[226:229], v[16:19]
	s_setprio 0
	s_barrier
	s_add_u32 s28, s52, 0x20000
	s_addc_u32 s29, s53, 0
	s_add_i32 s82, s72, s6
	v_lshl_add_u64 v[168:169], s[28:29], 0, v[130:131]
	s_mov_b32 m0, s82
	s_nop 0
	global_load_lds_dwordx4 v[168:169], off
	v_lshl_add_u64 v[168:169], s[28:29], 0, v[128:129]
	s_add_i32 m0, s82, 0x2000
	s_nop 0
	global_load_lds_dwordx4 v[168:169], off
	s_waitcnt vmcnt(6)
	s_barrier
	s_setprio 1
	v_mfma_f32_16x16x32_bf16 v[44:47], v[230:233], v[198:201], v[44:47]
	v_mfma_f32_16x16x32_bf16 v[40:43], v[238:241], v[198:201], v[40:43]
	v_mfma_f32_16x16x32_bf16 v[28:31], v[230:233], v[206:209], v[28:31]
	v_mfma_f32_16x16x32_bf16 v[24:27], v[238:241], v[206:209], v[24:27]
	v_mfma_f32_16x16x32_bf16 v[12:15], v[230:233], v[214:217], v[12:15]
	v_mfma_f32_16x16x32_bf16 v[8:11], v[238:241], v[214:217], v[8:11]
	v_mfma_f32_16x16x32_bf16 v[4:7], v[230:233], v[222:225], v[4:7]
	v_mfma_f32_16x16x32_bf16 v[0:3], v[238:241], v[222:225], v[0:3]
	v_mfma_f32_16x16x32_bf16 v[44:47], v[234:237], v[202:205], v[44:47]
	v_mfma_f32_16x16x32_bf16 v[40:43], v[242:245], v[202:205], v[40:43]
	v_mfma_f32_16x16x32_bf16 v[28:31], v[234:237], v[210:213], v[28:31]
	v_mfma_f32_16x16x32_bf16 v[24:27], v[242:245], v[210:213], v[24:27]
	v_mfma_f32_16x16x32_bf16 v[12:15], v[234:237], v[218:221], v[12:15]
	v_mfma_f32_16x16x32_bf16 v[8:11], v[242:245], v[218:221], v[8:11]
	v_mfma_f32_16x16x32_bf16 v[4:7], v[234:237], v[226:229], v[4:7]
	v_mfma_f32_16x16x32_bf16 v[0:3], v[242:245], v[226:229], v[0:3]
	s_setprio 0
	s_add_i32 s82, 0, 0x18000
	v_add_u32_e32 v153, s82, v141
	s_barrier
	ds_read_b128 v[168:171], v153
	ds_read_b128 v[172:175], v153 offset:1024
	ds_read_b128 v[176:179], v153 offset:2048
	ds_read_b128 v[194:197], v153 offset:3072
	s_add_u32 s28, s54, 0x40000
	s_addc_u32 s29, s55, 0
	s_mov_b32 m0, s26
	v_lshl_add_u64 v[230:231], s[28:29], 0, v[156:157]
	ds_read_b128 v[198:201], v145 offset:32768
	ds_read_b128 v[202:205], v145 offset:33792
	ds_read_b128 v[206:209], v145 offset:34816
	ds_read_b128 v[210:213], v145 offset:35840
	ds_read_b128 v[214:217], v145 offset:36864
	ds_read_b128 v[218:221], v145 offset:37888
	ds_read_b128 v[222:225], v145 offset:38912
	ds_read_b128 v[226:229], v145 offset:39936
	global_load_lds_dwordx4 v[230:231], off
	v_lshl_add_u64 v[230:231], s[28:29], 0, v[160:161]
	s_mov_b32 m0, s27
	s_nop 0
	global_load_lds_dwordx4 v[230:231], off
	s_waitcnt lgkmcnt(8)
	s_barrier
	s_nop 0
	s_setprio 1
	s_waitcnt lgkmcnt(7)
	v_mfma_f32_16x16x32_bf16 v[124:127], v[168:171], v[198:201], v[124:127]
	v_mfma_f32_16x16x32_bf16 v[120:123], v[176:179], v[198:201], v[120:123]
	s_waitcnt lgkmcnt(5)
	v_mfma_f32_16x16x32_bf16 v[116:119], v[168:171], v[206:209], v[116:119]
	v_mfma_f32_16x16x32_bf16 v[112:115], v[176:179], v[206:209], v[112:115]
	s_waitcnt lgkmcnt(3)
	v_mfma_f32_16x16x32_bf16 v[100:103], v[168:171], v[214:217], v[100:103]
	v_mfma_f32_16x16x32_bf16 v[96:99], v[176:179], v[214:217], v[96:99]
	s_waitcnt lgkmcnt(1)
	v_mfma_f32_16x16x32_bf16 v[84:87], v[168:171], v[222:225], v[84:87]
	v_mfma_f32_16x16x32_bf16 v[80:83], v[176:179], v[222:225], v[80:83]
	v_mfma_f32_16x16x32_bf16 v[124:127], v[172:175], v[202:205], v[124:127]
	v_mfma_f32_16x16x32_bf16 v[120:123], v[194:197], v[202:205], v[120:123]
	v_mfma_f32_16x16x32_bf16 v[116:119], v[172:175], v[210:213], v[116:119]
	v_mfma_f32_16x16x32_bf16 v[112:115], v[194:197], v[210:213], v[112:115]
	v_mfma_f32_16x16x32_bf16 v[100:103], v[172:175], v[218:221], v[100:103]
	v_mfma_f32_16x16x32_bf16 v[96:99], v[194:197], v[218:221], v[96:99]
	s_waitcnt lgkmcnt(0)
	v_mfma_f32_16x16x32_bf16 v[84:87], v[172:175], v[226:229], v[84:87]
	v_mfma_f32_16x16x32_bf16 v[80:83], v[194:197], v[226:229], v[80:83]
	s_setprio 0
	s_barrier
	s_add_i32 s54, 0, 0x1c000
	s_add_i32 s28, s82, s6
	v_add_u32_e32 v153, s54, v141
	v_lshl_add_u64 v[246:247], v[246:247], 0, s[10:11]
	s_mov_b32 m0, s28
	ds_read_b128 v[230:233], v153
	ds_read_b128 v[234:237], v153 offset:1024
	ds_read_b128 v[238:241], v153 offset:2048
	ds_read_b128 v[242:245], v153 offset:3072
	global_load_lds_dwordx4 v[246:247], off
	v_lshl_add_u64 v[246:247], v[248:249], 0, s[10:11]
	s_add_i32 m0, s28, 0x2000
	s_nop 0
	global_load_lds_dwordx4 v[246:247], off
	s_barrier
	s_nop 0
	s_setprio 1
	s_waitcnt lgkmcnt(3)
	v_mfma_f32_16x16x32_bf16 v[108:111], v[230:233], v[198:201], v[108:111]
	s_waitcnt lgkmcnt(1)
	v_mfma_f32_16x16x32_bf16 v[104:107], v[238:241], v[198:201], v[104:107]
	v_mfma_f32_16x16x32_bf16 v[92:95], v[230:233], v[206:209], v[92:95]
	v_mfma_f32_16x16x32_bf16 v[88:91], v[238:241], v[206:209], v[88:91]
	v_mfma_f32_16x16x32_bf16 v[76:79], v[230:233], v[214:217], v[76:79]
	v_mfma_f32_16x16x32_bf16 v[72:75], v[238:241], v[214:217], v[72:75]
	v_mfma_f32_16x16x32_bf16 v[68:71], v[230:233], v[222:225], v[68:71]
	v_mfma_f32_16x16x32_bf16 v[64:67], v[238:241], v[222:225], v[64:67]
	v_mfma_f32_16x16x32_bf16 v[108:111], v[234:237], v[202:205], v[108:111]
	s_waitcnt lgkmcnt(0)
	v_mfma_f32_16x16x32_bf16 v[104:107], v[242:245], v[202:205], v[104:107]
	v_mfma_f32_16x16x32_bf16 v[92:95], v[234:237], v[210:213], v[92:95]
	v_mfma_f32_16x16x32_bf16 v[88:91], v[242:245], v[210:213], v[88:91]
	v_mfma_f32_16x16x32_bf16 v[76:79], v[234:237], v[218:221], v[76:79]
	v_mfma_f32_16x16x32_bf16 v[72:75], v[242:245], v[218:221], v[72:75]
	v_mfma_f32_16x16x32_bf16 v[68:71], v[234:237], v[226:229], v[68:71]
	v_mfma_f32_16x16x32_bf16 v[64:67], v[242:245], v[226:229], v[64:67]
	s_setprio 0
	s_mov_b32 m0, s57
	v_lshl_add_u64 v[246:247], v[250:251], 0, s[10:11]
	s_barrier
	ds_read_b128 v[198:201], v145 offset:49152
	ds_read_b128 v[202:205], v145 offset:50176
	ds_read_b128 v[206:209], v145 offset:51200
	ds_read_b128 v[210:213], v145 offset:52224
	ds_read_b128 v[214:217], v145 offset:53248
	ds_read_b128 v[218:221], v145 offset:54272
	ds_read_b128 v[222:225], v145 offset:55296
	ds_read_b128 v[226:229], v145 offset:56320
	global_load_lds_dwordx4 v[246:247], off
	v_lshl_add_u64 v[246:247], v[252:253], 0, s[10:11]
	s_mov_b32 m0, s64
	s_nop 0
	global_load_lds_dwordx4 v[246:247], off
	s_barrier
	s_nop 0
	s_setprio 1
	s_waitcnt lgkmcnt(7)
	v_mfma_f32_16x16x32_bf16 v[60:63], v[168:171], v[198:201], v[60:63]
	v_mfma_f32_16x16x32_bf16 v[56:59], v[176:179], v[198:201], v[56:59]
	s_waitcnt lgkmcnt(5)
	v_mfma_f32_16x16x32_bf16 v[52:55], v[168:171], v[206:209], v[52:55]
	v_mfma_f32_16x16x32_bf16 v[48:51], v[176:179], v[206:209], v[48:51]
	s_waitcnt lgkmcnt(3)
	v_mfma_f32_16x16x32_bf16 v[36:39], v[168:171], v[214:217], v[36:39]
	v_mfma_f32_16x16x32_bf16 v[32:35], v[176:179], v[214:217], v[32:35]
	s_waitcnt lgkmcnt(1)
	v_mfma_f32_16x16x32_bf16 v[20:23], v[168:171], v[222:225], v[20:23]
	v_mfma_f32_16x16x32_bf16 v[16:19], v[176:179], v[222:225], v[16:19]
	v_mfma_f32_16x16x32_bf16 v[60:63], v[172:175], v[202:205], v[60:63]
	v_mfma_f32_16x16x32_bf16 v[56:59], v[194:197], v[202:205], v[56:59]
	v_mfma_f32_16x16x32_bf16 v[52:55], v[172:175], v[210:213], v[52:55]
	v_mfma_f32_16x16x32_bf16 v[48:51], v[194:197], v[210:213], v[48:51]
	v_mfma_f32_16x16x32_bf16 v[36:39], v[172:175], v[218:221], v[36:39]
	v_mfma_f32_16x16x32_bf16 v[32:35], v[194:197], v[218:221], v[32:35]
	s_waitcnt lgkmcnt(0)
	v_mfma_f32_16x16x32_bf16 v[20:23], v[172:175], v[226:229], v[20:23]
	v_mfma_f32_16x16x32_bf16 v[16:19], v[194:197], v[226:229], v[16:19]
	s_setprio 0
	s_barrier
	s_add_u32 s28, s52, 0x20080
	s_addc_u32 s29, s53, 0
	s_add_i32 s52, s54, s6
	v_lshl_add_u64 v[168:169], s[28:29], 0, v[130:131]
	s_mov_b32 m0, s52
	s_nop 0
	global_load_lds_dwordx4 v[168:169], off
	v_lshl_add_u64 v[168:169], s[28:29], 0, v[128:129]
	s_add_i32 m0, s52, 0x2000
	s_nop 0
	global_load_lds_dwordx4 v[168:169], off
	s_waitcnt vmcnt(6)
	s_barrier
	s_setprio 1
	v_mfma_f32_16x16x32_bf16 v[44:47], v[230:233], v[198:201], v[44:47]
	v_mfma_f32_16x16x32_bf16 v[40:43], v[238:241], v[198:201], v[40:43]
	v_mfma_f32_16x16x32_bf16 v[28:31], v[230:233], v[206:209], v[28:31]
	v_mfma_f32_16x16x32_bf16 v[24:27], v[238:241], v[206:209], v[24:27]
	v_mfma_f32_16x16x32_bf16 v[12:15], v[230:233], v[214:217], v[12:15]
	v_mfma_f32_16x16x32_bf16 v[8:11], v[238:241], v[214:217], v[8:11]
	v_mfma_f32_16x16x32_bf16 v[4:7], v[230:233], v[222:225], v[4:7]
	v_mfma_f32_16x16x32_bf16 v[0:3], v[238:241], v[222:225], v[0:3]
	v_mfma_f32_16x16x32_bf16 v[44:47], v[234:237], v[202:205], v[44:47]
	v_mfma_f32_16x16x32_bf16 v[40:43], v[242:245], v[202:205], v[40:43]
	v_mfma_f32_16x16x32_bf16 v[28:31], v[234:237], v[210:213], v[28:31]
	v_mfma_f32_16x16x32_bf16 v[24:27], v[242:245], v[210:213], v[24:27]
	v_mfma_f32_16x16x32_bf16 v[12:15], v[234:237], v[218:221], v[12:15]
	v_mfma_f32_16x16x32_bf16 v[8:11], v[242:245], v[218:221], v[8:11]
	v_mfma_f32_16x16x32_bf16 v[4:7], v[234:237], v[226:229], v[4:7]
	v_mfma_f32_16x16x32_bf16 v[0:3], v[242:245], v[226:229], v[0:3]
	s_setprio 0
	s_add_i32 s81, s81, 2
	s_add_u32 s79, s79, 0x100
	s_addc_u32 s80, s80, 0
	s_add_u32 s50, s50, 0x200
	s_addc_u32 s51, s51, 0
	s_cmp_gt_u32 s81, 5
	s_barrier
	s_cbranch_scc0 .LBB0_822
	s_cmp_eq_u32 s18, 0
	s_cselect_b32 s18, s39, 0
	s_cselect_b32 s23, s38, 0
	v_lshl_or_b32 v170, s77, 8, v142
	v_lshl_add_u32 v172, s20, 8, v140
	v_mov_b32_e32 v168, s23
	v_mov_b32_e32 v169, s18
	v_ashrrev_i32_e32 v171, 31, v170
	v_ashrrev_i32_e32 v173, 31, v172
	v_lshl_add_u64 v[168:169], v[170:171], 1, v[168:169]
	v_lshlrev_b64 v[170:171], 11, v[172:173]
	v_lshl_add_u64 v[170:171], v[168:169], 0, v[170:171]
	v_cvt_pk_bf16_f32 v60, v60, v61
	v_cvt_pk_bf16_f32 v61, v62, v63
	v_cvt_pk_bf16_f32 v62, v56, v57
	v_add_co_u32_e32 v56, vcc, s73, v170
	v_cvt_pk_bf16_f32 v68, v68, v69
	v_cvt_pk_bf16_f32 v69, v70, v71
	v_cvt_pk_bf16_f32 v70, v64, v65
	v_lshl_add_u64 v[64:65], v[170:171], 0, s[0:1]
	v_addc_co_u32_e32 v57, vcc, 0, v171, vcc
	v_cvt_pk_bf16_f32 v44, v44, v45
	v_cvt_pk_bf16_f32 v45, v46, v47
	v_cvt_pk_bf16_f32 v46, v40, v41
	v_cvt_pk_bf16_f32 v47, v42, v43
	global_store_dwordx4 v[64:65], v[44:47], off offset:256
	v_cvt_pk_bf16_f32 v108, v108, v109
	v_cvt_pk_bf16_f32 v109, v110, v111
	v_add_co_u32_e32 v46, vcc, s74, v170
	v_cvt_pk_bf16_f32 v110, v104, v105
	v_or_b32_e32 v104, 16, v172
	v_lshl_add_u64 v[44:45], v[170:171], 0, s[12:13]
	v_addc_co_u32_e32 v47, vcc, 0, v171, vcc
	v_cvt_pk_bf16_f32 v28, v28, v29
	v_cvt_pk_bf16_f32 v29, v30, v31
	v_cvt_pk_bf16_f32 v30, v24, v25
	v_cvt_pk_bf16_f32 v31, v26, v27
	v_ashrrev_i32_e32 v105, 31, v104
	v_cvt_pk_bf16_f32 v92, v92, v93
	v_cvt_pk_bf16_f32 v93, v94, v95
	v_cvt_pk_bf16_f32 v94, v88, v89
	v_or_b32_e32 v88, 32, v172
	global_store_dwordx4 v[44:45], v[28:31], off offset:256
	v_cvt_pk_bf16_f32 v111, v106, v107
	v_lshlrev_b64 v[104:105], 11, v[104:105]
	v_add_co_u32_e32 v30, vcc, s75, v170
	v_ashrrev_i32_e32 v89, 31, v88
	v_cvt_pk_bf16_f32 v76, v76, v77
	v_cvt_pk_bf16_f32 v77, v78, v79
	v_cvt_pk_bf16_f32 v78, v72, v73
	v_or_b32_e32 v72, 48, v172
	v_lshl_add_u64 v[28:29], v[170:171], 0, s[14:15]
	v_addc_co_u32_e32 v31, vcc, 0, v171, vcc
	v_cvt_pk_bf16_f32 v12, v12, v13
	v_cvt_pk_bf16_f32 v13, v14, v15
	v_cvt_pk_bf16_f32 v14, v8, v9
	v_cvt_pk_bf16_f32 v15, v10, v11
	global_store_dwordx4 v[170:171], v[108:111], off offset:256
	v_cvt_pk_bf16_f32 v95, v90, v91
	v_lshlrev_b64 v[88:89], 11, v[88:89]
	v_lshl_add_u64 v[108:109], v[168:169], 0, v[104:105]
	v_ashrrev_i32_e32 v73, 31, v72
	global_store_dwordx4 v[28:29], v[12:15], off offset:256
	global_store_dwordx4 v[108:109], v[92:95], off offset:256
	v_cvt_pk_bf16_f32 v79, v74, v75
	v_add_co_u32_e32 v14, vcc, s76, v170
	v_lshl_add_u64 v[92:93], v[168:169], 0, v[88:89]
	v_lshlrev_b64 v[72:73], 11, v[72:73]
	v_addc_co_u32_e32 v15, vcc, 0, v171, vcc
	v_cvt_pk_bf16_f32 v124, v124, v125
	v_cvt_pk_bf16_f32 v125, v126, v127
	v_cvt_pk_bf16_f32 v126, v120, v121
	v_cvt_pk_bf16_f32 v127, v122, v123
	v_cvt_pk_bf16_f32 v104, v116, v117
	v_cvt_pk_bf16_f32 v105, v118, v119
	v_cvt_pk_bf16_f32 v106, v112, v113
	v_cvt_pk_bf16_f32 v107, v114, v115
	v_cvt_pk_bf16_f32 v88, v100, v101
	v_cvt_pk_bf16_f32 v89, v102, v103
	v_cvt_pk_bf16_f32 v90, v96, v97
	v_cvt_pk_bf16_f32 v91, v98, v99
	global_store_dwordx4 v[92:93], v[76:79], off offset:256
	v_cvt_pk_bf16_f32 v74, v80, v81
	v_cvt_pk_bf16_f32 v75, v82, v83
	v_lshl_add_u64 v[76:77], v[168:169], 0, v[72:73]
	v_cvt_pk_bf16_f32 v72, v84, v85
	v_cvt_pk_bf16_f32 v73, v86, v87
	v_cvt_pk_bf16_f32 v71, v66, v67
	v_cvt_pk_bf16_f32 v63, v58, v59
	v_cvt_pk_bf16_f32 v40, v52, v53
	v_cvt_pk_bf16_f32 v41, v54, v55
	v_cvt_pk_bf16_f32 v42, v48, v49
	v_cvt_pk_bf16_f32 v43, v50, v51
	v_cvt_pk_bf16_f32 v24, v36, v37
	v_cvt_pk_bf16_f32 v25, v38, v39
	v_cvt_pk_bf16_f32 v26, v32, v33
	v_cvt_pk_bf16_f32 v27, v34, v35
	v_lshl_add_u64 v[12:13], v[170:171], 0, s[16:17]
	v_cvt_pk_bf16_f32 v8, v20, v21
	v_cvt_pk_bf16_f32 v9, v22, v23
	v_cvt_pk_bf16_f32 v10, v16, v17
	v_cvt_pk_bf16_f32 v11, v18, v19
	v_cvt_pk_bf16_f32 v4, v4, v5
	v_cvt_pk_bf16_f32 v5, v6, v7
	v_cvt_pk_bf16_f32 v6, v0, v1
	v_cvt_pk_bf16_f32 v7, v2, v3
	s_and_b64 vcc, exec, s[8:9]
	s_mov_b32 s18, s22
	s_mov_b32 s77, s44
	s_mov_b32 s20, s24
	s_mov_b64 s[50:51], s[48:49]
	s_mov_b64 s[52:53], s[46:47]
	global_store_dwordx4 v[170:171], v[124:127], off
	global_store_dwordx4 v[108:109], v[104:107], off
	global_store_dwordx4 v[92:93], v[88:91], off
	global_store_dwordx4 v[76:77], v[72:75], off
	global_store_dwordx4 v[76:77], v[68:71], off offset:256
	global_store_dwordx4 v[56:57], v[60:63], off
	global_store_dwordx4 v[46:47], v[40:43], off
	global_store_dwordx4 v[30:31], v[24:27], off
	global_store_dwordx4 v[14:15], v[8:11], off
	global_store_dwordx4 v[12:13], v[4:7], off offset:256
	s_cbranch_vccz .LBB0_819
	s_waitcnt vmcnt(0)
	s_cmpk_gt_u32 s3, 0xff
	s_cbranch_scc1 .LBB0_826
	s_barrier

.LBB0_834:
	ds_read_b128 v[168:171], v155
	ds_read_b128 v[172:175], v155 offset:1024
	ds_read_b128 v[176:179], v155 offset:2048
	ds_read_b128 v[194:197], v155 offset:3072
	s_add_u32 s28, s50, 0xfffe0080
	s_addc_u32 s29, s51, -1
	s_cmp_eq_u32 s81, 4
	s_cselect_b32 s55, s21, s29
	s_cselect_b32 s54, s25, s28
	s_cselect_b32 s53, s45, s80
	s_cselect_b32 s52, s78, s79
	v_lshl_add_u64 v[230:231], s[50:51], 0, v[136:137]
	s_add_i32 m0, s19, 0xc000
	ds_read_b128 v[198:201], v157
	ds_read_b128 v[202:205], v157 offset:1024
	ds_read_b128 v[206:209], v157 offset:2048
	ds_read_b128 v[210:213], v157 offset:3072
	ds_read_b128 v[214:217], v157 offset:4096
	ds_read_b128 v[218:221], v157 offset:5120
	ds_read_b128 v[222:225], v157 offset:6144
	ds_read_b128 v[226:229], v157 offset:7168
	global_load_lds_dwordx4 v[230:231], off
	v_lshl_add_u64 v[230:231], s[50:51], 0, v[138:139]
	s_add_i32 m0, s19, 0xe000
	s_nop 0
	global_load_lds_dwordx4 v[230:231], off
	s_waitcnt lgkmcnt(8)
	s_barrier
	s_nop 0
	s_setprio 1
	s_waitcnt lgkmcnt(7)
	v_mfma_f32_16x16x32_bf16 v[124:127], v[168:171], v[198:201], v[124:127]
	v_mfma_f32_16x16x32_bf16 v[120:123], v[176:179], v[198:201], v[120:123]
	s_waitcnt lgkmcnt(5)
	v_mfma_f32_16x16x32_bf16 v[116:119], v[168:171], v[206:209], v[116:119]
	v_mfma_f32_16x16x32_bf16 v[112:115], v[176:179], v[206:209], v[112:115]
	s_waitcnt lgkmcnt(3)
	v_mfma_f32_16x16x32_bf16 v[100:103], v[168:171], v[214:217], v[100:103]
	v_mfma_f32_16x16x32_bf16 v[96:99], v[176:179], v[214:217], v[96:99]
	s_waitcnt lgkmcnt(1)
	v_mfma_f32_16x16x32_bf16 v[84:87], v[168:171], v[222:225], v[84:87]
	v_mfma_f32_16x16x32_bf16 v[80:83], v[176:179], v[222:225], v[80:83]
	v_mfma_f32_16x16x32_bf16 v[124:127], v[172:175], v[202:205], v[124:127]
	v_mfma_f32_16x16x32_bf16 v[120:123], v[194:197], v[202:205], v[120:123]
	v_mfma_f32_16x16x32_bf16 v[116:119], v[172:175], v[210:213], v[116:119]
	v_mfma_f32_16x16x32_bf16 v[112:115], v[194:197], v[210:213], v[112:115]
	v_mfma_f32_16x16x32_bf16 v[100:103], v[172:175], v[218:221], v[100:103]
	v_mfma_f32_16x16x32_bf16 v[96:99], v[194:197], v[218:221], v[96:99]
	s_waitcnt lgkmcnt(0)
	v_mfma_f32_16x16x32_bf16 v[84:87], v[172:175], v[226:229], v[84:87]
	v_mfma_f32_16x16x32_bf16 v[80:83], v[194:197], v[226:229], v[80:83]
	s_setprio 0
	s_barrier
	s_add_i32 s28, s71, s6
	v_lshl_add_u64 v[246:247], s[52:53], 0, v[130:131]
	s_mov_b32 m0, s28
	ds_read_b128 v[230:233], v159
	ds_read_b128 v[234:237], v159 offset:1024
	ds_read_b128 v[238:241], v159 offset:2048
	ds_read_b128 v[242:245], v159 offset:3072
	global_load_lds_dwordx4 v[246:247], off
	v_lshl_add_u64 v[248:249], s[52:53], 0, v[128:129]
	s_add_i32 m0, s28, 0x2000
	s_nop 0
	global_load_lds_dwordx4 v[248:249], off
	s_barrier
	s_nop 0
	s_setprio 1
	s_waitcnt lgkmcnt(3)
	v_mfma_f32_16x16x32_bf16 v[108:111], v[230:233], v[198:201], v[108:111]
	s_waitcnt lgkmcnt(1)
	v_mfma_f32_16x16x32_bf16 v[104:107], v[238:241], v[198:201], v[104:107]
	v_mfma_f32_16x16x32_bf16 v[92:95], v[230:233], v[206:209], v[92:95]
	v_mfma_f32_16x16x32_bf16 v[88:91], v[238:241], v[206:209], v[88:91]
	v_mfma_f32_16x16x32_bf16 v[76:79], v[230:233], v[214:217], v[76:79]
	v_mfma_f32_16x16x32_bf16 v[72:75], v[238:241], v[214:217], v[72:75]
	v_mfma_f32_16x16x32_bf16 v[68:71], v[230:233], v[222:225], v[68:71]
	v_mfma_f32_16x16x32_bf16 v[64:67], v[238:241], v[222:225], v[64:67]
	v_mfma_f32_16x16x32_bf16 v[108:111], v[234:237], v[202:205], v[108:111]
	s_waitcnt lgkmcnt(0)
	v_mfma_f32_16x16x32_bf16 v[104:107], v[242:245], v[202:205], v[104:107]
	v_mfma_f32_16x16x32_bf16 v[92:95], v[234:237], v[210:213], v[92:95]
	v_mfma_f32_16x16x32_bf16 v[88:91], v[242:245], v[210:213], v[88:91]
	v_mfma_f32_16x16x32_bf16 v[76:79], v[234:237], v[218:221], v[76:79]
	v_mfma_f32_16x16x32_bf16 v[72:75], v[242:245], v[218:221], v[72:75]
	v_mfma_f32_16x16x32_bf16 v[68:71], v[234:237], v[226:229], v[68:71]
	v_mfma_f32_16x16x32_bf16 v[64:67], v[242:245], v[226:229], v[64:67]
	s_setprio 0
	s_mov_b32 m0, s19
	v_lshl_add_u64 v[250:251], s[54:55], 0, v[134:135]
	s_barrier
	ds_read_b128 v[198:201], v157 offset:16384
	ds_read_b128 v[202:205], v157 offset:17408
	ds_read_b128 v[206:209], v157 offset:18432
	ds_read_b128 v[210:213], v157 offset:19456
	ds_read_b128 v[214:217], v157 offset:20480
	ds_read_b128 v[218:221], v157 offset:21504
	ds_read_b128 v[222:225], v157 offset:22528
	ds_read_b128 v[226:229], v157 offset:23552
	global_load_lds_dwordx4 v[250:251], off
	v_lshl_add_u64 v[252:253], s[54:55], 0, v[132:133]
	s_mov_b32 m0, s23
	s_nop 0
	global_load_lds_dwordx4 v[252:253], off
	s_barrier
	s_nop 0
	s_setprio 1
	s_waitcnt lgkmcnt(7)
	v_mfma_f32_16x16x32_bf16 v[60:63], v[168:171], v[198:201], v[60:63]
	v_mfma_f32_16x16x32_bf16 v[56:59], v[176:179], v[198:201], v[56:59]
	s_waitcnt lgkmcnt(5)
	v_mfma_f32_16x16x32_bf16 v[52:55], v[168:171], v[206:209], v[52:55]
	v_mfma_f32_16x16x32_bf16 v[48:51], v[176:179], v[206:209], v[48:51]
	s_waitcnt lgkmcnt(3)
	v_mfma_f32_16x16x32_bf16 v[36:39], v[168:171], v[214:217], v[36:39]
	v_mfma_f32_16x16x32_bf16 v[32:35], v[176:179], v[214:217], v[32:35]
	s_waitcnt lgkmcnt(1)
	v_mfma_f32_16x16x32_bf16 v[20:23], v[168:171], v[222:225], v[20:23]
	v_mfma_f32_16x16x32_bf16 v[16:19], v[176:179], v[222:225], v[16:19]
	v_mfma_f32_16x16x32_bf16 v[60:63], v[172:175], v[202:205], v[60:63]
	v_mfma_f32_16x16x32_bf16 v[56:59], v[194:197], v[202:205], v[56:59]
	v_mfma_f32_16x16x32_bf16 v[52:55], v[172:175], v[210:213], v[52:55]
	v_mfma_f32_16x16x32_bf16 v[48:51], v[194:197], v[210:213], v[48:51]
	v_mfma_f32_16x16x32_bf16 v[36:39], v[172:175], v[218:221], v[36:39]
	v_mfma_f32_16x16x32_bf16 v[32:35], v[194:197], v[218:221], v[32:35]
	s_waitcnt lgkmcnt(0)
	v_mfma_f32_16x16x32_bf16 v[20:23], v[172:175], v[226:229], v[20:23]
	v_mfma_f32_16x16x32_bf16 v[16:19], v[194:197], v[226:229], v[16:19]
	s_setprio 0
	s_barrier
	s_add_u32 s28, s52, 0x20000
	s_addc_u32 s29, s53, 0
	s_add_i32 s82, s72, s6
	v_lshl_add_u64 v[168:169], s[28:29], 0, v[130:131]
	s_mov_b32 m0, s82
	s_nop 0
	global_load_lds_dwordx4 v[168:169], off
	v_lshl_add_u64 v[168:169], s[28:29], 0, v[128:129]
	s_add_i32 m0, s82, 0x2000
	s_nop 0
	global_load_lds_dwordx4 v[168:169], off
	s_waitcnt vmcnt(6)
	s_barrier
	s_setprio 1
	v_mfma_f32_16x16x32_bf16 v[44:47], v[230:233], v[198:201], v[44:47]
	v_mfma_f32_16x16x32_bf16 v[40:43], v[238:241], v[198:201], v[40:43]
	v_mfma_f32_16x16x32_bf16 v[28:31], v[230:233], v[206:209], v[28:31]
	v_mfma_f32_16x16x32_bf16 v[24:27], v[238:241], v[206:209], v[24:27]
	v_mfma_f32_16x16x32_bf16 v[12:15], v[230:233], v[214:217], v[12:15]
	v_mfma_f32_16x16x32_bf16 v[8:11], v[238:241], v[214:217], v[8:11]
	v_mfma_f32_16x16x32_bf16 v[4:7], v[230:233], v[222:225], v[4:7]
	v_mfma_f32_16x16x32_bf16 v[0:3], v[238:241], v[222:225], v[0:3]
	v_mfma_f32_16x16x32_bf16 v[44:47], v[234:237], v[202:205], v[44:47]
	v_mfma_f32_16x16x32_bf16 v[40:43], v[242:245], v[202:205], v[40:43]
	v_mfma_f32_16x16x32_bf16 v[28:31], v[234:237], v[210:213], v[28:31]
	v_mfma_f32_16x16x32_bf16 v[24:27], v[242:245], v[210:213], v[24:27]
	v_mfma_f32_16x16x32_bf16 v[12:15], v[234:237], v[218:221], v[12:15]
	v_mfma_f32_16x16x32_bf16 v[8:11], v[242:245], v[218:221], v[8:11]
	v_mfma_f32_16x16x32_bf16 v[4:7], v[234:237], v[226:229], v[4:7]
	v_mfma_f32_16x16x32_bf16 v[0:3], v[242:245], v[226:229], v[0:3]
	s_setprio 0
	s_add_i32 s82, 0, 0x18000
	v_add_u32_e32 v161, s82, v151
	s_barrier
	ds_read_b128 v[168:171], v161
	ds_read_b128 v[172:175], v161 offset:1024
	ds_read_b128 v[176:179], v161 offset:2048
	ds_read_b128 v[194:197], v161 offset:3072
	s_add_u32 s28, s54, 0x20000
	s_addc_u32 s29, s55, 0
	s_mov_b32 m0, s26
	v_lshl_add_u64 v[230:231], s[28:29], 0, v[134:135]
	ds_read_b128 v[198:201], v157 offset:32768
	ds_read_b128 v[202:205], v157 offset:33792
	ds_read_b128 v[206:209], v157 offset:34816
	ds_read_b128 v[210:213], v157 offset:35840
	ds_read_b128 v[214:217], v157 offset:36864
	ds_read_b128 v[218:221], v157 offset:37888
	ds_read_b128 v[222:225], v157 offset:38912
	ds_read_b128 v[226:229], v157 offset:39936
	global_load_lds_dwordx4 v[230:231], off
	v_lshl_add_u64 v[230:231], s[28:29], 0, v[132:133]
	s_mov_b32 m0, s27
	s_nop 0
	global_load_lds_dwordx4 v[230:231], off
	s_waitcnt lgkmcnt(8)
	s_barrier
	s_nop 0
	s_setprio 1
	s_waitcnt lgkmcnt(7)
	v_mfma_f32_16x16x32_bf16 v[124:127], v[168:171], v[198:201], v[124:127]
	v_mfma_f32_16x16x32_bf16 v[120:123], v[176:179], v[198:201], v[120:123]
	s_waitcnt lgkmcnt(5)
	v_mfma_f32_16x16x32_bf16 v[116:119], v[168:171], v[206:209], v[116:119]
	v_mfma_f32_16x16x32_bf16 v[112:115], v[176:179], v[206:209], v[112:115]
	s_waitcnt lgkmcnt(3)
	v_mfma_f32_16x16x32_bf16 v[100:103], v[168:171], v[214:217], v[100:103]
	v_mfma_f32_16x16x32_bf16 v[96:99], v[176:179], v[214:217], v[96:99]
	s_waitcnt lgkmcnt(1)
	v_mfma_f32_16x16x32_bf16 v[84:87], v[168:171], v[222:225], v[84:87]
	v_mfma_f32_16x16x32_bf16 v[80:83], v[176:179], v[222:225], v[80:83]
	v_mfma_f32_16x16x32_bf16 v[124:127], v[172:175], v[202:205], v[124:127]
	v_mfma_f32_16x16x32_bf16 v[120:123], v[194:197], v[202:205], v[120:123]
	v_mfma_f32_16x16x32_bf16 v[116:119], v[172:175], v[210:213], v[116:119]
	v_mfma_f32_16x16x32_bf16 v[112:115], v[194:197], v[210:213], v[112:115]
	v_mfma_f32_16x16x32_bf16 v[100:103], v[172:175], v[218:221], v[100:103]
	v_mfma_f32_16x16x32_bf16 v[96:99], v[194:197], v[218:221], v[96:99]
	s_waitcnt lgkmcnt(0)
	v_mfma_f32_16x16x32_bf16 v[84:87], v[172:175], v[226:229], v[84:87]
	v_mfma_f32_16x16x32_bf16 v[80:83], v[194:197], v[226:229], v[80:83]
	s_setprio 0
	s_barrier
	s_add_i32 s54, 0, 0x1c000
	s_add_i32 s28, s82, s6
	v_add_u32_e32 v161, s54, v151
	v_lshl_add_u64 v[246:247], v[246:247], 0, s[0:1]
	s_mov_b32 m0, s28
	ds_read_b128 v[230:233], v161
	ds_read_b128 v[234:237], v161 offset:1024
	ds_read_b128 v[238:241], v161 offset:2048
	ds_read_b128 v[242:245], v161 offset:3072
	global_load_lds_dwordx4 v[246:247], off
	v_lshl_add_u64 v[246:247], v[248:249], 0, s[0:1]
	s_add_i32 m0, s28, 0x2000
	s_nop 0
	global_load_lds_dwordx4 v[246:247], off
	s_barrier
	s_nop 0
	s_setprio 1
	s_waitcnt lgkmcnt(3)
	v_mfma_f32_16x16x32_bf16 v[108:111], v[230:233], v[198:201], v[108:111]
	s_waitcnt lgkmcnt(1)
	v_mfma_f32_16x16x32_bf16 v[104:107], v[238:241], v[198:201], v[104:107]
	v_mfma_f32_16x16x32_bf16 v[92:95], v[230:233], v[206:209], v[92:95]
	v_mfma_f32_16x16x32_bf16 v[88:91], v[238:241], v[206:209], v[88:91]
	v_mfma_f32_16x16x32_bf16 v[76:79], v[230:233], v[214:217], v[76:79]
	v_mfma_f32_16x16x32_bf16 v[72:75], v[238:241], v[214:217], v[72:75]
	v_mfma_f32_16x16x32_bf16 v[68:71], v[230:233], v[222:225], v[68:71]
	v_mfma_f32_16x16x32_bf16 v[64:67], v[238:241], v[222:225], v[64:67]
	v_mfma_f32_16x16x32_bf16 v[108:111], v[234:237], v[202:205], v[108:111]
	s_waitcnt lgkmcnt(0)
	v_mfma_f32_16x16x32_bf16 v[104:107], v[242:245], v[202:205], v[104:107]
	v_mfma_f32_16x16x32_bf16 v[92:95], v[234:237], v[210:213], v[92:95]
	v_mfma_f32_16x16x32_bf16 v[88:91], v[242:245], v[210:213], v[88:91]
	v_mfma_f32_16x16x32_bf16 v[76:79], v[234:237], v[218:221], v[76:79]
	v_mfma_f32_16x16x32_bf16 v[72:75], v[242:245], v[218:221], v[72:75]
	v_mfma_f32_16x16x32_bf16 v[68:71], v[234:237], v[226:229], v[68:71]
	v_mfma_f32_16x16x32_bf16 v[64:67], v[242:245], v[226:229], v[64:67]
	s_setprio 0
	s_mov_b32 m0, s57
	v_lshl_add_u64 v[246:247], v[250:251], 0, s[0:1]
	s_barrier
	ds_read_b128 v[198:201], v157 offset:49152
	ds_read_b128 v[202:205], v157 offset:50176
	ds_read_b128 v[206:209], v157 offset:51200
	ds_read_b128 v[210:213], v157 offset:52224
	ds_read_b128 v[214:217], v157 offset:53248
	ds_read_b128 v[218:221], v157 offset:54272
	ds_read_b128 v[222:225], v157 offset:55296
	ds_read_b128 v[226:229], v157 offset:56320
	global_load_lds_dwordx4 v[246:247], off
	v_lshl_add_u64 v[246:247], v[252:253], 0, s[0:1]
	s_mov_b32 m0, s64
	s_nop 0
	global_load_lds_dwordx4 v[246:247], off
	s_barrier
	s_nop 0
	s_setprio 1
	s_waitcnt lgkmcnt(7)
	v_mfma_f32_16x16x32_bf16 v[60:63], v[168:171], v[198:201], v[60:63]
	v_mfma_f32_16x16x32_bf16 v[56:59], v[176:179], v[198:201], v[56:59]
	s_waitcnt lgkmcnt(5)
	v_mfma_f32_16x16x32_bf16 v[52:55], v[168:171], v[206:209], v[52:55]
	v_mfma_f32_16x16x32_bf16 v[48:51], v[176:179], v[206:209], v[48:51]
	s_waitcnt lgkmcnt(3)
	v_mfma_f32_16x16x32_bf16 v[36:39], v[168:171], v[214:217], v[36:39]
	v_mfma_f32_16x16x32_bf16 v[32:35], v[176:179], v[214:217], v[32:35]
	s_waitcnt lgkmcnt(1)
	v_mfma_f32_16x16x32_bf16 v[20:23], v[168:171], v[222:225], v[20:23]
	v_mfma_f32_16x16x32_bf16 v[16:19], v[176:179], v[222:225], v[16:19]
	v_mfma_f32_16x16x32_bf16 v[60:63], v[172:175], v[202:205], v[60:63]
	v_mfma_f32_16x16x32_bf16 v[56:59], v[194:197], v[202:205], v[56:59]
	v_mfma_f32_16x16x32_bf16 v[52:55], v[172:175], v[210:213], v[52:55]
	v_mfma_f32_16x16x32_bf16 v[48:51], v[194:197], v[210:213], v[48:51]
	v_mfma_f32_16x16x32_bf16 v[36:39], v[172:175], v[218:221], v[36:39]
	v_mfma_f32_16x16x32_bf16 v[32:35], v[194:197], v[218:221], v[32:35]
	s_waitcnt lgkmcnt(0)
	v_mfma_f32_16x16x32_bf16 v[20:23], v[172:175], v[226:229], v[20:23]
	v_mfma_f32_16x16x32_bf16 v[16:19], v[194:197], v[226:229], v[16:19]
	s_setprio 0
	s_barrier
	s_add_u32 s28, s52, 0x20080
	s_addc_u32 s29, s53, 0
	s_add_i32 s52, s54, s6
	v_lshl_add_u64 v[168:169], s[28:29], 0, v[130:131]
	s_mov_b32 m0, s52
	s_nop 0
	global_load_lds_dwordx4 v[168:169], off
	v_lshl_add_u64 v[168:169], s[28:29], 0, v[128:129]
	s_add_i32 m0, s52, 0x2000
	s_nop 0
	global_load_lds_dwordx4 v[168:169], off
	s_waitcnt vmcnt(6)
	s_barrier
	s_setprio 1
	v_mfma_f32_16x16x32_bf16 v[44:47], v[230:233], v[198:201], v[44:47]
	v_mfma_f32_16x16x32_bf16 v[40:43], v[238:241], v[198:201], v[40:43]
	v_mfma_f32_16x16x32_bf16 v[28:31], v[230:233], v[206:209], v[28:31]
	v_mfma_f32_16x16x32_bf16 v[24:27], v[238:241], v[206:209], v[24:27]
	v_mfma_f32_16x16x32_bf16 v[12:15], v[230:233], v[214:217], v[12:15]
	v_mfma_f32_16x16x32_bf16 v[8:11], v[238:241], v[214:217], v[8:11]
	v_mfma_f32_16x16x32_bf16 v[4:7], v[230:233], v[222:225], v[4:7]
	v_mfma_f32_16x16x32_bf16 v[0:3], v[238:241], v[222:225], v[0:3]
	v_mfma_f32_16x16x32_bf16 v[44:47], v[234:237], v[202:205], v[44:47]
	v_mfma_f32_16x16x32_bf16 v[40:43], v[242:245], v[202:205], v[40:43]
	v_mfma_f32_16x16x32_bf16 v[28:31], v[234:237], v[210:213], v[28:31]
	v_mfma_f32_16x16x32_bf16 v[24:27], v[242:245], v[210:213], v[24:27]
	v_mfma_f32_16x16x32_bf16 v[12:15], v[234:237], v[218:221], v[12:15]
	v_mfma_f32_16x16x32_bf16 v[8:11], v[242:245], v[218:221], v[8:11]
	v_mfma_f32_16x16x32_bf16 v[4:7], v[234:237], v[226:229], v[4:7]
	v_mfma_f32_16x16x32_bf16 v[0:3], v[242:245], v[226:229], v[0:3]
	s_setprio 0
	s_add_i32 s81, s81, 2
	s_add_u32 s79, s79, 0x100
	s_addc_u32 s80, s80, 0
	s_add_u32 s50, s50, 0x100
	s_addc_u32 s51, s51, 0
	s_cmp_gt_u32 s81, 5
	s_barrier
	s_cbranch_scc0 .LBB0_834
	s_cmp_eq_u32 s18, 0
	s_cselect_b32 s18, s41, 0
	s_cselect_b32 s21, s40, 0
	v_lshl_or_b32 v170, s77, 8, v153
	v_lshl_add_u32 v172, s22, 8, v145
	v_mov_b32_e32 v168, s21
	v_mov_b32_e32 v169, s18
	v_ashrrev_i32_e32 v171, 31, v170
	v_ashrrev_i32_e32 v173, 31, v172
	v_lshl_add_u64 v[168:169], v[170:171], 1, v[168:169]
	v_lshlrev_b64 v[170:171], 11, v[172:173]
	v_lshl_add_u64 v[170:171], v[168:169], 0, v[170:171]
	v_cvt_pk_bf16_f32 v60, v60, v61
	v_cvt_pk_bf16_f32 v61, v62, v63
	v_cvt_pk_bf16_f32 v62, v56, v57
	v_add_co_u32_e32 v56, vcc, s73, v170
	v_cvt_pk_bf16_f32 v68, v68, v69
	v_cvt_pk_bf16_f32 v69, v70, v71
	v_cvt_pk_bf16_f32 v70, v64, v65
	v_lshl_add_u64 v[64:65], v[170:171], 0, s[10:11]
	v_addc_co_u32_e32 v57, vcc, 0, v171, vcc
	v_cvt_pk_bf16_f32 v44, v44, v45
	v_cvt_pk_bf16_f32 v45, v46, v47
	v_cvt_pk_bf16_f32 v46, v40, v41
	v_cvt_pk_bf16_f32 v47, v42, v43
	global_store_dwordx4 v[64:65], v[44:47], off offset:256
	v_cvt_pk_bf16_f32 v108, v108, v109
	v_cvt_pk_bf16_f32 v109, v110, v111
	v_add_co_u32_e32 v46, vcc, s74, v170
	v_cvt_pk_bf16_f32 v110, v104, v105
	v_or_b32_e32 v104, 16, v172
	v_lshl_add_u64 v[44:45], v[170:171], 0, s[12:13]
	v_addc_co_u32_e32 v47, vcc, 0, v171, vcc
	v_cvt_pk_bf16_f32 v28, v28, v29
	v_cvt_pk_bf16_f32 v29, v30, v31
	v_cvt_pk_bf16_f32 v30, v24, v25
	v_cvt_pk_bf16_f32 v31, v26, v27
	v_ashrrev_i32_e32 v105, 31, v104
	v_cvt_pk_bf16_f32 v92, v92, v93
	v_cvt_pk_bf16_f32 v93, v94, v95
	v_cvt_pk_bf16_f32 v94, v88, v89
	v_or_b32_e32 v88, 32, v172
	global_store_dwordx4 v[44:45], v[28:31], off offset:256
	v_cvt_pk_bf16_f32 v111, v106, v107
	v_lshlrev_b64 v[104:105], 11, v[104:105]
	v_add_co_u32_e32 v30, vcc, s75, v170
	v_ashrrev_i32_e32 v89, 31, v88
	v_cvt_pk_bf16_f32 v76, v76, v77
	v_cvt_pk_bf16_f32 v77, v78, v79
	v_cvt_pk_bf16_f32 v78, v72, v73
	v_or_b32_e32 v72, 48, v172
	v_lshl_add_u64 v[28:29], v[170:171], 0, s[14:15]
	v_addc_co_u32_e32 v31, vcc, 0, v171, vcc
	v_cvt_pk_bf16_f32 v12, v12, v13
	v_cvt_pk_bf16_f32 v13, v14, v15
	v_cvt_pk_bf16_f32 v14, v8, v9
	v_cvt_pk_bf16_f32 v15, v10, v11
	global_store_dwordx4 v[170:171], v[108:111], off offset:256
	v_cvt_pk_bf16_f32 v95, v90, v91
	v_lshlrev_b64 v[88:89], 11, v[88:89]
	v_lshl_add_u64 v[108:109], v[168:169], 0, v[104:105]
	v_ashrrev_i32_e32 v73, 31, v72
	global_store_dwordx4 v[28:29], v[12:15], off offset:256
	global_store_dwordx4 v[108:109], v[92:95], off offset:256
	v_cvt_pk_bf16_f32 v79, v74, v75
	v_add_co_u32_e32 v14, vcc, s76, v170
	v_lshl_add_u64 v[92:93], v[168:169], 0, v[88:89]
	v_lshlrev_b64 v[72:73], 11, v[72:73]
	v_addc_co_u32_e32 v15, vcc, 0, v171, vcc
	v_cvt_pk_bf16_f32 v124, v124, v125
	v_cvt_pk_bf16_f32 v125, v126, v127
	v_cvt_pk_bf16_f32 v126, v120, v121
	v_cvt_pk_bf16_f32 v127, v122, v123
	v_cvt_pk_bf16_f32 v104, v116, v117
	v_cvt_pk_bf16_f32 v105, v118, v119
	v_cvt_pk_bf16_f32 v106, v112, v113
	v_cvt_pk_bf16_f32 v107, v114, v115
	v_cvt_pk_bf16_f32 v88, v100, v101
	v_cvt_pk_bf16_f32 v89, v102, v103
	v_cvt_pk_bf16_f32 v90, v96, v97
	v_cvt_pk_bf16_f32 v91, v98, v99
	global_store_dwordx4 v[92:93], v[76:79], off offset:256
	v_cvt_pk_bf16_f32 v74, v80, v81
	v_cvt_pk_bf16_f32 v75, v82, v83
	v_lshl_add_u64 v[76:77], v[168:169], 0, v[72:73]
	v_cvt_pk_bf16_f32 v72, v84, v85
	v_cvt_pk_bf16_f32 v73, v86, v87
	v_cvt_pk_bf16_f32 v71, v66, v67
	v_cvt_pk_bf16_f32 v63, v58, v59
	v_cvt_pk_bf16_f32 v40, v52, v53
	v_cvt_pk_bf16_f32 v41, v54, v55
	v_cvt_pk_bf16_f32 v42, v48, v49
	v_cvt_pk_bf16_f32 v43, v50, v51
	v_cvt_pk_bf16_f32 v24, v36, v37
	v_cvt_pk_bf16_f32 v25, v38, v39
	v_cvt_pk_bf16_f32 v26, v32, v33
	v_cvt_pk_bf16_f32 v27, v34, v35
	v_lshl_add_u64 v[12:13], v[170:171], 0, s[16:17]
	v_cvt_pk_bf16_f32 v8, v20, v21
	v_cvt_pk_bf16_f32 v9, v22, v23
	v_cvt_pk_bf16_f32 v10, v16, v17
	v_cvt_pk_bf16_f32 v11, v18, v19
	v_cvt_pk_bf16_f32 v4, v4, v5
	v_cvt_pk_bf16_f32 v5, v6, v7
	v_cvt_pk_bf16_f32 v6, v0, v1
	v_cvt_pk_bf16_f32 v7, v2, v3
	s_and_b64 vcc, exec, s[8:9]
	s_mov_b32 s18, s20
	s_mov_b32 s77, s44
	s_mov_b32 s22, s24
	s_mov_b64 s[50:51], s[48:49]
	s_mov_b64 s[52:53], s[46:47]
	global_store_dwordx4 v[170:171], v[124:127], off
	global_store_dwordx4 v[108:109], v[104:107], off
	global_store_dwordx4 v[92:93], v[88:91], off
	global_store_dwordx4 v[76:77], v[72:75], off
	global_store_dwordx4 v[76:77], v[68:71], off offset:256
	global_store_dwordx4 v[56:57], v[60:63], off
	global_store_dwordx4 v[46:47], v[40:43], off
	global_store_dwordx4 v[30:31], v[24:27], off
	global_store_dwordx4 v[14:15], v[8:11], off
	global_store_dwordx4 v[12:13], v[4:7], off offset:256
	s_cbranch_vccz .LBB0_831
	s_waitcnt vmcnt(0)
	s_cmpk_gt_u32 s3, 0xff
	s_cbranch_scc1 .LBB0_838
	s_barrier

.LBB0_898:
	ds_read_b128 v[136:139], v151
	ds_read_b128 v[168:171], v151 offset:1024
	ds_read_b128 v[172:175], v151 offset:2048
	ds_read_b128 v[176:179], v151 offset:3072
	s_add_u32 s28, s46, 0xfffc0080
	s_addc_u32 s29, s47, -1
	s_cmp_eq_u32 s74, 12
	s_cselect_b32 s51, s19, s29
	s_cselect_b32 s50, s21, s28
	s_cselect_b32 s49, s23, s73
	s_cselect_b32 s48, s27, s72
	v_lshl_add_u64 v[140:141], s[46:47], 0, v[128:129]
	s_add_i32 m0, s45, 0xc000
	ds_read_b128 v[194:197], v153
	ds_read_b128 v[198:201], v153 offset:1024
	ds_read_b128 v[202:205], v153 offset:2048
	ds_read_b128 v[206:209], v153 offset:3072
	ds_read_b128 v[210:213], v153 offset:4096
	ds_read_b128 v[214:217], v153 offset:5120
	ds_read_b128 v[218:221], v153 offset:6144
	ds_read_b128 v[222:225], v153 offset:7168
	global_load_lds_dwordx4 v[140:141], off
	v_lshl_add_u64 v[140:141], s[46:47], 0, v[130:131]
	s_add_i32 m0, s45, 0xe000
	s_nop 0
	global_load_lds_dwordx4 v[140:141], off
	s_waitcnt lgkmcnt(8)
	s_barrier
	s_nop 0
	s_setprio 1
	s_waitcnt lgkmcnt(7)
	v_mfma_f32_16x16x32_bf16 v[124:127], v[136:139], v[194:197], v[124:127]
	v_mfma_f32_16x16x32_bf16 v[120:123], v[172:175], v[194:197], v[120:123]
	s_waitcnt lgkmcnt(5)
	v_mfma_f32_16x16x32_bf16 v[108:111], v[136:139], v[202:205], v[108:111]
	v_mfma_f32_16x16x32_bf16 v[104:107], v[172:175], v[202:205], v[104:107]
	s_waitcnt lgkmcnt(3)
	v_mfma_f32_16x16x32_bf16 v[92:95], v[136:139], v[210:213], v[92:95]
	v_mfma_f32_16x16x32_bf16 v[88:91], v[172:175], v[210:213], v[88:91]
	s_waitcnt lgkmcnt(1)
	v_mfma_f32_16x16x32_bf16 v[76:79], v[136:139], v[218:221], v[76:79]
	v_mfma_f32_16x16x32_bf16 v[72:75], v[172:175], v[218:221], v[72:75]
	v_mfma_f32_16x16x32_bf16 v[124:127], v[168:171], v[198:201], v[124:127]
	v_mfma_f32_16x16x32_bf16 v[120:123], v[176:179], v[198:201], v[120:123]
	v_mfma_f32_16x16x32_bf16 v[108:111], v[168:171], v[206:209], v[108:111]
	v_mfma_f32_16x16x32_bf16 v[104:107], v[176:179], v[206:209], v[104:107]
	v_mfma_f32_16x16x32_bf16 v[92:95], v[168:171], v[214:217], v[92:95]
	v_mfma_f32_16x16x32_bf16 v[88:91], v[176:179], v[214:217], v[88:91]
	s_waitcnt lgkmcnt(0)
	v_mfma_f32_16x16x32_bf16 v[76:79], v[168:171], v[222:225], v[76:79]
	v_mfma_f32_16x16x32_bf16 v[72:75], v[176:179], v[222:225], v[72:75]
	s_setprio 0
	s_barrier
	s_add_i32 s28, s70, s53
	v_lshl_add_u64 v[140:141], s[48:49], 0, v[158:159]
	s_mov_b32 m0, s28
	ds_read_b128 v[226:229], v155
	ds_read_b128 v[230:233], v155 offset:1024
	ds_read_b128 v[234:237], v155 offset:2048
	ds_read_b128 v[238:241], v155 offset:3072
	global_load_lds_dwordx4 v[140:141], off
	v_lshl_add_u64 v[242:243], s[48:49], 0, v[162:163]
	s_add_i32 m0, s28, 0x2000
	s_nop 0
	global_load_lds_dwordx4 v[242:243], off
	s_barrier
	s_nop 0
	s_setprio 1
	s_waitcnt lgkmcnt(3)
	v_mfma_f32_16x16x32_bf16 v[116:119], v[226:229], v[194:197], v[116:119]
	s_waitcnt lgkmcnt(1)
	v_mfma_f32_16x16x32_bf16 v[112:115], v[234:237], v[194:197], v[112:115]
	v_mfma_f32_16x16x32_bf16 v[100:103], v[226:229], v[202:205], v[100:103]
	v_mfma_f32_16x16x32_bf16 v[96:99], v[234:237], v[202:205], v[96:99]
	v_mfma_f32_16x16x32_bf16 v[84:87], v[226:229], v[210:213], v[84:87]
	v_mfma_f32_16x16x32_bf16 v[80:83], v[234:237], v[210:213], v[80:83]
	v_mfma_f32_16x16x32_bf16 v[68:71], v[226:229], v[218:221], v[68:71]
	v_mfma_f32_16x16x32_bf16 v[64:67], v[234:237], v[218:221], v[64:67]
	v_mfma_f32_16x16x32_bf16 v[116:119], v[230:233], v[198:201], v[116:119]
	s_waitcnt lgkmcnt(0)
	v_mfma_f32_16x16x32_bf16 v[112:115], v[238:241], v[198:201], v[112:115]
	v_mfma_f32_16x16x32_bf16 v[100:103], v[230:233], v[206:209], v[100:103]
	v_mfma_f32_16x16x32_bf16 v[96:99], v[238:241], v[206:209], v[96:99]
	v_mfma_f32_16x16x32_bf16 v[84:87], v[230:233], v[214:217], v[84:87]
	v_mfma_f32_16x16x32_bf16 v[80:83], v[238:241], v[214:217], v[80:83]
	v_mfma_f32_16x16x32_bf16 v[68:71], v[230:233], v[222:225], v[68:71]
	v_mfma_f32_16x16x32_bf16 v[64:67], v[238:241], v[222:225], v[64:67]
	s_setprio 0
	s_mov_b32 m0, s45
	v_lshl_add_u64 v[244:245], s[50:51], 0, v[156:157]
	s_barrier
	ds_read_b128 v[194:197], v153 offset:16384
	ds_read_b128 v[198:201], v153 offset:17408
	ds_read_b128 v[202:205], v153 offset:18432
	ds_read_b128 v[206:209], v153 offset:19456
	ds_read_b128 v[210:213], v153 offset:20480
	ds_read_b128 v[214:217], v153 offset:21504
	ds_read_b128 v[218:221], v153 offset:22528
	ds_read_b128 v[222:225], v153 offset:23552
	global_load_lds_dwordx4 v[244:245], off
	v_lshl_add_u64 v[246:247], s[50:51], 0, v[160:161]
	s_mov_b32 m0, s4
	s_nop 0
	global_load_lds_dwordx4 v[246:247], off
	s_barrier
	s_nop 0
	s_setprio 1
	s_waitcnt lgkmcnt(7)
	v_mfma_f32_16x16x32_bf16 v[60:63], v[136:139], v[194:197], v[60:63]
	v_mfma_f32_16x16x32_bf16 v[56:59], v[172:175], v[194:197], v[56:59]
	s_waitcnt lgkmcnt(5)
	v_mfma_f32_16x16x32_bf16 v[44:47], v[136:139], v[202:205], v[44:47]
	v_mfma_f32_16x16x32_bf16 v[40:43], v[172:175], v[202:205], v[40:43]
	s_waitcnt lgkmcnt(3)
	v_mfma_f32_16x16x32_bf16 v[28:31], v[136:139], v[210:213], v[28:31]
	v_mfma_f32_16x16x32_bf16 v[24:27], v[172:175], v[210:213], v[24:27]
	s_waitcnt lgkmcnt(1)
	v_mfma_f32_16x16x32_bf16 v[12:15], v[136:139], v[218:221], v[12:15]
	v_mfma_f32_16x16x32_bf16 v[8:11], v[172:175], v[218:221], v[8:11]
	v_mfma_f32_16x16x32_bf16 v[60:63], v[168:171], v[198:201], v[60:63]
	v_mfma_f32_16x16x32_bf16 v[56:59], v[176:179], v[198:201], v[56:59]
	v_mfma_f32_16x16x32_bf16 v[44:47], v[168:171], v[206:209], v[44:47]
	v_mfma_f32_16x16x32_bf16 v[40:43], v[176:179], v[206:209], v[40:43]
	v_mfma_f32_16x16x32_bf16 v[28:31], v[168:171], v[214:217], v[28:31]
	v_mfma_f32_16x16x32_bf16 v[24:27], v[176:179], v[214:217], v[24:27]
	s_waitcnt lgkmcnt(0)
	v_mfma_f32_16x16x32_bf16 v[12:15], v[168:171], v[222:225], v[12:15]
	v_mfma_f32_16x16x32_bf16 v[8:11], v[176:179], v[222:225], v[8:11]
	s_setprio 0
	s_barrier
	s_add_u32 s28, s48, 0x40000
	s_addc_u32 s29, s49, 0
	s_add_i32 s75, s71, s53
	v_lshl_add_u64 v[136:137], s[28:29], 0, v[158:159]
	s_mov_b32 m0, s75
	s_nop 0
	global_load_lds_dwordx4 v[136:137], off
	v_lshl_add_u64 v[136:137], s[28:29], 0, v[162:163]
	s_add_i32 m0, s75, 0x2000
	s_nop 0
	global_load_lds_dwordx4 v[136:137], off
	s_waitcnt vmcnt(6)
	s_barrier
	s_setprio 1
	v_mfma_f32_16x16x32_bf16 v[52:55], v[226:229], v[194:197], v[52:55]
	v_mfma_f32_16x16x32_bf16 v[48:51], v[234:237], v[194:197], v[48:51]
	v_mfma_f32_16x16x32_bf16 v[36:39], v[226:229], v[202:205], v[36:39]
	v_mfma_f32_16x16x32_bf16 v[32:35], v[234:237], v[202:205], v[32:35]
	v_mfma_f32_16x16x32_bf16 v[20:23], v[226:229], v[210:213], v[20:23]
	v_mfma_f32_16x16x32_bf16 v[16:19], v[234:237], v[210:213], v[16:19]
	v_mfma_f32_16x16x32_bf16 v[4:7], v[226:229], v[218:221], v[4:7]
	v_mfma_f32_16x16x32_bf16 v[0:3], v[234:237], v[218:221], v[0:3]
	v_mfma_f32_16x16x32_bf16 v[52:55], v[230:233], v[198:201], v[52:55]
	v_mfma_f32_16x16x32_bf16 v[48:51], v[238:241], v[198:201], v[48:51]
	v_mfma_f32_16x16x32_bf16 v[36:39], v[230:233], v[206:209], v[36:39]
	v_mfma_f32_16x16x32_bf16 v[32:35], v[238:241], v[206:209], v[32:35]
	v_mfma_f32_16x16x32_bf16 v[20:23], v[230:233], v[214:217], v[20:23]
	v_mfma_f32_16x16x32_bf16 v[16:19], v[238:241], v[214:217], v[16:19]
	v_mfma_f32_16x16x32_bf16 v[4:7], v[230:233], v[222:225], v[4:7]
	v_mfma_f32_16x16x32_bf16 v[0:3], v[238:241], v[222:225], v[0:3]
	s_setprio 0
	s_add_i32 s75, 0, 0x18000
	v_add_u32_e32 v164, s75, v143
	s_barrier
	ds_read_b128 v[136:139], v164
	ds_read_b128 v[168:171], v164 offset:1024
	ds_read_b128 v[172:175], v164 offset:2048
	ds_read_b128 v[176:179], v164 offset:3072
	s_add_u32 s28, s50, 0x40000
	s_addc_u32 s29, s51, 0
	s_mov_b32 m0, s5
	v_lshl_add_u64 v[226:227], s[28:29], 0, v[156:157]
	ds_read_b128 v[194:197], v153 offset:32768
	ds_read_b128 v[198:201], v153 offset:33792
	ds_read_b128 v[202:205], v153 offset:34816
	ds_read_b128 v[206:209], v153 offset:35840
	ds_read_b128 v[210:213], v153 offset:36864
	ds_read_b128 v[214:217], v153 offset:37888
	ds_read_b128 v[218:221], v153 offset:38912
	ds_read_b128 v[222:225], v153 offset:39936
	global_load_lds_dwordx4 v[226:227], off
	v_lshl_add_u64 v[226:227], s[28:29], 0, v[160:161]
	s_mov_b32 m0, s55
	s_nop 0
	global_load_lds_dwordx4 v[226:227], off
	s_waitcnt lgkmcnt(8)
	s_barrier
	s_nop 0
	s_setprio 1
	s_waitcnt lgkmcnt(7)
	v_mfma_f32_16x16x32_bf16 v[124:127], v[136:139], v[194:197], v[124:127]
	v_mfma_f32_16x16x32_bf16 v[120:123], v[172:175], v[194:197], v[120:123]
	s_waitcnt lgkmcnt(5)
	v_mfma_f32_16x16x32_bf16 v[108:111], v[136:139], v[202:205], v[108:111]
	v_mfma_f32_16x16x32_bf16 v[104:107], v[172:175], v[202:205], v[104:107]
	s_waitcnt lgkmcnt(3)
	v_mfma_f32_16x16x32_bf16 v[92:95], v[136:139], v[210:213], v[92:95]
	v_mfma_f32_16x16x32_bf16 v[88:91], v[172:175], v[210:213], v[88:91]
	s_waitcnt lgkmcnt(1)
	v_mfma_f32_16x16x32_bf16 v[76:79], v[136:139], v[218:221], v[76:79]
	v_mfma_f32_16x16x32_bf16 v[72:75], v[172:175], v[218:221], v[72:75]
	v_mfma_f32_16x16x32_bf16 v[124:127], v[168:171], v[198:201], v[124:127]
	v_mfma_f32_16x16x32_bf16 v[120:123], v[176:179], v[198:201], v[120:123]
	v_mfma_f32_16x16x32_bf16 v[108:111], v[168:171], v[206:209], v[108:111]
	v_mfma_f32_16x16x32_bf16 v[104:107], v[176:179], v[206:209], v[104:107]
	v_mfma_f32_16x16x32_bf16 v[92:95], v[168:171], v[214:217], v[92:95]
	v_mfma_f32_16x16x32_bf16 v[88:91], v[176:179], v[214:217], v[88:91]
	s_waitcnt lgkmcnt(0)
	v_mfma_f32_16x16x32_bf16 v[76:79], v[168:171], v[222:225], v[76:79]
	v_mfma_f32_16x16x32_bf16 v[72:75], v[176:179], v[222:225], v[72:75]
	s_setprio 0
	s_barrier
	s_add_i32 s50, 0, 0x1c000
	s_add_i32 s28, s75, s53
	v_add_u32_e32 v164, s50, v143
	v_lshl_add_u64 v[140:141], v[140:141], 0, s[10:11]
	s_mov_b32 m0, s28
	ds_read_b128 v[226:229], v164
	ds_read_b128 v[230:233], v164 offset:1024
	ds_read_b128 v[234:237], v164 offset:2048
	ds_read_b128 v[238:241], v164 offset:3072
	global_load_lds_dwordx4 v[140:141], off
	v_lshl_add_u64 v[140:141], v[242:243], 0, s[10:11]
	s_add_i32 m0, s28, 0x2000
	s_nop 0
	global_load_lds_dwordx4 v[140:141], off
	s_barrier
	s_nop 0
	s_setprio 1
	s_waitcnt lgkmcnt(3)
	v_mfma_f32_16x16x32_bf16 v[116:119], v[226:229], v[194:197], v[116:119]
	s_waitcnt lgkmcnt(1)
	v_mfma_f32_16x16x32_bf16 v[112:115], v[234:237], v[194:197], v[112:115]
	v_mfma_f32_16x16x32_bf16 v[100:103], v[226:229], v[202:205], v[100:103]
	v_mfma_f32_16x16x32_bf16 v[96:99], v[234:237], v[202:205], v[96:99]
	v_mfma_f32_16x16x32_bf16 v[84:87], v[226:229], v[210:213], v[84:87]
	v_mfma_f32_16x16x32_bf16 v[80:83], v[234:237], v[210:213], v[80:83]
	v_mfma_f32_16x16x32_bf16 v[68:71], v[226:229], v[218:221], v[68:71]
	v_mfma_f32_16x16x32_bf16 v[64:67], v[234:237], v[218:221], v[64:67]
	v_mfma_f32_16x16x32_bf16 v[116:119], v[230:233], v[198:201], v[116:119]
	s_waitcnt lgkmcnt(0)
	v_mfma_f32_16x16x32_bf16 v[112:115], v[238:241], v[198:201], v[112:115]
	v_mfma_f32_16x16x32_bf16 v[100:103], v[230:233], v[206:209], v[100:103]
	v_mfma_f32_16x16x32_bf16 v[96:99], v[238:241], v[206:209], v[96:99]
	v_mfma_f32_16x16x32_bf16 v[84:87], v[230:233], v[214:217], v[84:87]
	v_mfma_f32_16x16x32_bf16 v[80:83], v[238:241], v[214:217], v[80:83]
	v_mfma_f32_16x16x32_bf16 v[68:71], v[230:233], v[222:225], v[68:71]
	v_mfma_f32_16x16x32_bf16 v[64:67], v[238:241], v[222:225], v[64:67]
	s_setprio 0
	s_mov_b32 m0, s6
	v_lshl_add_u64 v[140:141], v[244:245], 0, s[10:11]
	s_barrier
	ds_read_b128 v[194:197], v153 offset:49152
	ds_read_b128 v[198:201], v153 offset:50176
	ds_read_b128 v[202:205], v153 offset:51200
	ds_read_b128 v[206:209], v153 offset:52224
	ds_read_b128 v[210:213], v153 offset:53248
	ds_read_b128 v[214:217], v153 offset:54272
	ds_read_b128 v[218:221], v153 offset:55296
	ds_read_b128 v[222:225], v153 offset:56320
	global_load_lds_dwordx4 v[140:141], off
	v_lshl_add_u64 v[140:141], v[246:247], 0, s[10:11]
	s_mov_b32 m0, s7
	s_nop 0
	global_load_lds_dwordx4 v[140:141], off
	s_barrier
	s_nop 0
	s_setprio 1
	s_waitcnt lgkmcnt(7)
	v_mfma_f32_16x16x32_bf16 v[60:63], v[136:139], v[194:197], v[60:63]
	v_mfma_f32_16x16x32_bf16 v[56:59], v[172:175], v[194:197], v[56:59]
	s_waitcnt lgkmcnt(5)
	v_mfma_f32_16x16x32_bf16 v[44:47], v[136:139], v[202:205], v[44:47]
	v_mfma_f32_16x16x32_bf16 v[40:43], v[172:175], v[202:205], v[40:43]
	s_waitcnt lgkmcnt(3)
	v_mfma_f32_16x16x32_bf16 v[28:31], v[136:139], v[210:213], v[28:31]
	v_mfma_f32_16x16x32_bf16 v[24:27], v[172:175], v[210:213], v[24:27]
	s_waitcnt lgkmcnt(1)
	v_mfma_f32_16x16x32_bf16 v[12:15], v[136:139], v[218:221], v[12:15]
	v_mfma_f32_16x16x32_bf16 v[8:11], v[172:175], v[218:221], v[8:11]
	v_mfma_f32_16x16x32_bf16 v[60:63], v[168:171], v[198:201], v[60:63]
	v_mfma_f32_16x16x32_bf16 v[56:59], v[176:179], v[198:201], v[56:59]
	v_mfma_f32_16x16x32_bf16 v[44:47], v[168:171], v[206:209], v[44:47]
	v_mfma_f32_16x16x32_bf16 v[40:43], v[176:179], v[206:209], v[40:43]
	v_mfma_f32_16x16x32_bf16 v[28:31], v[168:171], v[214:217], v[28:31]
	v_mfma_f32_16x16x32_bf16 v[24:27], v[176:179], v[214:217], v[24:27]
	s_waitcnt lgkmcnt(0)
	v_mfma_f32_16x16x32_bf16 v[12:15], v[168:171], v[222:225], v[12:15]
	v_mfma_f32_16x16x32_bf16 v[8:11], v[176:179], v[222:225], v[8:11]
	s_setprio 0
	s_barrier
	s_add_u32 s28, s48, 0x40080
	s_addc_u32 s29, s49, 0
	s_add_i32 s48, s50, s53
	v_lshl_add_u64 v[136:137], s[28:29], 0, v[158:159]
	s_mov_b32 m0, s48
	s_nop 0
	global_load_lds_dwordx4 v[136:137], off
	v_lshl_add_u64 v[136:137], s[28:29], 0, v[162:163]
	s_add_i32 m0, s48, 0x2000
	s_nop 0
	global_load_lds_dwordx4 v[136:137], off
	s_waitcnt vmcnt(6)
	s_barrier
	s_setprio 1
	v_mfma_f32_16x16x32_bf16 v[52:55], v[226:229], v[194:197], v[52:55]
	v_mfma_f32_16x16x32_bf16 v[48:51], v[234:237], v[194:197], v[48:51]
	v_mfma_f32_16x16x32_bf16 v[36:39], v[226:229], v[202:205], v[36:39]
	v_mfma_f32_16x16x32_bf16 v[32:35], v[234:237], v[202:205], v[32:35]
	v_mfma_f32_16x16x32_bf16 v[20:23], v[226:229], v[210:213], v[20:23]
	v_mfma_f32_16x16x32_bf16 v[16:19], v[234:237], v[210:213], v[16:19]
	v_mfma_f32_16x16x32_bf16 v[4:7], v[226:229], v[218:221], v[4:7]
	v_mfma_f32_16x16x32_bf16 v[0:3], v[234:237], v[218:221], v[0:3]
	v_mfma_f32_16x16x32_bf16 v[52:55], v[230:233], v[198:201], v[52:55]
	v_mfma_f32_16x16x32_bf16 v[48:51], v[238:241], v[198:201], v[48:51]
	v_mfma_f32_16x16x32_bf16 v[36:39], v[230:233], v[206:209], v[36:39]
	v_mfma_f32_16x16x32_bf16 v[32:35], v[238:241], v[206:209], v[32:35]
	v_mfma_f32_16x16x32_bf16 v[20:23], v[230:233], v[214:217], v[20:23]
	v_mfma_f32_16x16x32_bf16 v[16:19], v[238:241], v[214:217], v[16:19]
	v_mfma_f32_16x16x32_bf16 v[4:7], v[230:233], v[222:225], v[4:7]
	v_mfma_f32_16x16x32_bf16 v[0:3], v[238:241], v[222:225], v[0:3]
	s_setprio 0
	s_add_i32 s74, s74, 2
	s_add_u32 s46, s46, 0x100
	s_addc_u32 s47, s47, 0
	s_add_u32 s72, s72, 0x100
	s_addc_u32 s73, s73, 0
	s_cmp_gt_u32 s74, 13
	s_barrier
	s_cbranch_scc0 .LBB0_898
	v_lshl_add_u32 v140, s44, 8, v142
	v_lshl_or_b32 v138, s26, 7, v145
	v_ashrrev_i32_e32 v141, 31, v140
	v_ashrrev_i32_e32 v139, 31, v138
	v_lshlrev_b64 v[136:137], 10, v[140:141]
	v_lshl_add_u64 v[136:137], v[136:137], 0, v[138:139]
	v_lshlrev_b64 v[136:137], 1, v[136:137]
	v_lshl_add_u64 v[168:169], s[38:39], 0, v[136:137]
	v_lshl_add_u64 v[172:173], s[40:41], 0, v[136:137]
	global_load_dwordx4 v[168:171], v[168:169], off
	v_mul_f32_e32 v124, 0xbfb8aa3b, v124
	global_load_dwordx4 v[172:175], v[172:173], off
	v_add_u32_e32 v202, 0x8000, v136
	global_load_dwordx4 v[198:201], v202, s[38:39]
	global_load_dwordx4 v[204:207], v202, s[40:41]
	v_add_u32_e32 v202, 0x10000, v136
	global_load_dwordx4 v[198:201], v202, s[38:39]
	global_load_dwordx4 v[204:207], v202, s[40:41]
	v_add_u32_e32 v202, 0x18000, v136
	global_load_dwordx4 v[198:201], v202, s[38:39]
	global_load_dwordx4 v[204:207], v202, s[40:41]
	v_add_u32_e32 v202, 0x40000, v136
	global_load_dwordx4 v[198:201], v202, s[38:39]
	global_load_dwordx4 v[204:207], v202, s[40:41]
	v_add_u32_e32 v202, 0x48000, v136
	global_load_dwordx4 v[198:201], v202, s[38:39]
	global_load_dwordx4 v[204:207], v202, s[40:41]
	v_add_u32_e32 v202, 0x50000, v136
	global_load_dwordx4 v[198:201], v202, s[38:39]
	global_load_dwordx4 v[204:207], v202, s[40:41]
	v_add_u32_e32 v202, 0x58000, v136
	global_load_dwordx4 v[198:201], v202, s[38:39]
	global_load_dwordx4 v[204:207], v202, s[40:41]
	v_mul_f32_e32 v116, 0xbfb8aa3b, v116
	v_mul_f32_e32 v112, 0xbfb8aa3b, v112
	v_mul_f32_e32 v125, 0xbfb8aa3b, v125
	v_mul_f32_e32 v117, 0xbfb8aa3b, v117
	v_mul_f32_e32 v113, 0xbfb8aa3b, v113
	v_mul_f32_e32 v120, 0xbfb8aa3b, v120
	v_mul_f32_e32 v121, 0xbfb8aa3b, v121
	v_mul_f32_e32 v118, 0xbfb8aa3b, v118
	v_mul_f32_e32 v114, 0xbfb8aa3b, v114
	v_mul_f32_e32 v119, 0xbfb8aa3b, v119
	v_exp_f32_e32 v124, v124
	v_exp_f32_e32 v116, v116
	v_exp_f32_e32 v112, v112
	v_exp_f32_e32 v125, v125
	v_exp_f32_e32 v117, v117
	v_exp_f32_e32 v113, v113
	v_exp_f32_e32 v120, v120
	v_exp_f32_e32 v121, v121
	v_exp_f32_e32 v118, v118
	v_exp_f32_e32 v114, v114
	v_exp_f32_e32 v119, v119
	v_mul_f32_e32 v126, 0xbfb8aa3b, v126
	v_mul_f32_e32 v122, 0xbfb8aa3b, v122
	v_mul_f32_e32 v123, 0xbfb8aa3b, v123
	v_mul_f32_e32 v115, 0xbfb8aa3b, v115
	v_exp_f32_e32 v126, v126
	v_exp_f32_e32 v122, v122
	v_exp_f32_e32 v141, v123
	v_exp_f32_e32 v164, v115
	v_add_f32_e32 v115, 1.0, v124
	v_add_f32_e32 v116, 1.0, v116
	v_add_f32_e32 v123, 1.0, v112
	v_add_f32_e32 v124, 1.0, v125
	v_add_f32_e32 v117, 1.0, v117
	v_add_f32_e32 v125, 1.0, v113
	v_mul_f32_e32 v127, 0xbfb8aa3b, v127
	v_add_f32_e32 v120, 1.0, v120
	v_add_f32_e32 v121, 1.0, v121
	v_add_f32_e32 v166, 1.0, v118
	v_add_f32_e32 v177, 1.0, v114
	v_add_f32_e32 v178, 1.0, v119
	v_rcp_f32_e32 v112, v115
	v_rcp_f32_e32 v114, v116
	v_rcp_f32_e32 v118, v123
	v_rcp_f32_e32 v115, v117
	v_rcp_f32_e32 v119, v125
	v_exp_f32_e32 v127, v127
	v_rcp_f32_e32 v116, v120
	v_rcp_f32_e32 v113, v124
	v_rcp_f32_e32 v117, v121
	v_add_f32_e32 v126, 1.0, v126
	v_add_f32_e32 v176, 1.0, v122
	v_rcp_f32_e32 v123, v178
	v_rcp_f32_e32 v120, v126
	v_rcp_f32_e32 v124, v176
	v_rcp_f32_e32 v126, v177
	v_add_f32_e32 v127, 1.0, v127
	v_rcp_f32_e32 v122, v166
	v_rcp_f32_e32 v121, v127
	v_mul_f32_e32 v108, 0xbfb8aa3b, v108
	v_mul_f32_e32 v100, 0xbfb8aa3b, v100
	v_mul_f32_e32 v96, 0xbfb8aa3b, v96
	v_mul_f32_e32 v109, 0xbfb8aa3b, v109
	v_mul_f32_e32 v101, 0xbfb8aa3b, v101
	v_mul_f32_e32 v97, 0xbfb8aa3b, v97
	v_mul_f32_e32 v104, 0xbfb8aa3b, v104
	v_mul_f32_e32 v105, 0xbfb8aa3b, v105
	v_exp_f32_e32 v108, v108
	v_exp_f32_e32 v100, v100
	v_exp_f32_e32 v96, v96
	v_exp_f32_e32 v109, v109
	v_exp_f32_e32 v101, v101
	v_exp_f32_e32 v97, v97
	v_exp_f32_e32 v104, v104
	v_exp_f32_e32 v105, v105
	v_mul_f32_e32 v110, 0xbfb8aa3b, v110
	v_mul_f32_e32 v102, 0xbfb8aa3b, v102
	s_waitcnt vmcnt(0)
	v_lshlrev_b32_e32 v176, 16, v168
	v_and_b32_e32 v177, 0xffff0000, v168
	v_lshlrev_b32_e32 v178, 16, v172
	v_and_b32_e32 v179, 0xffff0000, v172
	v_lshlrev_b32_e32 v196, 16, v174
	v_and_b32_e32 v197, 0xffff0000, v174
	v_lshlrev_b32_e32 v194, 16, v170
	v_and_b32_e32 v195, 0xffff0000, v170
	v_pk_mul_f32 v[114:115], v[114:115], v[178:179]
	v_pk_mul_f32 v[118:119], v[118:119], v[196:197]
	v_pk_fma_f32 v[112:113], v[112:113], v[176:177], v[114:115]
	v_pk_fma_f32 v[114:115], v[116:117], v[194:195], v[118:119]
	v_add_f32_e32 v118, 1.0, v141
	v_rcp_f32_e32 v125, v118
	v_add_f32_e32 v118, 1.0, v164
	v_rcp_f32_e32 v127, v118
	v_lshlrev_b32_e32 v172, 16, v173
	v_and_b32_e32 v173, 0xffff0000, v173
	v_lshlrev_b32_e32 v168, 16, v169
	v_and_b32_e32 v169, 0xffff0000, v169
	v_pk_mul_f32 v[122:123], v[122:123], v[172:173]
	v_lshlrev_b32_e32 v118, 16, v171
	v_pk_fma_f32 v[116:117], v[120:121], v[168:169], v[122:123]
	v_lshlrev_b32_e32 v120, 16, v175
	v_and_b32_e32 v121, 0xffff0000, v175
	v_and_b32_e32 v119, 0xffff0000, v171
	v_pk_mul_f32 v[120:121], v[126:127], v[120:121]
	v_cvt_pk_bf16_f32 v112, v112, v113
	v_pk_fma_f32 v[118:119], v[124:125], v[118:119], v[120:121]
	v_cvt_pk_bf16_f32 v113, v116, v117
	v_cvt_pk_bf16_f32 v114, v114, v115
	v_cvt_pk_bf16_f32 v115, v118, v119
	v_lshl_add_u64 v[116:117], s[58:59], 0, v[136:137]
	global_store_dwordx4 v[116:117], v[112:115], off
	v_exp_f32_e32 v110, v110
	v_exp_f32_e32 v102, v102
	v_or_b32_e32 v112, 16, v140
	v_ashrrev_i32_e32 v113, 31, v112
	v_lshlrev_b64 v[112:113], 10, v[112:113]
	v_lshl_add_u64 v[112:113], v[112:113], 0, v[138:139]
	v_lshlrev_b64 v[120:121], 1, v[112:113]
	v_lshl_add_u64 v[112:113], s[38:39], 0, v[120:121]
	v_lshl_add_u64 v[116:117], s[40:41], 0, v[120:121]
	global_load_dwordx4 v[112:115], v[112:113], off
	v_mul_f32_e32 v106, 0xbfb8aa3b, v106
	global_load_dwordx4 v[116:119], v[116:117], off
	v_add_f32_e32 v108, 1.0, v108
	v_add_f32_e32 v100, 1.0, v100
	v_add_f32_e32 v122, 1.0, v96
	v_add_f32_e32 v109, 1.0, v109
	v_add_f32_e32 v101, 1.0, v101
	v_add_f32_e32 v123, 1.0, v97
	v_mul_f32_e32 v98, 0xbfb8aa3b, v98
	v_exp_f32_e32 v106, v106
	v_add_f32_e32 v104, 1.0, v104
	v_add_f32_e32 v105, 1.0, v105
	v_rcp_f32_e32 v96, v108
	v_rcp_f32_e32 v100, v100
	v_rcp_f32_e32 v108, v122
	v_rcp_f32_e32 v97, v109
	v_rcp_f32_e32 v101, v101
	v_rcp_f32_e32 v109, v123
	v_exp_f32_e32 v98, v98
	v_rcp_f32_e32 v104, v104
	v_rcp_f32_e32 v105, v105
	v_add_f32_e32 v110, 1.0, v110
	v_add_f32_e32 v124, 1.0, v102
	v_rcp_f32_e32 v102, v110
	v_rcp_f32_e32 v110, v124
	v_mul_f32_e32 v111, 0xbfb8aa3b, v111
	v_add_f32_e32 v106, 1.0, v106
	v_mul_f32_e32 v103, 0xbfb8aa3b, v103
	v_add_f32_e32 v141, 1.0, v98
	v_rcp_f32_e32 v98, v106
	v_exp_f32_e32 v106, v103
	v_mul_f32_e32 v99, 0xbfb8aa3b, v99
	v_mul_f32_e32 v84, 0xbfb8aa3b, v84
	v_mul_f32_e32 v85, 0xbfb8aa3b, v85
	v_mul_f32_e32 v92, 0xbfb8aa3b, v92
	v_mul_f32_e32 v80, 0xbfb8aa3b, v80
	v_mul_f32_e32 v93, 0xbfb8aa3b, v93
	v_mul_f32_e32 v81, 0xbfb8aa3b, v81
	v_exp_f32_e32 v84, v84
	v_exp_f32_e32 v85, v85
	v_exp_f32_e32 v92, v92
	v_exp_f32_e32 v80, v80
	v_exp_f32_e32 v93, v93
	v_exp_f32_e32 v81, v81
	v_mul_f32_e32 v88, 0xbfb8aa3b, v88
	v_mul_f32_e32 v89, 0xbfb8aa3b, v89
	v_exp_f32_e32 v88, v88
	v_exp_f32_e32 v89, v89
	v_add_f32_e32 v84, 1.0, v84
	v_add_f32_e32 v85, 1.0, v85
	v_add_f32_e32 v92, 1.0, v92
	v_add_f32_e32 v93, 1.0, v93
	v_rcp_f32_e32 v84, v84
	v_rcp_f32_e32 v85, v85
	v_add_f32_e32 v88, 1.0, v88
	v_add_f32_e32 v89, 1.0, v89
	v_rcp_f32_e32 v88, v88
	v_rcp_f32_e32 v89, v89
	v_mul_f32_e32 v86, 0xbfb8aa3b, v86
	v_mul_f32_e32 v82, 0xbfb8aa3b, v82
	v_mul_f32_e32 v87, 0xbfb8aa3b, v87
	v_mul_f32_e32 v83, 0xbfb8aa3b, v83
	v_mul_f32_e32 v91, 0xbfb8aa3b, v91
	v_exp_f32_e32 v91, v91
	v_mul_f32_e32 v76, 0xbfb8aa3b, v76
	v_mul_f32_e32 v68, 0xbfb8aa3b, v68
	v_exp_f32_e32 v76, v76
	v_mul_f32_e32 v72, 0xbfb8aa3b, v72
	v_mul_f32_e32 v64, 0xbfb8aa3b, v64
	v_exp_f32_e32 v72, v72
	v_mul_f32_e32 v77, 0xbfb8aa3b, v77
	v_mul_f32_e32 v69, 0xbfb8aa3b, v69
	v_exp_f32_e32 v77, v77
	v_mul_f32_e32 v73, 0xbfb8aa3b, v73
	v_mul_f32_e32 v65, 0xbfb8aa3b, v65
	v_exp_f32_e32 v73, v73
	v_mul_f32_e32 v70, 0xbfb8aa3b, v70
	v_exp_f32_e32 v70, v70
	v_mul_f32_e32 v66, 0xbfb8aa3b, v66
	s_waitcnt vmcnt(0)
	v_lshlrev_b32_e32 v122, 16, v112
	v_and_b32_e32 v123, 0xffff0000, v112
	v_lshlrev_b32_e32 v124, 16, v116
	v_and_b32_e32 v125, 0xffff0000, v116
	v_lshlrev_b32_e32 v168, 16, v118
	v_and_b32_e32 v169, 0xffff0000, v118
	v_lshlrev_b32_e32 v126, 16, v114
	v_and_b32_e32 v127, 0xffff0000, v114
	v_pk_mul_f32 v[100:101], v[100:101], v[124:125]
	v_pk_mul_f32 v[108:109], v[108:109], v[168:169]
	v_pk_fma_f32 v[96:97], v[96:97], v[122:123], v[100:101]
	v_pk_fma_f32 v[100:101], v[104:105], v[126:127], v[108:109]
	v_exp_f32_e32 v105, v111
	v_rcp_f32_e32 v104, v141
	v_lshlrev_b32_e32 v108, 16, v113
	v_and_b32_e32 v109, 0xffff0000, v113
	v_add_f32_e32 v103, 1.0, v105
	v_add_f32_e32 v105, 1.0, v106
	v_rcp_f32_e32 v111, v105
	v_mul_f32_e32 v105, 0xbfb8aa3b, v107
	v_exp_f32_e32 v105, v105
	v_exp_f32_e32 v106, v99
	v_rcp_f32_e32 v103, v103
	v_lshlrev_b32_e32 v112, 16, v117
	v_add_f32_e32 v99, 1.0, v105
	v_add_f32_e32 v105, 1.0, v106
	v_rcp_f32_e32 v105, v105
	v_and_b32_e32 v113, 0xffff0000, v117
	v_rcp_f32_e32 v99, v99
	v_pk_mul_f32 v[110:111], v[110:111], v[112:113]
	v_lshlrev_b32_e32 v106, 16, v115
	v_pk_fma_f32 v[102:103], v[102:103], v[108:109], v[110:111]
	v_lshlrev_b32_e32 v108, 16, v119
	v_and_b32_e32 v109, 0xffff0000, v119
	v_and_b32_e32 v107, 0xffff0000, v115
	v_pk_mul_f32 v[104:105], v[104:105], v[108:109]
	v_cvt_pk_bf16_f32 v96, v96, v97
	v_pk_fma_f32 v[104:105], v[98:99], v[106:107], v[104:105]
	v_cvt_pk_bf16_f32 v97, v102, v103
	v_cvt_pk_bf16_f32 v98, v100, v101
	v_cvt_pk_bf16_f32 v99, v104, v105
	v_lshl_add_u64 v[100:101], s[58:59], 0, v[120:121]
	global_store_dwordx4 v[100:101], v[96:99], off
	v_add_f32_e32 v106, 1.0, v80
	v_add_f32_e32 v107, 1.0, v81
	v_or_b32_e32 v96, 32, v140
	v_ashrrev_i32_e32 v97, 31, v96
	v_lshlrev_b64 v[96:97], 10, v[96:97]
	v_lshl_add_u64 v[96:97], v[96:97], 0, v[138:139]
	v_lshlrev_b64 v[104:105], 1, v[96:97]
	v_lshl_add_u64 v[96:97], s[38:39], 0, v[104:105]
	v_lshl_add_u64 v[100:101], s[40:41], 0, v[104:105]
	global_load_dwordx4 v[96:99], v[96:97], off
	v_rcp_f32_e32 v80, v92
	global_load_dwordx4 v[100:103], v[100:101], off
	v_rcp_f32_e32 v92, v106
	v_rcp_f32_e32 v81, v93
	v_rcp_f32_e32 v93, v107
	v_mul_f32_e32 v71, 0xbfb8aa3b, v71
	v_exp_f32_e32 v71, v71
	v_mul_f32_e32 v78, 0xbfb8aa3b, v78
	v_exp_f32_e32 v78, v78
	v_mul_f32_e32 v75, 0xbfb8aa3b, v75
	v_add_f32_e32 v71, 1.0, v71
	v_rcp_f32_e32 v71, v71
	v_exp_f32_e32 v75, v75
	v_mul_f32_e32 v67, 0xbfb8aa3b, v67
	v_mul_f32_e32 v60, 0xbfb8aa3b, v60
	v_mul_f32_e32 v52, 0xbfb8aa3b, v52
	v_exp_f32_e32 v60, v60
	v_mul_f32_e32 v56, 0xbfb8aa3b, v56
	v_mul_f32_e32 v48, 0xbfb8aa3b, v48
	v_exp_f32_e32 v56, v56
	v_mul_f32_e32 v61, 0xbfb8aa3b, v61
	v_mul_f32_e32 v53, 0xbfb8aa3b, v53
	v_exp_f32_e32 v61, v61
	v_mul_f32_e32 v57, 0xbfb8aa3b, v57
	v_mul_f32_e32 v49, 0xbfb8aa3b, v49
	v_exp_f32_e32 v57, v57
	v_mul_f32_e32 v54, 0xbfb8aa3b, v54
	v_exp_f32_e32 v54, v54
	v_mul_f32_e32 v50, 0xbfb8aa3b, v50
	v_mul_f32_e32 v55, 0xbfb8aa3b, v55
	v_exp_f32_e32 v55, v55
	v_mul_f32_e32 v62, 0xbfb8aa3b, v62
	v_exp_f32_e32 v62, v62
	v_mul_f32_e32 v59, 0xbfb8aa3b, v59
	v_add_f32_e32 v55, 1.0, v55
	v_rcp_f32_e32 v55, v55
	v_exp_f32_e32 v59, v59
	v_mul_f32_e32 v51, 0xbfb8aa3b, v51
	v_mul_f32_e32 v44, 0xbfb8aa3b, v44
	v_mul_f32_e32 v36, 0xbfb8aa3b, v36
	v_exp_f32_e32 v44, v44
	v_mul_f32_e32 v40, 0xbfb8aa3b, v40
	v_mul_f32_e32 v32, 0xbfb8aa3b, v32
	v_exp_f32_e32 v40, v40
	v_mul_f32_e32 v45, 0xbfb8aa3b, v45
	v_mul_f32_e32 v37, 0xbfb8aa3b, v37
	v_exp_f32_e32 v45, v45
	v_mul_f32_e32 v41, 0xbfb8aa3b, v41
	v_mul_f32_e32 v33, 0xbfb8aa3b, v33
	v_exp_f32_e32 v41, v41
	v_mul_f32_e32 v38, 0xbfb8aa3b, v38
	v_exp_f32_e32 v38, v38
	v_mul_f32_e32 v34, 0xbfb8aa3b, v34
	v_mul_f32_e32 v39, 0xbfb8aa3b, v39
	v_exp_f32_e32 v39, v39
	v_mul_f32_e32 v46, 0xbfb8aa3b, v46
	v_exp_f32_e32 v46, v46
	v_mul_f32_e32 v43, 0xbfb8aa3b, v43
	v_add_f32_e32 v39, 1.0, v39
	v_rcp_f32_e32 v39, v39
	v_exp_f32_e32 v43, v43
	v_mul_f32_e32 v35, 0xbfb8aa3b, v35
	v_mul_f32_e32 v28, 0xbfb8aa3b, v28
	v_mul_f32_e32 v20, 0xbfb8aa3b, v20
	v_exp_f32_e32 v28, v28
	v_mul_f32_e32 v24, 0xbfb8aa3b, v24
	v_mul_f32_e32 v16, 0xbfb8aa3b, v16
	v_exp_f32_e32 v24, v24
	v_mul_f32_e32 v29, 0xbfb8aa3b, v29
	v_mul_f32_e32 v21, 0xbfb8aa3b, v21
	v_exp_f32_e32 v29, v29
	v_mul_f32_e32 v25, 0xbfb8aa3b, v25
	v_mul_f32_e32 v17, 0xbfb8aa3b, v17
	v_exp_f32_e32 v25, v25
	v_mul_f32_e32 v22, 0xbfb8aa3b, v22
	v_exp_f32_e32 v22, v22
	v_mul_f32_e32 v18, 0xbfb8aa3b, v18
	v_mul_f32_e32 v23, 0xbfb8aa3b, v23
	v_exp_f32_e32 v23, v23
	s_waitcnt vmcnt(0)
	v_lshlrev_b32_e32 v106, 16, v96
	v_and_b32_e32 v107, 0xffff0000, v96
	v_lshlrev_b32_e32 v108, 16, v100
	v_and_b32_e32 v109, 0xffff0000, v100
	v_lshlrev_b32_e32 v112, 16, v102
	v_and_b32_e32 v113, 0xffff0000, v102
	v_pk_mul_f32 v[84:85], v[84:85], v[108:109]
	v_lshlrev_b32_e32 v110, 16, v98
	v_pk_fma_f32 v[80:81], v[80:81], v[106:107], v[84:85]
	v_pk_mul_f32 v[84:85], v[92:93], v[112:113]
	v_exp_f32_e32 v93, v86
	v_and_b32_e32 v111, 0xffff0000, v98
	v_pk_fma_f32 v[84:85], v[88:89], v[110:111], v[84:85]
	v_mul_f32_e32 v89, 0xbfb8aa3b, v90
	v_mul_f32_e32 v92, 0xbfb8aa3b, v94
	v_exp_f32_e32 v89, v89
	v_exp_f32_e32 v90, v82
	v_exp_f32_e32 v92, v92
	v_add_f32_e32 v88, 1.0, v93
	v_exp_f32_e32 v93, v87
	v_add_f32_e32 v82, 1.0, v89
	v_add_f32_e32 v89, 1.0, v90
	v_mul_f32_e32 v90, 0xbfb8aa3b, v95
	v_add_f32_e32 v86, 1.0, v92
	v_exp_f32_e32 v92, v90
	v_rcp_f32_e32 v90, v89
	v_add_f32_e32 v89, 1.0, v93
	v_rcp_f32_e32 v88, v88
	v_rcp_f32_e32 v89, v89
	v_add_f32_e32 v87, 1.0, v92
	v_lshlrev_b32_e32 v94, 16, v101
	v_and_b32_e32 v95, 0xffff0000, v101
	v_rcp_f32_e32 v86, v86
	v_rcp_f32_e32 v87, v87
	v_pk_mul_f32 v[88:89], v[88:89], v[94:95]
	v_exp_f32_e32 v94, v83
	v_lshlrev_b32_e32 v92, 16, v97
	v_and_b32_e32 v93, 0xffff0000, v97
	v_pk_fma_f32 v[86:87], v[86:87], v[92:93], v[88:89]
	v_add_f32_e32 v88, 1.0, v94
	v_add_f32_e32 v83, 1.0, v91
	v_rcp_f32_e32 v91, v88
	v_rcp_f32_e32 v82, v82
	v_rcp_f32_e32 v83, v83
	v_lshlrev_b32_e32 v92, 16, v103
	v_and_b32_e32 v93, 0xffff0000, v103
	v_lshlrev_b32_e32 v88, 16, v99
	v_and_b32_e32 v89, 0xffff0000, v99
	v_pk_mul_f32 v[90:91], v[90:91], v[92:93]
	v_cvt_pk_bf16_f32 v80, v80, v81
	v_pk_fma_f32 v[88:89], v[82:83], v[88:89], v[90:91]
	v_cvt_pk_bf16_f32 v81, v86, v87
	v_cvt_pk_bf16_f32 v82, v84, v85
	v_cvt_pk_bf16_f32 v83, v88, v89
	v_lshl_add_u64 v[84:85], s[58:59], 0, v[104:105]
	global_store_dwordx4 v[84:85], v[80:83], off
	v_exp_f32_e32 v90, v68
	v_add_f32_e32 v68, 1.0, v76
	v_or_b32_e32 v80, 48, v140
	v_ashrrev_i32_e32 v81, 31, v80
	v_lshlrev_b64 v[80:81], 10, v[80:81]
	v_lshl_add_u64 v[80:81], v[80:81], 0, v[138:139]
	v_lshlrev_b64 v[88:89], 1, v[80:81]
	v_lshl_add_u64 v[80:81], s[38:39], 0, v[88:89]
	global_load_dwordx4 v[80:83], v[80:81], off
	v_lshl_add_u64 v[84:85], s[40:41], 0, v[88:89]
	global_load_dwordx4 v[84:87], v[84:85], off
	v_add_f32_e32 v76, 1.0, v90
	v_exp_f32_e32 v90, v64
	v_add_f32_e32 v64, 1.0, v72
	v_rcp_f32_e32 v76, v76
	v_rcp_f32_e32 v68, v68
	v_add_f32_e32 v72, 1.0, v90
	v_exp_f32_e32 v90, v69
	v_add_f32_e32 v69, 1.0, v77
	v_rcp_f32_e32 v69, v69
	v_rcp_f32_e32 v72, v72
	v_add_f32_e32 v77, 1.0, v90
	v_rcp_f32_e32 v77, v77
	v_rcp_f32_e32 v64, v64
	v_mul_f32_e32 v30, 0xbfb8aa3b, v30
	v_exp_f32_e32 v30, v30
	v_add_f32_e32 v23, 1.0, v23
	v_rcp_f32_e32 v23, v23
	v_mul_f32_e32 v27, 0xbfb8aa3b, v27
	v_exp_f32_e32 v27, v27
	v_mul_f32_e32 v19, 0xbfb8aa3b, v19
	v_mul_f32_e32 v12, 0xbfb8aa3b, v12
	v_mul_f32_e32 v4, 0xbfb8aa3b, v4
	v_exp_f32_e32 v12, v12
	v_mul_f32_e32 v8, 0xbfb8aa3b, v8
	v_mul_f32_e32 v0, 0xbfb8aa3b, v0
	v_exp_f32_e32 v8, v8
	v_mul_f32_e32 v13, 0xbfb8aa3b, v13
	v_mul_f32_e32 v5, 0xbfb8aa3b, v5
	v_exp_f32_e32 v13, v13
	v_mul_f32_e32 v9, 0xbfb8aa3b, v9
	v_mul_f32_e32 v1, 0xbfb8aa3b, v1
	v_exp_f32_e32 v9, v9
	v_mul_f32_e32 v6, 0xbfb8aa3b, v6
	v_exp_f32_e32 v6, v6
	v_mul_f32_e32 v2, 0xbfb8aa3b, v2
	v_mul_f32_e32 v7, 0xbfb8aa3b, v7
	v_exp_f32_e32 v7, v7
	v_mul_f32_e32 v14, 0xbfb8aa3b, v14
	v_exp_f32_e32 v14, v14
	v_mul_f32_e32 v11, 0xbfb8aa3b, v11
	v_add_f32_e32 v7, 1.0, v7
	v_rcp_f32_e32 v7, v7
	v_exp_f32_e32 v11, v11
	v_mul_f32_e32 v3, 0xbfb8aa3b, v3
	s_and_b64 vcc, exec, s[8:9]
	s_mov_b32 s26, s22
	s_mov_b32 s44, s20
	s_mov_b64 s[48:49], s[42:43]
	s_mov_b64 s[46:47], s[24:25]
	s_waitcnt vmcnt(0)
	v_lshlrev_b32_e32 v90, 16, v80
	v_and_b32_e32 v91, 0xffff0000, v80
	v_exp_f32_e32 v80, v65
	v_add_f32_e32 v65, 1.0, v73
	v_lshlrev_b32_e32 v92, 16, v84
	v_and_b32_e32 v93, 0xffff0000, v84
	v_add_f32_e32 v73, 1.0, v80
	v_rcp_f32_e32 v73, v73
	v_rcp_f32_e32 v65, v65
	v_pk_mul_f32 v[76:77], v[76:77], v[92:93]
	s_nop 0
	v_pk_fma_f32 v[68:69], v[68:69], v[90:91], v[76:77]
	v_lshlrev_b32_e32 v90, 16, v86
	v_and_b32_e32 v91, 0xffff0000, v86
	v_lshlrev_b32_e32 v76, 16, v82
	v_and_b32_e32 v77, 0xffff0000, v82
	v_pk_mul_f32 v[72:73], v[72:73], v[90:91]
	s_nop 0
	v_pk_fma_f32 v[72:73], v[64:65], v[76:77], v[72:73]
	v_add_f32_e32 v65, 1.0, v70
	v_mul_f32_e32 v70, 0xbfb8aa3b, v74
	v_exp_f32_e32 v74, v70
	v_exp_f32_e32 v76, v66
	v_rcp_f32_e32 v70, v65
	v_add_f32_e32 v64, 1.0, v78
	v_add_f32_e32 v65, 1.0, v74
	v_mul_f32_e32 v74, 0xbfb8aa3b, v79
	v_rcp_f32_e32 v66, v65
	v_add_f32_e32 v65, 1.0, v76
	v_exp_f32_e32 v76, v74
	v_rcp_f32_e32 v74, v65
	v_rcp_f32_e32 v64, v64
	v_lshlrev_b32_e32 v78, 16, v85
	v_add_f32_e32 v65, 1.0, v76
	v_rcp_f32_e32 v65, v65
	v_and_b32_e32 v79, 0xffff0000, v85
	v_pk_mul_f32 v[70:71], v[70:71], v[78:79]
	v_exp_f32_e32 v78, v67
	v_lshlrev_b32_e32 v76, 16, v81
	v_and_b32_e32 v77, 0xffff0000, v81
	v_pk_fma_f32 v[70:71], v[64:65], v[76:77], v[70:71]
	v_add_f32_e32 v64, 1.0, v75
	v_rcp_f32_e32 v67, v64
	v_add_f32_e32 v64, 1.0, v78
	v_rcp_f32_e32 v75, v64
	v_lshlrev_b32_e32 v76, 16, v87
	v_and_b32_e32 v77, 0xffff0000, v87
	v_lshlrev_b32_e32 v64, 16, v83
	v_and_b32_e32 v65, 0xffff0000, v83
	v_pk_mul_f32 v[74:75], v[74:75], v[76:77]
	s_nop 0
	v_pk_fma_f32 v[74:75], v[66:67], v[64:65], v[74:75]
	v_cvt_pk_bf16_f32 v64, v68, v69
	v_cvt_pk_bf16_f32 v65, v70, v71
	v_cvt_pk_bf16_f32 v66, v72, v73
	v_cvt_pk_bf16_f32 v67, v74, v75
	v_lshl_add_u64 v[68:69], s[58:59], 0, v[88:89]
	v_lshl_add_u64 v[72:73], v[136:137], 0, s[0:1]
	global_store_dwordx4 v[68:69], v[64:67], off
	v_lshl_add_u64 v[68:69], s[40:41], 0, v[72:73]
	global_load_dwordx4 v[68:71], v[68:69], off
	v_lshl_add_u64 v[64:65], s[38:39], 0, v[72:73]
	global_load_dwordx4 v[64:67], v[64:65], off
	v_exp_f32_e32 v74, v52
	v_add_f32_e32 v52, 1.0, v60
	v_rcp_f32_e32 v52, v52
	v_add_f32_e32 v60, 1.0, v74
	v_exp_f32_e32 v74, v48
	v_add_f32_e32 v48, 1.0, v56
	v_rcp_f32_e32 v60, v60
	v_rcp_f32_e32 v48, v48
	v_add_f32_e32 v56, 1.0, v74
	v_exp_f32_e32 v74, v53
	v_add_f32_e32 v53, 1.0, v61
	v_rcp_f32_e32 v53, v53
	v_rcp_f32_e32 v56, v56
	v_add_f32_e32 v61, 1.0, v74
	v_rcp_f32_e32 v61, v61
	s_waitcnt vmcnt(0)
	v_lshlrev_b32_e32 v76, 16, v68
	v_and_b32_e32 v77, 0xffff0000, v68
	v_lshlrev_b32_e32 v74, 16, v64
	v_and_b32_e32 v75, 0xffff0000, v64
	v_exp_f32_e32 v64, v49
	v_add_f32_e32 v49, 1.0, v57
	v_rcp_f32_e32 v49, v49
	v_pk_mul_f32 v[60:61], v[60:61], v[76:77]
	v_add_f32_e32 v57, 1.0, v64
	v_rcp_f32_e32 v57, v57
	v_pk_fma_f32 v[52:53], v[52:53], v[74:75], v[60:61]
	v_lshlrev_b32_e32 v74, 16, v70
	v_and_b32_e32 v75, 0xffff0000, v70
	v_lshlrev_b32_e32 v60, 16, v66
	v_and_b32_e32 v61, 0xffff0000, v66
	v_pk_mul_f32 v[56:57], v[56:57], v[74:75]
	s_nop 0
	v_pk_fma_f32 v[56:57], v[48:49], v[60:61], v[56:57]
	v_add_f32_e32 v49, 1.0, v54
	v_mul_f32_e32 v54, 0xbfb8aa3b, v58
	v_exp_f32_e32 v58, v54
	v_exp_f32_e32 v60, v50
	v_rcp_f32_e32 v54, v49
	v_add_f32_e32 v48, 1.0, v62
	v_add_f32_e32 v49, 1.0, v58
	v_mul_f32_e32 v58, 0xbfb8aa3b, v63
	v_rcp_f32_e32 v50, v49
	v_add_f32_e32 v49, 1.0, v60
	v_exp_f32_e32 v60, v58
	v_rcp_f32_e32 v58, v49
	v_rcp_f32_e32 v48, v48
	v_lshlrev_b32_e32 v62, 16, v69
	v_add_f32_e32 v49, 1.0, v60
	v_rcp_f32_e32 v49, v49
	v_and_b32_e32 v63, 0xffff0000, v69
	v_pk_mul_f32 v[54:55], v[54:55], v[62:63]
	v_exp_f32_e32 v62, v51
	v_lshlrev_b32_e32 v60, 16, v65
	v_and_b32_e32 v61, 0xffff0000, v65
	v_pk_fma_f32 v[54:55], v[48:49], v[60:61], v[54:55]
	v_add_f32_e32 v48, 1.0, v59
	v_rcp_f32_e32 v51, v48
	v_add_f32_e32 v48, 1.0, v62
	v_rcp_f32_e32 v59, v48
	v_lshlrev_b32_e32 v60, 16, v71
	v_and_b32_e32 v61, 0xffff0000, v71
	v_lshlrev_b32_e32 v48, 16, v67
	v_and_b32_e32 v49, 0xffff0000, v67
	v_pk_mul_f32 v[58:59], v[58:59], v[60:61]
	s_nop 0
	v_pk_fma_f32 v[58:59], v[50:51], v[48:49], v[58:59]
	v_cvt_pk_bf16_f32 v48, v52, v53
	v_cvt_pk_bf16_f32 v49, v54, v55
	v_cvt_pk_bf16_f32 v50, v56, v57
	v_cvt_pk_bf16_f32 v51, v58, v59
	v_lshl_add_u64 v[52:53], s[58:59], 0, v[72:73]
	v_lshl_add_u64 v[56:57], v[136:137], 0, s[12:13]
	global_store_dwordx4 v[52:53], v[48:51], off
	v_lshl_add_u64 v[52:53], s[40:41], 0, v[56:57]
	global_load_dwordx4 v[52:55], v[52:53], off
	v_lshl_add_u64 v[48:49], s[38:39], 0, v[56:57]
	global_load_dwordx4 v[48:51], v[48:49], off
	v_exp_f32_e32 v58, v36
	v_add_f32_e32 v36, 1.0, v44
	v_rcp_f32_e32 v36, v36
	v_add_f32_e32 v44, 1.0, v58
	v_exp_f32_e32 v58, v32
	v_add_f32_e32 v32, 1.0, v40
	v_rcp_f32_e32 v44, v44
	v_rcp_f32_e32 v32, v32
	v_add_f32_e32 v40, 1.0, v58
	v_exp_f32_e32 v58, v37
	v_add_f32_e32 v37, 1.0, v45
	v_rcp_f32_e32 v37, v37
	v_rcp_f32_e32 v40, v40
	v_add_f32_e32 v45, 1.0, v58
	v_rcp_f32_e32 v45, v45
	s_waitcnt vmcnt(0)
	v_lshlrev_b32_e32 v60, 16, v52
	v_and_b32_e32 v61, 0xffff0000, v52
	v_lshlrev_b32_e32 v58, 16, v48
	v_and_b32_e32 v59, 0xffff0000, v48
	v_exp_f32_e32 v48, v33
	v_add_f32_e32 v33, 1.0, v41
	v_rcp_f32_e32 v33, v33
	v_pk_mul_f32 v[44:45], v[44:45], v[60:61]
	v_add_f32_e32 v41, 1.0, v48
	v_rcp_f32_e32 v41, v41
	v_pk_fma_f32 v[36:37], v[36:37], v[58:59], v[44:45]
	v_lshlrev_b32_e32 v58, 16, v54
	v_and_b32_e32 v59, 0xffff0000, v54
	v_lshlrev_b32_e32 v44, 16, v50
	v_and_b32_e32 v45, 0xffff0000, v50
	v_pk_mul_f32 v[40:41], v[40:41], v[58:59]
	s_nop 0
	v_pk_fma_f32 v[40:41], v[32:33], v[44:45], v[40:41]
	v_add_f32_e32 v33, 1.0, v38
	v_mul_f32_e32 v38, 0xbfb8aa3b, v42
	v_exp_f32_e32 v42, v38
	v_exp_f32_e32 v44, v34
	v_rcp_f32_e32 v38, v33
	v_add_f32_e32 v32, 1.0, v46
	v_add_f32_e32 v33, 1.0, v42
	v_mul_f32_e32 v42, 0xbfb8aa3b, v47
	v_rcp_f32_e32 v34, v33
	v_add_f32_e32 v33, 1.0, v44
	v_exp_f32_e32 v44, v42
	v_rcp_f32_e32 v42, v33
	v_rcp_f32_e32 v32, v32
	v_lshlrev_b32_e32 v46, 16, v53
	v_add_f32_e32 v33, 1.0, v44
	v_rcp_f32_e32 v33, v33
	v_and_b32_e32 v47, 0xffff0000, v53
	v_pk_mul_f32 v[38:39], v[38:39], v[46:47]
	v_exp_f32_e32 v46, v35
	v_lshlrev_b32_e32 v44, 16, v49
	v_and_b32_e32 v45, 0xffff0000, v49
	v_pk_fma_f32 v[38:39], v[32:33], v[44:45], v[38:39]
	v_add_f32_e32 v32, 1.0, v43
	v_rcp_f32_e32 v35, v32
	v_add_f32_e32 v32, 1.0, v46
	v_rcp_f32_e32 v43, v32
	v_lshlrev_b32_e32 v44, 16, v55
	v_and_b32_e32 v45, 0xffff0000, v55
	v_lshlrev_b32_e32 v32, 16, v51
	v_and_b32_e32 v33, 0xffff0000, v51
	v_pk_mul_f32 v[42:43], v[42:43], v[44:45]
	s_nop 0
	v_pk_fma_f32 v[42:43], v[34:35], v[32:33], v[42:43]
	v_cvt_pk_bf16_f32 v32, v36, v37
	v_cvt_pk_bf16_f32 v33, v38, v39
	v_cvt_pk_bf16_f32 v34, v40, v41
	v_cvt_pk_bf16_f32 v35, v42, v43
	v_lshl_add_u64 v[36:37], s[58:59], 0, v[56:57]
	v_lshl_add_u64 v[40:41], v[136:137], 0, s[14:15]
	global_store_dwordx4 v[36:37], v[32:35], off
	v_lshl_add_u64 v[36:37], s[40:41], 0, v[40:41]
	global_load_dwordx4 v[36:39], v[36:37], off
	v_lshl_add_u64 v[32:33], s[38:39], 0, v[40:41]
	global_load_dwordx4 v[32:35], v[32:33], off
	v_exp_f32_e32 v42, v20
	v_add_f32_e32 v20, 1.0, v28
	v_rcp_f32_e32 v20, v20
	v_add_f32_e32 v28, 1.0, v42
	v_exp_f32_e32 v42, v16
	v_add_f32_e32 v16, 1.0, v24
	v_rcp_f32_e32 v28, v28
	v_rcp_f32_e32 v16, v16
	v_add_f32_e32 v24, 1.0, v42
	v_exp_f32_e32 v42, v21
	v_add_f32_e32 v21, 1.0, v29
	v_rcp_f32_e32 v21, v21
	v_rcp_f32_e32 v24, v24
	v_add_f32_e32 v29, 1.0, v42
	v_rcp_f32_e32 v29, v29
	s_waitcnt vmcnt(0)
	v_lshlrev_b32_e32 v44, 16, v36
	v_and_b32_e32 v45, 0xffff0000, v36
	v_lshlrev_b32_e32 v42, 16, v32
	v_and_b32_e32 v43, 0xffff0000, v32
	v_exp_f32_e32 v32, v17
	v_add_f32_e32 v17, 1.0, v25
	v_rcp_f32_e32 v17, v17
	v_pk_mul_f32 v[28:29], v[28:29], v[44:45]
	v_add_f32_e32 v25, 1.0, v32
	v_rcp_f32_e32 v25, v25
	v_pk_fma_f32 v[20:21], v[20:21], v[42:43], v[28:29]
	v_lshlrev_b32_e32 v42, 16, v38
	v_and_b32_e32 v43, 0xffff0000, v38
	v_lshlrev_b32_e32 v28, 16, v34
	v_and_b32_e32 v29, 0xffff0000, v34
	v_pk_mul_f32 v[24:25], v[24:25], v[42:43]
	s_nop 0
	v_pk_fma_f32 v[24:25], v[16:17], v[28:29], v[24:25]
	v_add_f32_e32 v17, 1.0, v22
	v_mul_f32_e32 v22, 0xbfb8aa3b, v26
	v_exp_f32_e32 v26, v22
	v_exp_f32_e32 v28, v18
	v_rcp_f32_e32 v22, v17
	v_add_f32_e32 v16, 1.0, v30
	v_add_f32_e32 v17, 1.0, v26
	v_mul_f32_e32 v26, 0xbfb8aa3b, v31
	v_rcp_f32_e32 v18, v17
	v_add_f32_e32 v17, 1.0, v28
	v_exp_f32_e32 v28, v26
	v_rcp_f32_e32 v26, v17
	v_rcp_f32_e32 v16, v16
	v_lshlrev_b32_e32 v30, 16, v37
	v_add_f32_e32 v17, 1.0, v28
	v_rcp_f32_e32 v17, v17
	v_and_b32_e32 v31, 0xffff0000, v37
	v_pk_mul_f32 v[22:23], v[22:23], v[30:31]
	v_exp_f32_e32 v30, v19
	v_lshlrev_b32_e32 v28, 16, v33
	v_and_b32_e32 v29, 0xffff0000, v33
	v_pk_fma_f32 v[22:23], v[16:17], v[28:29], v[22:23]
	v_add_f32_e32 v16, 1.0, v27
	v_rcp_f32_e32 v19, v16
	v_add_f32_e32 v16, 1.0, v30
	v_rcp_f32_e32 v27, v16
	v_lshlrev_b32_e32 v28, 16, v39
	v_and_b32_e32 v29, 0xffff0000, v39
	v_lshlrev_b32_e32 v16, 16, v35
	v_and_b32_e32 v17, 0xffff0000, v35
	v_pk_mul_f32 v[26:27], v[26:27], v[28:29]
	s_nop 0
	v_pk_fma_f32 v[26:27], v[18:19], v[16:17], v[26:27]
	v_cvt_pk_bf16_f32 v16, v20, v21
	v_cvt_pk_bf16_f32 v17, v22, v23
	v_cvt_pk_bf16_f32 v18, v24, v25
	v_cvt_pk_bf16_f32 v19, v26, v27
	v_lshl_add_u64 v[20:21], s[58:59], 0, v[40:41]
	v_lshl_add_u64 v[24:25], v[136:137], 0, s[16:17]
	global_store_dwordx4 v[20:21], v[16:19], off
	v_lshl_add_u64 v[20:21], s[40:41], 0, v[24:25]
	global_load_dwordx4 v[20:23], v[20:21], off
	v_lshl_add_u64 v[16:17], s[38:39], 0, v[24:25]
	global_load_dwordx4 v[16:19], v[16:17], off
	v_exp_f32_e32 v26, v4
	v_add_f32_e32 v4, 1.0, v12
	v_rcp_f32_e32 v4, v4
	v_add_f32_e32 v12, 1.0, v26
	v_exp_f32_e32 v26, v0
	v_add_f32_e32 v0, 1.0, v8
	v_rcp_f32_e32 v12, v12
	v_rcp_f32_e32 v0, v0
	v_add_f32_e32 v8, 1.0, v26
	v_exp_f32_e32 v26, v5
	v_add_f32_e32 v5, 1.0, v13
	v_rcp_f32_e32 v5, v5
	v_rcp_f32_e32 v8, v8
	v_add_f32_e32 v13, 1.0, v26
	v_rcp_f32_e32 v13, v13
	s_waitcnt vmcnt(0)
	v_lshlrev_b32_e32 v28, 16, v20
	v_and_b32_e32 v29, 0xffff0000, v20
	v_lshlrev_b32_e32 v26, 16, v16
	v_and_b32_e32 v27, 0xffff0000, v16
	v_exp_f32_e32 v16, v1
	v_add_f32_e32 v1, 1.0, v9
	v_rcp_f32_e32 v1, v1
	v_pk_mul_f32 v[12:13], v[12:13], v[28:29]
	v_add_f32_e32 v9, 1.0, v16
	v_rcp_f32_e32 v9, v9
	v_pk_fma_f32 v[4:5], v[4:5], v[26:27], v[12:13]
	v_lshlrev_b32_e32 v26, 16, v22
	v_and_b32_e32 v27, 0xffff0000, v22
	v_lshlrev_b32_e32 v12, 16, v18
	v_and_b32_e32 v13, 0xffff0000, v18
	v_pk_mul_f32 v[8:9], v[8:9], v[26:27]
	s_nop 0
	v_pk_fma_f32 v[8:9], v[0:1], v[12:13], v[8:9]
	v_add_f32_e32 v1, 1.0, v6
	v_mul_f32_e32 v6, 0xbfb8aa3b, v10
	v_exp_f32_e32 v10, v6
	v_exp_f32_e32 v12, v2
	v_rcp_f32_e32 v6, v1
	v_add_f32_e32 v0, 1.0, v14
	v_add_f32_e32 v1, 1.0, v10
	v_mul_f32_e32 v10, 0xbfb8aa3b, v15
	v_rcp_f32_e32 v2, v1
	v_add_f32_e32 v1, 1.0, v12
	v_exp_f32_e32 v12, v10
	v_rcp_f32_e32 v10, v1
	v_rcp_f32_e32 v0, v0
	v_lshlrev_b32_e32 v14, 16, v21
	v_add_f32_e32 v1, 1.0, v12
	v_rcp_f32_e32 v1, v1
	v_and_b32_e32 v15, 0xffff0000, v21
	v_pk_mul_f32 v[6:7], v[6:7], v[14:15]
	v_exp_f32_e32 v14, v3
	v_lshlrev_b32_e32 v12, 16, v17
	v_and_b32_e32 v13, 0xffff0000, v17
	v_pk_fma_f32 v[6:7], v[0:1], v[12:13], v[6:7]
	v_add_f32_e32 v0, 1.0, v11
	v_rcp_f32_e32 v3, v0
	v_add_f32_e32 v0, 1.0, v14
	v_rcp_f32_e32 v11, v0
	v_lshlrev_b32_e32 v12, 16, v23
	v_and_b32_e32 v13, 0xffff0000, v23
	v_lshlrev_b32_e32 v0, 16, v19
	v_and_b32_e32 v1, 0xffff0000, v19
	v_pk_mul_f32 v[10:11], v[10:11], v[12:13]
	s_nop 0
	v_pk_fma_f32 v[10:11], v[2:3], v[0:1], v[10:11]
	v_cvt_pk_bf16_f32 v0, v4, v5
	v_cvt_pk_bf16_f32 v1, v6, v7
	v_cvt_pk_bf16_f32 v2, v8, v9
	v_cvt_pk_bf16_f32 v3, v10, v11
	v_lshl_add_u64 v[4:5], s[58:59], 0, v[24:25]
	global_store_dwordx4 v[4:5], v[0:3], off
	s_cbranch_vccz .LBB0_895
	s_waitcnt vmcnt(0)
	s_cmpk_gt_u32 s3, 0xff
	s_cbranch_scc1 .LBB0_902
	s_barrier

.LBB0_962:
	ds_read_b128 v[168:171], v139
	ds_read_b128 v[172:175], v139 offset:1024
	ds_read_b128 v[176:179], v139 offset:2048
	ds_read_b128 v[194:197], v139 offset:3072
	s_add_u32 s28, s44, 0xfffc0080
	s_addc_u32 s29, s45, -1
	s_cmp_eq_u32 s75, 12
	s_cselect_b32 s49, s21, s29
	s_cselect_b32 s48, s25, s28
	s_cselect_b32 s47, s39, s74
	s_cselect_b32 s46, s72, s73
	v_lshl_add_u64 v[142:143], s[44:45], 0, v[128:129]
	s_add_i32 m0, s19, 0xc000
	ds_read_b128 v[198:201], v140
	ds_read_b128 v[202:205], v140 offset:1024
	ds_read_b128 v[206:209], v140 offset:2048
	ds_read_b128 v[210:213], v140 offset:3072
	ds_read_b128 v[214:217], v140 offset:4096
	ds_read_b128 v[218:221], v140 offset:5120
	ds_read_b128 v[222:225], v140 offset:6144
	ds_read_b128 v[226:229], v140 offset:7168
	global_load_lds_dwordx4 v[142:143], off
	v_lshl_add_u64 v[142:143], s[44:45], 0, v[130:131]
	s_add_i32 m0, s19, 0xe000
	s_nop 0
	global_load_lds_dwordx4 v[142:143], off
	s_waitcnt lgkmcnt(8)
	s_barrier
	s_nop 0
	s_setprio 1
	s_waitcnt lgkmcnt(7)
	v_mfma_f32_16x16x32_bf16 v[124:127], v[168:171], v[198:201], v[124:127]
	v_mfma_f32_16x16x32_bf16 v[120:123], v[176:179], v[198:201], v[120:123]
	s_waitcnt lgkmcnt(5)
	v_mfma_f32_16x16x32_bf16 v[116:119], v[168:171], v[206:209], v[116:119]
	v_mfma_f32_16x16x32_bf16 v[112:115], v[176:179], v[206:209], v[112:115]
	s_waitcnt lgkmcnt(3)
	v_mfma_f32_16x16x32_bf16 v[100:103], v[168:171], v[214:217], v[100:103]
	v_mfma_f32_16x16x32_bf16 v[96:99], v[176:179], v[214:217], v[96:99]
	s_waitcnt lgkmcnt(1)
	v_mfma_f32_16x16x32_bf16 v[84:87], v[168:171], v[222:225], v[84:87]
	v_mfma_f32_16x16x32_bf16 v[80:83], v[176:179], v[222:225], v[80:83]
	v_mfma_f32_16x16x32_bf16 v[124:127], v[172:175], v[202:205], v[124:127]
	v_mfma_f32_16x16x32_bf16 v[120:123], v[194:197], v[202:205], v[120:123]
	v_mfma_f32_16x16x32_bf16 v[116:119], v[172:175], v[210:213], v[116:119]
	v_mfma_f32_16x16x32_bf16 v[112:115], v[194:197], v[210:213], v[112:115]
	v_mfma_f32_16x16x32_bf16 v[100:103], v[172:175], v[218:221], v[100:103]
	v_mfma_f32_16x16x32_bf16 v[96:99], v[194:197], v[218:221], v[96:99]
	s_waitcnt lgkmcnt(0)
	v_mfma_f32_16x16x32_bf16 v[84:87], v[172:175], v[226:229], v[84:87]
	v_mfma_f32_16x16x32_bf16 v[80:83], v[194:197], v[226:229], v[80:83]
	s_setprio 0
	s_barrier
	s_add_i32 s28, s55, s6
	v_lshl_add_u64 v[142:143], s[46:47], 0, v[158:159]
	s_mov_b32 m0, s28
	ds_read_b128 v[230:233], v141
	ds_read_b128 v[234:237], v141 offset:1024
	ds_read_b128 v[238:241], v141 offset:2048
	ds_read_b128 v[242:245], v141 offset:3072
	global_load_lds_dwordx4 v[142:143], off
	v_lshl_add_u64 v[246:247], s[46:47], 0, v[162:163]
	s_add_i32 m0, s28, 0x2000
	s_nop 0
	global_load_lds_dwordx4 v[246:247], off
	s_barrier
	s_nop 0
	s_setprio 1
	s_waitcnt lgkmcnt(3)
	v_mfma_f32_16x16x32_bf16 v[108:111], v[230:233], v[198:201], v[108:111]
	s_waitcnt lgkmcnt(1)
	v_mfma_f32_16x16x32_bf16 v[104:107], v[238:241], v[198:201], v[104:107]
	v_mfma_f32_16x16x32_bf16 v[92:95], v[230:233], v[206:209], v[92:95]
	v_mfma_f32_16x16x32_bf16 v[88:91], v[238:241], v[206:209], v[88:91]
	v_mfma_f32_16x16x32_bf16 v[76:79], v[230:233], v[214:217], v[76:79]
	v_mfma_f32_16x16x32_bf16 v[72:75], v[238:241], v[214:217], v[72:75]
	v_mfma_f32_16x16x32_bf16 v[68:71], v[230:233], v[222:225], v[68:71]
	v_mfma_f32_16x16x32_bf16 v[64:67], v[238:241], v[222:225], v[64:67]
	v_mfma_f32_16x16x32_bf16 v[108:111], v[234:237], v[202:205], v[108:111]
	s_waitcnt lgkmcnt(0)
	v_mfma_f32_16x16x32_bf16 v[104:107], v[242:245], v[202:205], v[104:107]
	v_mfma_f32_16x16x32_bf16 v[92:95], v[234:237], v[210:213], v[92:95]
	v_mfma_f32_16x16x32_bf16 v[88:91], v[242:245], v[210:213], v[88:91]
	v_mfma_f32_16x16x32_bf16 v[76:79], v[234:237], v[218:221], v[76:79]
	v_mfma_f32_16x16x32_bf16 v[72:75], v[242:245], v[218:221], v[72:75]
	v_mfma_f32_16x16x32_bf16 v[68:71], v[234:237], v[226:229], v[68:71]
	v_mfma_f32_16x16x32_bf16 v[64:67], v[242:245], v[226:229], v[64:67]
	s_setprio 0
	s_mov_b32 m0, s19
	v_lshl_add_u64 v[248:249], s[48:49], 0, v[156:157]
	s_barrier
	ds_read_b128 v[198:201], v140 offset:16384
	ds_read_b128 v[202:205], v140 offset:17408
	ds_read_b128 v[206:209], v140 offset:18432
	ds_read_b128 v[210:213], v140 offset:19456
	ds_read_b128 v[214:217], v140 offset:20480
	ds_read_b128 v[218:221], v140 offset:21504
	ds_read_b128 v[222:225], v140 offset:22528
	ds_read_b128 v[226:229], v140 offset:23552
	global_load_lds_dwordx4 v[248:249], off
	v_lshl_add_u64 v[250:251], s[48:49], 0, v[160:161]
	s_mov_b32 m0, s23
	s_nop 0
	global_load_lds_dwordx4 v[250:251], off
	s_barrier
	s_nop 0
	s_setprio 1
	s_waitcnt lgkmcnt(7)
	v_mfma_f32_16x16x32_bf16 v[60:63], v[168:171], v[198:201], v[60:63]
	v_mfma_f32_16x16x32_bf16 v[56:59], v[176:179], v[198:201], v[56:59]
	s_waitcnt lgkmcnt(5)
	v_mfma_f32_16x16x32_bf16 v[52:55], v[168:171], v[206:209], v[52:55]
	v_mfma_f32_16x16x32_bf16 v[48:51], v[176:179], v[206:209], v[48:51]
	s_waitcnt lgkmcnt(3)
	v_mfma_f32_16x16x32_bf16 v[36:39], v[168:171], v[214:217], v[36:39]
	v_mfma_f32_16x16x32_bf16 v[32:35], v[176:179], v[214:217], v[32:35]
	s_waitcnt lgkmcnt(1)
	v_mfma_f32_16x16x32_bf16 v[20:23], v[168:171], v[222:225], v[20:23]
	v_mfma_f32_16x16x32_bf16 v[16:19], v[176:179], v[222:225], v[16:19]
	v_mfma_f32_16x16x32_bf16 v[60:63], v[172:175], v[202:205], v[60:63]
	v_mfma_f32_16x16x32_bf16 v[56:59], v[194:197], v[202:205], v[56:59]
	v_mfma_f32_16x16x32_bf16 v[52:55], v[172:175], v[210:213], v[52:55]
	v_mfma_f32_16x16x32_bf16 v[48:51], v[194:197], v[210:213], v[48:51]
	v_mfma_f32_16x16x32_bf16 v[36:39], v[172:175], v[218:221], v[36:39]
	v_mfma_f32_16x16x32_bf16 v[32:35], v[194:197], v[218:221], v[32:35]
	s_waitcnt lgkmcnt(0)
	v_mfma_f32_16x16x32_bf16 v[20:23], v[172:175], v[226:229], v[20:23]
	v_mfma_f32_16x16x32_bf16 v[16:19], v[194:197], v[226:229], v[16:19]
	s_setprio 0
	s_barrier
	s_add_u32 s28, s46, 0x40000
	s_addc_u32 s29, s47, 0
	s_add_i32 s76, s56, s6
	v_lshl_add_u64 v[168:169], s[28:29], 0, v[158:159]
	s_mov_b32 m0, s76
	s_nop 0
	global_load_lds_dwordx4 v[168:169], off
	v_lshl_add_u64 v[168:169], s[28:29], 0, v[162:163]
	s_add_i32 m0, s76, 0x2000
	s_nop 0
	global_load_lds_dwordx4 v[168:169], off
	s_waitcnt vmcnt(6)
	s_barrier
	s_setprio 1
	v_mfma_f32_16x16x32_bf16 v[44:47], v[230:233], v[198:201], v[44:47]
	v_mfma_f32_16x16x32_bf16 v[40:43], v[238:241], v[198:201], v[40:43]
	v_mfma_f32_16x16x32_bf16 v[28:31], v[230:233], v[206:209], v[28:31]
	v_mfma_f32_16x16x32_bf16 v[24:27], v[238:241], v[206:209], v[24:27]
	v_mfma_f32_16x16x32_bf16 v[12:15], v[230:233], v[214:217], v[12:15]
	v_mfma_f32_16x16x32_bf16 v[8:11], v[238:241], v[214:217], v[8:11]
	v_mfma_f32_16x16x32_bf16 v[4:7], v[230:233], v[222:225], v[4:7]
	v_mfma_f32_16x16x32_bf16 v[0:3], v[238:241], v[222:225], v[0:3]
	v_mfma_f32_16x16x32_bf16 v[44:47], v[234:237], v[202:205], v[44:47]
	v_mfma_f32_16x16x32_bf16 v[40:43], v[242:245], v[202:205], v[40:43]
	v_mfma_f32_16x16x32_bf16 v[28:31], v[234:237], v[210:213], v[28:31]
	v_mfma_f32_16x16x32_bf16 v[24:27], v[242:245], v[210:213], v[24:27]
	v_mfma_f32_16x16x32_bf16 v[12:15], v[234:237], v[218:221], v[12:15]
	v_mfma_f32_16x16x32_bf16 v[8:11], v[242:245], v[218:221], v[8:11]
	v_mfma_f32_16x16x32_bf16 v[4:7], v[234:237], v[226:229], v[4:7]
	v_mfma_f32_16x16x32_bf16 v[0:3], v[242:245], v[226:229], v[0:3]
	s_setprio 0
	s_add_i32 s76, 0, 0x18000
	v_add_u32_e32 v145, s76, v137
	s_barrier
	ds_read_b128 v[168:171], v145
	ds_read_b128 v[172:175], v145 offset:1024
	ds_read_b128 v[176:179], v145 offset:2048
	ds_read_b128 v[194:197], v145 offset:3072
	s_add_u32 s28, s48, 0x40000
	s_addc_u32 s29, s49, 0
	s_mov_b32 m0, s26
	v_lshl_add_u64 v[230:231], s[28:29], 0, v[156:157]
	ds_read_b128 v[198:201], v140 offset:32768
	ds_read_b128 v[202:205], v140 offset:33792
	ds_read_b128 v[206:209], v140 offset:34816
	ds_read_b128 v[210:213], v140 offset:35840
	ds_read_b128 v[214:217], v140 offset:36864
	ds_read_b128 v[218:221], v140 offset:37888
	ds_read_b128 v[222:225], v140 offset:38912
	ds_read_b128 v[226:229], v140 offset:39936
	global_load_lds_dwordx4 v[230:231], off
	v_lshl_add_u64 v[230:231], s[28:29], 0, v[160:161]
	s_mov_b32 m0, s27
	s_nop 0
	global_load_lds_dwordx4 v[230:231], off
	s_waitcnt lgkmcnt(8)
	s_barrier
	s_nop 0
	s_setprio 1
	s_waitcnt lgkmcnt(7)
	v_mfma_f32_16x16x32_bf16 v[124:127], v[168:171], v[198:201], v[124:127]
	v_mfma_f32_16x16x32_bf16 v[120:123], v[176:179], v[198:201], v[120:123]
	s_waitcnt lgkmcnt(5)
	v_mfma_f32_16x16x32_bf16 v[116:119], v[168:171], v[206:209], v[116:119]
	v_mfma_f32_16x16x32_bf16 v[112:115], v[176:179], v[206:209], v[112:115]
	s_waitcnt lgkmcnt(3)
	v_mfma_f32_16x16x32_bf16 v[100:103], v[168:171], v[214:217], v[100:103]
	v_mfma_f32_16x16x32_bf16 v[96:99], v[176:179], v[214:217], v[96:99]
	s_waitcnt lgkmcnt(1)
	v_mfma_f32_16x16x32_bf16 v[84:87], v[168:171], v[222:225], v[84:87]
	v_mfma_f32_16x16x32_bf16 v[80:83], v[176:179], v[222:225], v[80:83]
	v_mfma_f32_16x16x32_bf16 v[124:127], v[172:175], v[202:205], v[124:127]
	v_mfma_f32_16x16x32_bf16 v[120:123], v[194:197], v[202:205], v[120:123]
	v_mfma_f32_16x16x32_bf16 v[116:119], v[172:175], v[210:213], v[116:119]
	v_mfma_f32_16x16x32_bf16 v[112:115], v[194:197], v[210:213], v[112:115]
	v_mfma_f32_16x16x32_bf16 v[100:103], v[172:175], v[218:221], v[100:103]
	v_mfma_f32_16x16x32_bf16 v[96:99], v[194:197], v[218:221], v[96:99]
	s_waitcnt lgkmcnt(0)
	v_mfma_f32_16x16x32_bf16 v[84:87], v[172:175], v[226:229], v[84:87]
	v_mfma_f32_16x16x32_bf16 v[80:83], v[194:197], v[226:229], v[80:83]
	s_setprio 0
	s_barrier
	s_add_i32 s48, 0, 0x1c000
	s_add_i32 s28, s76, s6
	v_add_u32_e32 v145, s48, v137
	v_lshl_add_u64 v[142:143], v[142:143], 0, s[10:11]
	s_mov_b32 m0, s28
	ds_read_b128 v[230:233], v145
	ds_read_b128 v[234:237], v145 offset:1024
	ds_read_b128 v[238:241], v145 offset:2048
	ds_read_b128 v[242:245], v145 offset:3072
	global_load_lds_dwordx4 v[142:143], off
	v_lshl_add_u64 v[142:143], v[246:247], 0, s[10:11]
	s_add_i32 m0, s28, 0x2000
	s_nop 0
	global_load_lds_dwordx4 v[142:143], off
	s_barrier
	s_nop 0
	s_setprio 1
	s_waitcnt lgkmcnt(3)
	v_mfma_f32_16x16x32_bf16 v[108:111], v[230:233], v[198:201], v[108:111]
	s_waitcnt lgkmcnt(1)
	v_mfma_f32_16x16x32_bf16 v[104:107], v[238:241], v[198:201], v[104:107]
	v_mfma_f32_16x16x32_bf16 v[92:95], v[230:233], v[206:209], v[92:95]
	v_mfma_f32_16x16x32_bf16 v[88:91], v[238:241], v[206:209], v[88:91]
	v_mfma_f32_16x16x32_bf16 v[76:79], v[230:233], v[214:217], v[76:79]
	v_mfma_f32_16x16x32_bf16 v[72:75], v[238:241], v[214:217], v[72:75]
	v_mfma_f32_16x16x32_bf16 v[68:71], v[230:233], v[222:225], v[68:71]
	v_mfma_f32_16x16x32_bf16 v[64:67], v[238:241], v[222:225], v[64:67]
	v_mfma_f32_16x16x32_bf16 v[108:111], v[234:237], v[202:205], v[108:111]
	s_waitcnt lgkmcnt(0)
	v_mfma_f32_16x16x32_bf16 v[104:107], v[242:245], v[202:205], v[104:107]
	v_mfma_f32_16x16x32_bf16 v[92:95], v[234:237], v[210:213], v[92:95]
	v_mfma_f32_16x16x32_bf16 v[88:91], v[242:245], v[210:213], v[88:91]
	v_mfma_f32_16x16x32_bf16 v[76:79], v[234:237], v[218:221], v[76:79]
	v_mfma_f32_16x16x32_bf16 v[72:75], v[242:245], v[218:221], v[72:75]
	v_mfma_f32_16x16x32_bf16 v[68:71], v[234:237], v[226:229], v[68:71]
	v_mfma_f32_16x16x32_bf16 v[64:67], v[242:245], v[226:229], v[64:67]
	s_setprio 0
	s_mov_b32 m0, s51
	v_lshl_add_u64 v[142:143], v[248:249], 0, s[10:11]
	s_barrier
	ds_read_b128 v[198:201], v140 offset:49152
	ds_read_b128 v[202:205], v140 offset:50176
	ds_read_b128 v[206:209], v140 offset:51200
	ds_read_b128 v[210:213], v140 offset:52224
	ds_read_b128 v[214:217], v140 offset:53248
	ds_read_b128 v[218:221], v140 offset:54272
	ds_read_b128 v[222:225], v140 offset:55296
	ds_read_b128 v[226:229], v140 offset:56320
	global_load_lds_dwordx4 v[142:143], off
	v_lshl_add_u64 v[142:143], v[250:251], 0, s[10:11]
	s_mov_b32 m0, s52
	s_nop 0
	global_load_lds_dwordx4 v[142:143], off
	s_barrier
	s_nop 0
	s_setprio 1
	s_waitcnt lgkmcnt(7)
	v_mfma_f32_16x16x32_bf16 v[60:63], v[168:171], v[198:201], v[60:63]
	v_mfma_f32_16x16x32_bf16 v[56:59], v[176:179], v[198:201], v[56:59]
	s_waitcnt lgkmcnt(5)
	v_mfma_f32_16x16x32_bf16 v[52:55], v[168:171], v[206:209], v[52:55]
	v_mfma_f32_16x16x32_bf16 v[48:51], v[176:179], v[206:209], v[48:51]
	s_waitcnt lgkmcnt(3)
	v_mfma_f32_16x16x32_bf16 v[36:39], v[168:171], v[214:217], v[36:39]
	v_mfma_f32_16x16x32_bf16 v[32:35], v[176:179], v[214:217], v[32:35]
	s_waitcnt lgkmcnt(1)
	v_mfma_f32_16x16x32_bf16 v[20:23], v[168:171], v[222:225], v[20:23]
	v_mfma_f32_16x16x32_bf16 v[16:19], v[176:179], v[222:225], v[16:19]
	v_mfma_f32_16x16x32_bf16 v[60:63], v[172:175], v[202:205], v[60:63]
	v_mfma_f32_16x16x32_bf16 v[56:59], v[194:197], v[202:205], v[56:59]
	v_mfma_f32_16x16x32_bf16 v[52:55], v[172:175], v[210:213], v[52:55]
	v_mfma_f32_16x16x32_bf16 v[48:51], v[194:197], v[210:213], v[48:51]
	v_mfma_f32_16x16x32_bf16 v[36:39], v[172:175], v[218:221], v[36:39]
	v_mfma_f32_16x16x32_bf16 v[32:35], v[194:197], v[218:221], v[32:35]
	s_waitcnt lgkmcnt(0)
	v_mfma_f32_16x16x32_bf16 v[20:23], v[172:175], v[226:229], v[20:23]
	v_mfma_f32_16x16x32_bf16 v[16:19], v[194:197], v[226:229], v[16:19]
	s_setprio 0
	s_barrier
	s_add_u32 s28, s46, 0x40080
	s_addc_u32 s29, s47, 0
	s_add_i32 s46, s48, s6
	v_lshl_add_u64 v[142:143], s[28:29], 0, v[158:159]
	s_mov_b32 m0, s46
	s_nop 0
	global_load_lds_dwordx4 v[142:143], off
	v_lshl_add_u64 v[142:143], s[28:29], 0, v[162:163]
	s_add_i32 m0, s46, 0x2000
	s_nop 0
	global_load_lds_dwordx4 v[142:143], off
	s_waitcnt vmcnt(6)
	s_barrier
	s_setprio 1
	v_mfma_f32_16x16x32_bf16 v[44:47], v[230:233], v[198:201], v[44:47]
	v_mfma_f32_16x16x32_bf16 v[40:43], v[238:241], v[198:201], v[40:43]
	v_mfma_f32_16x16x32_bf16 v[28:31], v[230:233], v[206:209], v[28:31]
	v_mfma_f32_16x16x32_bf16 v[24:27], v[238:241], v[206:209], v[24:27]
	v_mfma_f32_16x16x32_bf16 v[12:15], v[230:233], v[214:217], v[12:15]
	v_mfma_f32_16x16x32_bf16 v[8:11], v[238:241], v[214:217], v[8:11]
	v_mfma_f32_16x16x32_bf16 v[4:7], v[230:233], v[222:225], v[4:7]
	v_mfma_f32_16x16x32_bf16 v[0:3], v[238:241], v[222:225], v[0:3]
	v_mfma_f32_16x16x32_bf16 v[44:47], v[234:237], v[202:205], v[44:47]
	v_mfma_f32_16x16x32_bf16 v[40:43], v[242:245], v[202:205], v[40:43]
	v_mfma_f32_16x16x32_bf16 v[28:31], v[234:237], v[210:213], v[28:31]
	v_mfma_f32_16x16x32_bf16 v[24:27], v[242:245], v[210:213], v[24:27]
	v_mfma_f32_16x16x32_bf16 v[12:15], v[234:237], v[218:221], v[12:15]
	v_mfma_f32_16x16x32_bf16 v[8:11], v[242:245], v[218:221], v[8:11]
	v_mfma_f32_16x16x32_bf16 v[4:7], v[234:237], v[226:229], v[4:7]
	v_mfma_f32_16x16x32_bf16 v[0:3], v[242:245], v[226:229], v[0:3]
	s_setprio 0
	s_add_i32 s75, s75, 2
	s_add_u32 s73, s73, 0x100
	s_addc_u32 s74, s74, 0
	s_add_u32 s44, s44, 0x100
	s_addc_u32 s45, s45, 0
	s_cmp_gt_u32 s75, 13
	s_barrier
	s_cbranch_scc0 .LBB0_962
	s_cmp_eq_u32 s18, 0
	s_cselect_b32 s18, s63, 0
	s_cselect_b32 s21, s62, 0
	v_lshl_or_b32 v168, s71, 8, v138
	v_lshl_add_u32 v170, s22, 8, v136
	v_mov_b32_e32 v142, s21
	v_mov_b32_e32 v143, s18
	v_ashrrev_i32_e32 v169, 31, v168
	v_ashrrev_i32_e32 v171, 31, v170
	v_lshl_add_u64 v[142:143], v[168:169], 1, v[142:143]
	v_lshlrev_b64 v[168:169], 11, v[170:171]
	v_lshl_add_u64 v[168:169], v[142:143], 0, v[168:169]
	v_cvt_pk_bf16_f32 v60, v60, v61
	v_cvt_pk_bf16_f32 v61, v62, v63
	v_cvt_pk_bf16_f32 v62, v56, v57
	v_add_co_u32_e32 v56, vcc, s57, v168
	v_cvt_pk_bf16_f32 v68, v68, v69
	v_cvt_pk_bf16_f32 v69, v70, v71
	v_cvt_pk_bf16_f32 v70, v64, v65
	v_lshl_add_u64 v[64:65], v[168:169], 0, s[0:1]
	v_addc_co_u32_e32 v57, vcc, 0, v169, vcc
	v_cvt_pk_bf16_f32 v44, v44, v45
	v_cvt_pk_bf16_f32 v45, v46, v47
	v_cvt_pk_bf16_f32 v46, v40, v41
	v_cvt_pk_bf16_f32 v47, v42, v43
	global_store_dwordx4 v[64:65], v[44:47], off offset:256
	v_cvt_pk_bf16_f32 v108, v108, v109
	v_cvt_pk_bf16_f32 v109, v110, v111
	v_add_co_u32_e32 v46, vcc, s64, v168
	v_cvt_pk_bf16_f32 v110, v104, v105
	v_or_b32_e32 v104, 16, v170
	v_lshl_add_u64 v[44:45], v[168:169], 0, s[12:13]
	v_addc_co_u32_e32 v47, vcc, 0, v169, vcc
	v_cvt_pk_bf16_f32 v28, v28, v29
	v_cvt_pk_bf16_f32 v29, v30, v31
	v_cvt_pk_bf16_f32 v30, v24, v25
	v_cvt_pk_bf16_f32 v31, v26, v27
	v_ashrrev_i32_e32 v105, 31, v104
	v_cvt_pk_bf16_f32 v92, v92, v93
	v_cvt_pk_bf16_f32 v93, v94, v95
	v_cvt_pk_bf16_f32 v94, v88, v89
	v_or_b32_e32 v88, 32, v170
	global_store_dwordx4 v[44:45], v[28:31], off offset:256
	v_cvt_pk_bf16_f32 v111, v106, v107
	v_lshlrev_b64 v[104:105], 11, v[104:105]
	v_add_co_u32_e32 v30, vcc, s65, v168
	v_ashrrev_i32_e32 v89, 31, v88
	v_cvt_pk_bf16_f32 v76, v76, v77
	v_cvt_pk_bf16_f32 v77, v78, v79
	v_cvt_pk_bf16_f32 v78, v72, v73
	v_or_b32_e32 v72, 48, v170
	v_lshl_add_u64 v[28:29], v[168:169], 0, s[14:15]
	v_addc_co_u32_e32 v31, vcc, 0, v169, vcc
	v_cvt_pk_bf16_f32 v12, v12, v13
	v_cvt_pk_bf16_f32 v13, v14, v15
	v_cvt_pk_bf16_f32 v14, v8, v9
	v_cvt_pk_bf16_f32 v15, v10, v11
	global_store_dwordx4 v[168:169], v[108:111], off offset:256
	v_cvt_pk_bf16_f32 v95, v90, v91
	v_lshlrev_b64 v[88:89], 11, v[88:89]
	v_lshl_add_u64 v[108:109], v[142:143], 0, v[104:105]
	v_ashrrev_i32_e32 v73, 31, v72
	global_store_dwordx4 v[28:29], v[12:15], off offset:256
	global_store_dwordx4 v[108:109], v[92:95], off offset:256
	v_cvt_pk_bf16_f32 v79, v74, v75
	v_add_co_u32_e32 v14, vcc, s70, v168
	v_lshl_add_u64 v[92:93], v[142:143], 0, v[88:89]
	v_lshlrev_b64 v[72:73], 11, v[72:73]
	v_addc_co_u32_e32 v15, vcc, 0, v169, vcc
	v_cvt_pk_bf16_f32 v124, v124, v125
	v_cvt_pk_bf16_f32 v125, v126, v127
	v_cvt_pk_bf16_f32 v126, v120, v121
	v_cvt_pk_bf16_f32 v127, v122, v123
	v_cvt_pk_bf16_f32 v104, v116, v117
	v_cvt_pk_bf16_f32 v105, v118, v119
	v_cvt_pk_bf16_f32 v106, v112, v113
	v_cvt_pk_bf16_f32 v107, v114, v115
	v_cvt_pk_bf16_f32 v88, v100, v101
	v_cvt_pk_bf16_f32 v89, v102, v103
	v_cvt_pk_bf16_f32 v90, v96, v97
	v_cvt_pk_bf16_f32 v91, v98, v99
	global_store_dwordx4 v[92:93], v[76:79], off offset:256
	v_cvt_pk_bf16_f32 v74, v80, v81
	v_cvt_pk_bf16_f32 v75, v82, v83
	v_lshl_add_u64 v[76:77], v[142:143], 0, v[72:73]
	v_cvt_pk_bf16_f32 v72, v84, v85
	v_cvt_pk_bf16_f32 v73, v86, v87
	v_cvt_pk_bf16_f32 v71, v66, v67
	v_cvt_pk_bf16_f32 v63, v58, v59
	v_cvt_pk_bf16_f32 v40, v52, v53
	v_cvt_pk_bf16_f32 v41, v54, v55
	v_cvt_pk_bf16_f32 v42, v48, v49
	v_cvt_pk_bf16_f32 v43, v50, v51
	v_cvt_pk_bf16_f32 v24, v36, v37
	v_cvt_pk_bf16_f32 v25, v38, v39
	v_cvt_pk_bf16_f32 v26, v32, v33
	v_cvt_pk_bf16_f32 v27, v34, v35
	v_lshl_add_u64 v[12:13], v[168:169], 0, s[16:17]
	v_cvt_pk_bf16_f32 v8, v20, v21
	v_cvt_pk_bf16_f32 v9, v22, v23
	v_cvt_pk_bf16_f32 v10, v16, v17
	v_cvt_pk_bf16_f32 v11, v18, v19
	v_cvt_pk_bf16_f32 v4, v4, v5
	v_cvt_pk_bf16_f32 v5, v6, v7
	v_cvt_pk_bf16_f32 v6, v0, v1
	v_cvt_pk_bf16_f32 v7, v2, v3
	s_and_b64 vcc, exec, s[8:9]
	s_mov_b32 s18, s20
	s_mov_b32 s71, s38
	s_mov_b32 s22, s24
	s_mov_b64 s[44:45], s[42:43]
	s_mov_b64 s[46:47], s[40:41]
	global_store_dwordx4 v[168:169], v[124:127], off
	global_store_dwordx4 v[108:109], v[104:107], off
	global_store_dwordx4 v[92:93], v[88:91], off
	global_store_dwordx4 v[76:77], v[72:75], off
	global_store_dwordx4 v[76:77], v[68:71], off offset:256
	global_store_dwordx4 v[56:57], v[60:63], off
	global_store_dwordx4 v[46:47], v[40:43], off
	global_store_dwordx4 v[30:31], v[24:27], off
	global_store_dwordx4 v[14:15], v[8:11], off
	global_store_dwordx4 v[12:13], v[4:7], off offset:256
	s_cbranch_vccz .LBB0_959
	s_waitcnt vmcnt(0)
	s_cmpk_gt_u32 s3, 0xff
	s_cbranch_scc1 .LBB0_966
	s_barrier

.LBB0_1083:
	ds_read_b128 v[168:171], v139
	ds_read_b128 v[172:175], v139 offset:1024
	ds_read_b128 v[176:179], v139 offset:2048
	ds_read_b128 v[194:197], v139 offset:3072
	s_add_u32 s24, s22, 0xfffc0080
	s_addc_u32 s25, s23, -1
	s_cmp_eq_u32 s53, 12
	s_cselect_b32 s39, s11, s25
	s_cselect_b32 s38, s13, s24
	s_cselect_b32 s25, s15, s52
	s_cselect_b32 s24, s50, s51
	v_lshl_add_u64 v[142:143], s[22:23], 0, v[128:129]
	s_add_i32 m0, s21, 0xc000
	ds_read_b128 v[198:201], v140
	ds_read_b128 v[202:205], v140 offset:1024
	ds_read_b128 v[206:209], v140 offset:2048
	ds_read_b128 v[210:213], v140 offset:3072
	ds_read_b128 v[214:217], v140 offset:4096
	ds_read_b128 v[218:221], v140 offset:5120
	ds_read_b128 v[222:225], v140 offset:6144
	ds_read_b128 v[226:229], v140 offset:7168
	global_load_lds_dwordx4 v[142:143], off
	v_lshl_add_u64 v[142:143], s[22:23], 0, v[130:131]
	s_add_i32 m0, s21, 0xe000
	s_nop 0
	global_load_lds_dwordx4 v[142:143], off
	s_waitcnt lgkmcnt(8)
	s_barrier
	s_nop 0
	s_setprio 1
	s_waitcnt lgkmcnt(7)
	v_mfma_f32_16x16x32_bf16 v[124:127], v[168:171], v[198:201], v[124:127]
	v_mfma_f32_16x16x32_bf16 v[120:123], v[176:179], v[198:201], v[120:123]
	s_waitcnt lgkmcnt(5)
	v_mfma_f32_16x16x32_bf16 v[108:111], v[168:171], v[206:209], v[108:111]
	v_mfma_f32_16x16x32_bf16 v[104:107], v[176:179], v[206:209], v[104:107]
	s_waitcnt lgkmcnt(3)
	v_mfma_f32_16x16x32_bf16 v[92:95], v[168:171], v[214:217], v[92:95]
	v_mfma_f32_16x16x32_bf16 v[88:91], v[176:179], v[214:217], v[88:91]
	s_waitcnt lgkmcnt(1)
	v_mfma_f32_16x16x32_bf16 v[76:79], v[168:171], v[222:225], v[76:79]
	v_mfma_f32_16x16x32_bf16 v[72:75], v[176:179], v[222:225], v[72:75]
	v_mfma_f32_16x16x32_bf16 v[124:127], v[172:175], v[202:205], v[124:127]
	v_mfma_f32_16x16x32_bf16 v[120:123], v[194:197], v[202:205], v[120:123]
	v_mfma_f32_16x16x32_bf16 v[108:111], v[172:175], v[210:213], v[108:111]
	v_mfma_f32_16x16x32_bf16 v[104:107], v[194:197], v[210:213], v[104:107]
	v_mfma_f32_16x16x32_bf16 v[92:95], v[172:175], v[218:221], v[92:95]
	v_mfma_f32_16x16x32_bf16 v[88:91], v[194:197], v[218:221], v[88:91]
	s_waitcnt lgkmcnt(0)
	v_mfma_f32_16x16x32_bf16 v[76:79], v[172:175], v[226:229], v[76:79]
	v_mfma_f32_16x16x32_bf16 v[72:75], v[194:197], v[226:229], v[72:75]
	s_setprio 0
	s_barrier
	s_add_i32 s28, s46, s6
	v_lshl_add_u64 v[142:143], s[24:25], 0, v[158:159]
	s_mov_b32 m0, s28
	ds_read_b128 v[230:233], v141
	ds_read_b128 v[234:237], v141 offset:1024
	ds_read_b128 v[238:241], v141 offset:2048
	ds_read_b128 v[242:245], v141 offset:3072
	global_load_lds_dwordx4 v[142:143], off
	v_lshl_add_u64 v[246:247], s[24:25], 0, v[162:163]
	s_add_i32 m0, s28, 0x2000
	s_nop 0
	global_load_lds_dwordx4 v[246:247], off
	s_barrier
	s_nop 0
	s_setprio 1
	s_waitcnt lgkmcnt(3)
	v_mfma_f32_16x16x32_bf16 v[116:119], v[230:233], v[198:201], v[116:119]
	s_waitcnt lgkmcnt(1)
	v_mfma_f32_16x16x32_bf16 v[112:115], v[238:241], v[198:201], v[112:115]
	v_mfma_f32_16x16x32_bf16 v[100:103], v[230:233], v[206:209], v[100:103]
	v_mfma_f32_16x16x32_bf16 v[96:99], v[238:241], v[206:209], v[96:99]
	v_mfma_f32_16x16x32_bf16 v[84:87], v[230:233], v[214:217], v[84:87]
	v_mfma_f32_16x16x32_bf16 v[80:83], v[238:241], v[214:217], v[80:83]
	v_mfma_f32_16x16x32_bf16 v[68:71], v[230:233], v[222:225], v[68:71]
	v_mfma_f32_16x16x32_bf16 v[64:67], v[238:241], v[222:225], v[64:67]
	v_mfma_f32_16x16x32_bf16 v[116:119], v[234:237], v[202:205], v[116:119]
	s_waitcnt lgkmcnt(0)
	v_mfma_f32_16x16x32_bf16 v[112:115], v[242:245], v[202:205], v[112:115]
	v_mfma_f32_16x16x32_bf16 v[100:103], v[234:237], v[210:213], v[100:103]
	v_mfma_f32_16x16x32_bf16 v[96:99], v[242:245], v[210:213], v[96:99]
	v_mfma_f32_16x16x32_bf16 v[84:87], v[234:237], v[218:221], v[84:87]
	v_mfma_f32_16x16x32_bf16 v[80:83], v[242:245], v[218:221], v[80:83]
	v_mfma_f32_16x16x32_bf16 v[68:71], v[234:237], v[226:229], v[68:71]
	v_mfma_f32_16x16x32_bf16 v[64:67], v[242:245], v[226:229], v[64:67]
	s_setprio 0
	s_mov_b32 m0, s21
	v_lshl_add_u64 v[248:249], s[38:39], 0, v[156:157]
	s_barrier
	ds_read_b128 v[198:201], v140 offset:16384
	ds_read_b128 v[202:205], v140 offset:17408
	ds_read_b128 v[206:209], v140 offset:18432
	ds_read_b128 v[210:213], v140 offset:19456
	ds_read_b128 v[214:217], v140 offset:20480
	ds_read_b128 v[218:221], v140 offset:21504
	ds_read_b128 v[222:225], v140 offset:22528
	ds_read_b128 v[226:229], v140 offset:23552
	global_load_lds_dwordx4 v[248:249], off
	v_lshl_add_u64 v[250:251], s[38:39], 0, v[160:161]
	s_mov_b32 m0, s26
	s_nop 0
	global_load_lds_dwordx4 v[250:251], off
	s_barrier
	s_nop 0
	s_setprio 1
	s_waitcnt lgkmcnt(7)
	v_mfma_f32_16x16x32_bf16 v[60:63], v[168:171], v[198:201], v[60:63]
	v_mfma_f32_16x16x32_bf16 v[56:59], v[176:179], v[198:201], v[56:59]
	s_waitcnt lgkmcnt(5)
	v_mfma_f32_16x16x32_bf16 v[44:47], v[168:171], v[206:209], v[44:47]
	v_mfma_f32_16x16x32_bf16 v[40:43], v[176:179], v[206:209], v[40:43]
	s_waitcnt lgkmcnt(3)
	v_mfma_f32_16x16x32_bf16 v[28:31], v[168:171], v[214:217], v[28:31]
	v_mfma_f32_16x16x32_bf16 v[24:27], v[176:179], v[214:217], v[24:27]
	s_waitcnt lgkmcnt(1)
	v_mfma_f32_16x16x32_bf16 v[12:15], v[168:171], v[222:225], v[12:15]
	v_mfma_f32_16x16x32_bf16 v[8:11], v[176:179], v[222:225], v[8:11]
	v_mfma_f32_16x16x32_bf16 v[60:63], v[172:175], v[202:205], v[60:63]
	v_mfma_f32_16x16x32_bf16 v[56:59], v[194:197], v[202:205], v[56:59]
	v_mfma_f32_16x16x32_bf16 v[44:47], v[172:175], v[210:213], v[44:47]
	v_mfma_f32_16x16x32_bf16 v[40:43], v[194:197], v[210:213], v[40:43]
	v_mfma_f32_16x16x32_bf16 v[28:31], v[172:175], v[218:221], v[28:31]
	v_mfma_f32_16x16x32_bf16 v[24:27], v[194:197], v[218:221], v[24:27]
	s_waitcnt lgkmcnt(0)
	v_mfma_f32_16x16x32_bf16 v[12:15], v[172:175], v[226:229], v[12:15]
	v_mfma_f32_16x16x32_bf16 v[8:11], v[194:197], v[226:229], v[8:11]
	s_setprio 0
	s_barrier
	s_add_u32 s28, s24, 0x40000
	s_addc_u32 s29, s25, 0
	s_add_i32 s54, s47, s6
	v_lshl_add_u64 v[168:169], s[28:29], 0, v[158:159]
	s_mov_b32 m0, s54
	s_nop 0
	global_load_lds_dwordx4 v[168:169], off
	v_lshl_add_u64 v[168:169], s[28:29], 0, v[162:163]
	s_add_i32 m0, s54, 0x2000
	s_nop 0
	global_load_lds_dwordx4 v[168:169], off
	s_waitcnt vmcnt(6)
	s_barrier
	s_setprio 1
	v_mfma_f32_16x16x32_bf16 v[52:55], v[230:233], v[198:201], v[52:55]
	v_mfma_f32_16x16x32_bf16 v[48:51], v[238:241], v[198:201], v[48:51]
	v_mfma_f32_16x16x32_bf16 v[36:39], v[230:233], v[206:209], v[36:39]
	v_mfma_f32_16x16x32_bf16 v[32:35], v[238:241], v[206:209], v[32:35]
	v_mfma_f32_16x16x32_bf16 v[20:23], v[230:233], v[214:217], v[20:23]
	v_mfma_f32_16x16x32_bf16 v[16:19], v[238:241], v[214:217], v[16:19]
	v_mfma_f32_16x16x32_bf16 v[4:7], v[230:233], v[222:225], v[4:7]
	v_mfma_f32_16x16x32_bf16 v[0:3], v[238:241], v[222:225], v[0:3]
	v_mfma_f32_16x16x32_bf16 v[52:55], v[234:237], v[202:205], v[52:55]
	v_mfma_f32_16x16x32_bf16 v[48:51], v[242:245], v[202:205], v[48:51]
	v_mfma_f32_16x16x32_bf16 v[36:39], v[234:237], v[210:213], v[36:39]
	v_mfma_f32_16x16x32_bf16 v[32:35], v[242:245], v[210:213], v[32:35]
	v_mfma_f32_16x16x32_bf16 v[20:23], v[234:237], v[218:221], v[20:23]
	v_mfma_f32_16x16x32_bf16 v[16:19], v[242:245], v[218:221], v[16:19]
	v_mfma_f32_16x16x32_bf16 v[4:7], v[234:237], v[226:229], v[4:7]
	v_mfma_f32_16x16x32_bf16 v[0:3], v[242:245], v[226:229], v[0:3]
	s_setprio 0
	s_add_i32 s54, 0, 0x18000
	v_add_u32_e32 v145, s54, v137
	s_barrier
	ds_read_b128 v[168:171], v145
	ds_read_b128 v[172:175], v145 offset:1024
	ds_read_b128 v[176:179], v145 offset:2048
	ds_read_b128 v[194:197], v145 offset:3072
	s_add_u32 s28, s38, 0x40000
	s_addc_u32 s29, s39, 0
	s_mov_b32 m0, s27
	v_lshl_add_u64 v[230:231], s[28:29], 0, v[156:157]
	ds_read_b128 v[198:201], v140 offset:32768
	ds_read_b128 v[202:205], v140 offset:33792
	ds_read_b128 v[206:209], v140 offset:34816
	ds_read_b128 v[210:213], v140 offset:35840
	ds_read_b128 v[214:217], v140 offset:36864
	ds_read_b128 v[218:221], v140 offset:37888
	ds_read_b128 v[222:225], v140 offset:38912
	ds_read_b128 v[226:229], v140 offset:39936
	global_load_lds_dwordx4 v[230:231], off
	v_lshl_add_u64 v[230:231], s[28:29], 0, v[160:161]
	s_mov_b32 m0, s33
	s_nop 0
	global_load_lds_dwordx4 v[230:231], off
	s_waitcnt lgkmcnt(8)
	s_barrier
	s_nop 0
	s_setprio 1
	s_waitcnt lgkmcnt(7)
	v_mfma_f32_16x16x32_bf16 v[124:127], v[168:171], v[198:201], v[124:127]
	v_mfma_f32_16x16x32_bf16 v[120:123], v[176:179], v[198:201], v[120:123]
	s_waitcnt lgkmcnt(5)
	v_mfma_f32_16x16x32_bf16 v[108:111], v[168:171], v[206:209], v[108:111]
	v_mfma_f32_16x16x32_bf16 v[104:107], v[176:179], v[206:209], v[104:107]
	s_waitcnt lgkmcnt(3)
	v_mfma_f32_16x16x32_bf16 v[92:95], v[168:171], v[214:217], v[92:95]
	v_mfma_f32_16x16x32_bf16 v[88:91], v[176:179], v[214:217], v[88:91]
	s_waitcnt lgkmcnt(1)
	v_mfma_f32_16x16x32_bf16 v[76:79], v[168:171], v[222:225], v[76:79]
	v_mfma_f32_16x16x32_bf16 v[72:75], v[176:179], v[222:225], v[72:75]
	v_mfma_f32_16x16x32_bf16 v[124:127], v[172:175], v[202:205], v[124:127]
	v_mfma_f32_16x16x32_bf16 v[120:123], v[194:197], v[202:205], v[120:123]
	v_mfma_f32_16x16x32_bf16 v[108:111], v[172:175], v[210:213], v[108:111]
	v_mfma_f32_16x16x32_bf16 v[104:107], v[194:197], v[210:213], v[104:107]
	v_mfma_f32_16x16x32_bf16 v[92:95], v[172:175], v[218:221], v[92:95]
	v_mfma_f32_16x16x32_bf16 v[88:91], v[194:197], v[218:221], v[88:91]
	s_waitcnt lgkmcnt(0)
	v_mfma_f32_16x16x32_bf16 v[76:79], v[172:175], v[226:229], v[76:79]
	v_mfma_f32_16x16x32_bf16 v[72:75], v[194:197], v[226:229], v[72:75]
	s_setprio 0
	s_barrier
	s_add_i32 s28, 0, 0x1c000
	s_add_i32 s29, s54, s6
	v_add_u32_e32 v145, s28, v137
	v_lshl_add_u64 v[142:143], v[142:143], 0, s[0:1]
	s_mov_b32 m0, s29
	ds_read_b128 v[230:233], v145
	ds_read_b128 v[234:237], v145 offset:1024
	ds_read_b128 v[238:241], v145 offset:2048
	ds_read_b128 v[242:245], v145 offset:3072
	global_load_lds_dwordx4 v[142:143], off
	v_lshl_add_u64 v[142:143], v[246:247], 0, s[0:1]
	s_add_i32 m0, s29, 0x2000
	s_nop 0
	global_load_lds_dwordx4 v[142:143], off
	s_barrier
	s_nop 0
	s_setprio 1
	s_waitcnt lgkmcnt(3)
	v_mfma_f32_16x16x32_bf16 v[116:119], v[230:233], v[198:201], v[116:119]
	s_waitcnt lgkmcnt(1)
	v_mfma_f32_16x16x32_bf16 v[112:115], v[238:241], v[198:201], v[112:115]
	v_mfma_f32_16x16x32_bf16 v[100:103], v[230:233], v[206:209], v[100:103]
	v_mfma_f32_16x16x32_bf16 v[96:99], v[238:241], v[206:209], v[96:99]
	v_mfma_f32_16x16x32_bf16 v[84:87], v[230:233], v[214:217], v[84:87]
	v_mfma_f32_16x16x32_bf16 v[80:83], v[238:241], v[214:217], v[80:83]
	v_mfma_f32_16x16x32_bf16 v[68:71], v[230:233], v[222:225], v[68:71]
	v_mfma_f32_16x16x32_bf16 v[64:67], v[238:241], v[222:225], v[64:67]
	v_mfma_f32_16x16x32_bf16 v[116:119], v[234:237], v[202:205], v[116:119]
	s_waitcnt lgkmcnt(0)
	v_mfma_f32_16x16x32_bf16 v[112:115], v[242:245], v[202:205], v[112:115]
	v_mfma_f32_16x16x32_bf16 v[100:103], v[234:237], v[210:213], v[100:103]
	v_mfma_f32_16x16x32_bf16 v[96:99], v[242:245], v[210:213], v[96:99]
	v_mfma_f32_16x16x32_bf16 v[84:87], v[234:237], v[218:221], v[84:87]
	v_mfma_f32_16x16x32_bf16 v[80:83], v[242:245], v[218:221], v[80:83]
	v_mfma_f32_16x16x32_bf16 v[68:71], v[234:237], v[226:229], v[68:71]
	v_mfma_f32_16x16x32_bf16 v[64:67], v[242:245], v[226:229], v[64:67]
	s_setprio 0
	s_mov_b32 m0, s42
	v_lshl_add_u64 v[142:143], v[248:249], 0, s[0:1]
	s_barrier
	ds_read_b128 v[198:201], v140 offset:49152
	ds_read_b128 v[202:205], v140 offset:50176
	ds_read_b128 v[206:209], v140 offset:51200
	ds_read_b128 v[210:213], v140 offset:52224
	ds_read_b128 v[214:217], v140 offset:53248
	ds_read_b128 v[218:221], v140 offset:54272
	ds_read_b128 v[222:225], v140 offset:55296
	ds_read_b128 v[226:229], v140 offset:56320
	global_load_lds_dwordx4 v[142:143], off
	v_lshl_add_u64 v[142:143], v[250:251], 0, s[0:1]
	s_mov_b32 m0, s43
	s_nop 0
	global_load_lds_dwordx4 v[142:143], off
	s_barrier
	s_nop 0
	s_setprio 1
	s_waitcnt lgkmcnt(7)
	v_mfma_f32_16x16x32_bf16 v[60:63], v[168:171], v[198:201], v[60:63]
	v_mfma_f32_16x16x32_bf16 v[56:59], v[176:179], v[198:201], v[56:59]
	s_waitcnt lgkmcnt(5)
	v_mfma_f32_16x16x32_bf16 v[44:47], v[168:171], v[206:209], v[44:47]
	v_mfma_f32_16x16x32_bf16 v[40:43], v[176:179], v[206:209], v[40:43]
	s_waitcnt lgkmcnt(3)
	v_mfma_f32_16x16x32_bf16 v[28:31], v[168:171], v[214:217], v[28:31]
	v_mfma_f32_16x16x32_bf16 v[24:27], v[176:179], v[214:217], v[24:27]
	s_waitcnt lgkmcnt(1)
	v_mfma_f32_16x16x32_bf16 v[12:15], v[168:171], v[222:225], v[12:15]
	v_mfma_f32_16x16x32_bf16 v[8:11], v[176:179], v[222:225], v[8:11]
	v_mfma_f32_16x16x32_bf16 v[60:63], v[172:175], v[202:205], v[60:63]
	v_mfma_f32_16x16x32_bf16 v[56:59], v[194:197], v[202:205], v[56:59]
	v_mfma_f32_16x16x32_bf16 v[44:47], v[172:175], v[210:213], v[44:47]
	v_mfma_f32_16x16x32_bf16 v[40:43], v[194:197], v[210:213], v[40:43]
	v_mfma_f32_16x16x32_bf16 v[28:31], v[172:175], v[218:221], v[28:31]
	v_mfma_f32_16x16x32_bf16 v[24:27], v[194:197], v[218:221], v[24:27]
	s_waitcnt lgkmcnt(0)
	v_mfma_f32_16x16x32_bf16 v[12:15], v[172:175], v[226:229], v[12:15]
	v_mfma_f32_16x16x32_bf16 v[8:11], v[194:197], v[226:229], v[8:11]
	s_setprio 0
	s_barrier
	s_add_u32 s24, s24, 0x40080
	s_addc_u32 s25, s25, 0
	s_add_i32 s28, s28, s6
	v_lshl_add_u64 v[142:143], s[24:25], 0, v[158:159]
	s_mov_b32 m0, s28
	s_nop 0
	global_load_lds_dwordx4 v[142:143], off
	v_lshl_add_u64 v[142:143], s[24:25], 0, v[162:163]
	s_add_i32 m0, s28, 0x2000
	s_nop 0
	global_load_lds_dwordx4 v[142:143], off
	s_waitcnt vmcnt(6)
	s_barrier
	s_setprio 1
	v_mfma_f32_16x16x32_bf16 v[52:55], v[230:233], v[198:201], v[52:55]
	v_mfma_f32_16x16x32_bf16 v[48:51], v[238:241], v[198:201], v[48:51]
	v_mfma_f32_16x16x32_bf16 v[36:39], v[230:233], v[206:209], v[36:39]
	v_mfma_f32_16x16x32_bf16 v[32:35], v[238:241], v[206:209], v[32:35]
	v_mfma_f32_16x16x32_bf16 v[20:23], v[230:233], v[214:217], v[20:23]
	v_mfma_f32_16x16x32_bf16 v[16:19], v[238:241], v[214:217], v[16:19]
	v_mfma_f32_16x16x32_bf16 v[4:7], v[230:233], v[222:225], v[4:7]
	v_mfma_f32_16x16x32_bf16 v[0:3], v[238:241], v[222:225], v[0:3]
	v_mfma_f32_16x16x32_bf16 v[52:55], v[234:237], v[202:205], v[52:55]
	v_mfma_f32_16x16x32_bf16 v[48:51], v[242:245], v[202:205], v[48:51]
	v_mfma_f32_16x16x32_bf16 v[36:39], v[234:237], v[210:213], v[36:39]
	v_mfma_f32_16x16x32_bf16 v[32:35], v[242:245], v[210:213], v[32:35]
	v_mfma_f32_16x16x32_bf16 v[20:23], v[234:237], v[218:221], v[20:23]
	v_mfma_f32_16x16x32_bf16 v[16:19], v[242:245], v[218:221], v[16:19]
	v_mfma_f32_16x16x32_bf16 v[4:7], v[234:237], v[226:229], v[4:7]
	v_mfma_f32_16x16x32_bf16 v[0:3], v[242:245], v[226:229], v[0:3]
	s_setprio 0
	s_add_i32 s53, s53, 2
	s_add_u32 s22, s22, 0x100
	s_addc_u32 s23, s23, 0
	s_add_u32 s51, s51, 0x100
	s_addc_u32 s52, s52, 0
	s_cmp_gt_u32 s53, 13
	s_barrier
	s_cbranch_scc0 .LBB0_1083
	v_mul_f32_e32 v143, 0xbfb8aa3b, v124
	v_exp_f32_e32 v143, v143
	v_mul_f32_e32 v145, 0xbfb8aa3b, v120
	v_mul_f32_e32 v151, 0xbfb8aa3b, v125
	v_exp_f32_e32 v145, v145
	v_exp_f32_e32 v151, v151
	v_add_f32_e32 v143, 1.0, v143
	v_rcp_f32_e32 v170, v143
	v_add_f32_e32 v143, 1.0, v145
	v_add_f32_e32 v145, 1.0, v151
	v_rcp_f32_e32 v171, v145
	v_mul_f32_e32 v145, 0xbfb8aa3b, v121
	v_exp_f32_e32 v145, v145
	v_rcp_f32_e32 v172, v143
	v_pk_mul_f32 v[124:125], v[124:125], v[170:171]
	v_mul_f32_e32 v143, 0xbfb8aa3b, v127
	v_pk_mul_f32 v[116:117], v[124:125], v[116:117]
	v_add_f32_e32 v124, 1.0, v145
	v_mul_f32_e32 v125, 0xbfb8aa3b, v122
	v_rcp_f32_e32 v173, v124
	v_mul_f32_e32 v124, 0xbfb8aa3b, v126
	v_exp_f32_e32 v125, v125
	v_exp_f32_e32 v124, v124
	v_exp_f32_e32 v143, v143
	v_mul_f32_e32 v145, 0xbfb8aa3b, v123
	v_exp_f32_e32 v145, v145
	v_add_f32_e32 v125, 1.0, v125
	v_add_f32_e32 v124, 1.0, v124
	v_rcp_f32_e32 v170, v125
	v_add_f32_e32 v125, 1.0, v143
	v_rcp_f32_e32 v124, v124
	v_rcp_f32_e32 v125, v125
	v_add_f32_e32 v143, 1.0, v145
	v_rcp_f32_e32 v171, v143
	v_pk_mul_f32 v[120:121], v[120:121], v[172:173]
	v_lshl_or_b32 v168, s49, 7, v138
	v_pk_mul_f32 v[112:113], v[120:121], v[112:113]
	v_pk_mul_f32 v[120:121], v[126:127], v[124:125]
	v_lshl_add_u32 v142, s20, 8, v136
	v_pk_mul_f32 v[118:119], v[120:121], v[118:119]
	v_pk_mul_f32 v[120:121], v[122:123], v[170:171]
	v_ashrrev_i32_e32 v169, 31, v168
	v_pk_mul_f32 v[114:115], v[120:121], v[114:115]
	v_cvt_pk_bf16_f32 v116, v116, v117
	v_cvt_pk_bf16_f32 v117, v118, v119
	v_cvt_pk_bf16_f32 v118, v112, v113
	v_mov_b64_e32 v[112:113], s[58:59]
	v_cvt_pk_bf16_f32 v119, v114, v115
	v_mad_i64_i32 v[120:121], s[22:23], v142, s48, v[112:113]
	v_lshlrev_b64 v[114:115], 1, v[168:169]
	v_lshl_add_u64 v[120:121], v[120:121], 0, v[114:115]
	global_store_dwordx4 v[120:121], v[116:119], off
	s_and_b64 vcc, exec, s[8:9]
	s_mov_b32 s49, s14
	v_mul_f32_e32 v116, 0xbfb8aa3b, v108
	v_mul_f32_e32 v117, 0xbfb8aa3b, v104
	v_mul_f32_e32 v118, 0xbfb8aa3b, v109
	v_exp_f32_e32 v116, v116
	v_exp_f32_e32 v117, v117
	v_exp_f32_e32 v118, v118
	s_mov_b32 s20, s12
	v_add_f32_e32 v116, 1.0, v116
	v_add_f32_e32 v119, 1.0, v117
	v_add_f32_e32 v117, 1.0, v118
	v_rcp_f32_e32 v116, v116
	v_rcp_f32_e32 v117, v117
	v_mul_f32_e32 v118, 0xbfb8aa3b, v105
	v_exp_f32_e32 v120, v118
	v_rcp_f32_e32 v118, v119
	v_pk_mul_f32 v[108:109], v[108:109], v[116:117]
	v_mul_f32_e32 v116, 0xbfb8aa3b, v111
	v_pk_mul_f32 v[100:101], v[108:109], v[100:101]
	v_add_f32_e32 v108, 1.0, v120
	v_rcp_f32_e32 v119, v108
	v_mul_f32_e32 v109, 0xbfb8aa3b, v106
	v_mul_f32_e32 v108, 0xbfb8aa3b, v110
	v_exp_f32_e32 v109, v109
	v_exp_f32_e32 v108, v108
	v_exp_f32_e32 v117, v116
	v_mul_f32_e32 v116, 0xbfb8aa3b, v107
	v_pk_mul_f32 v[104:105], v[104:105], v[118:119]
	v_exp_f32_e32 v118, v116
	v_add_f32_e32 v109, 1.0, v109
	v_add_f32_e32 v108, 1.0, v108
	v_rcp_f32_e32 v116, v109
	v_add_f32_e32 v109, 1.0, v117
	v_rcp_f32_e32 v108, v108
	v_rcp_f32_e32 v109, v109
	v_add_f32_e32 v117, 1.0, v118
	v_rcp_f32_e32 v117, v117
	v_pk_mul_f32 v[104:105], v[104:105], v[96:97]
	v_pk_mul_f32 v[96:97], v[110:111], v[108:109]
	s_mov_b64 s[24:25], s[18:19]
	v_pk_mul_f32 v[102:103], v[96:97], v[102:103]
	v_pk_mul_f32 v[96:97], v[106:107], v[116:117]
	s_nop 0
	v_pk_mul_f32 v[106:107], v[96:97], v[98:99]
	v_cvt_pk_bf16_f32 v96, v100, v101
	v_or_b32_e32 v100, 16, v142
	v_mad_i64_i32 v[100:101], s[22:23], v100, s48, v[112:113]
	v_cvt_pk_bf16_f32 v97, v102, v103
	v_cvt_pk_bf16_f32 v98, v104, v105
	v_cvt_pk_bf16_f32 v99, v106, v107
	v_lshl_add_u64 v[100:101], v[100:101], 0, v[114:115]
	global_store_dwordx4 v[100:101], v[96:99], off
	s_nop 1
	v_mul_f32_e32 v96, 0xbfb8aa3b, v92
	v_mul_f32_e32 v97, 0xbfb8aa3b, v88
	v_mul_f32_e32 v98, 0xbfb8aa3b, v93
	v_exp_f32_e32 v96, v96
	v_exp_f32_e32 v97, v97
	v_exp_f32_e32 v98, v98
	v_add_f32_e32 v96, 1.0, v96
	v_add_f32_e32 v99, 1.0, v97
	v_add_f32_e32 v97, 1.0, v98
	v_rcp_f32_e32 v96, v96
	v_rcp_f32_e32 v97, v97
	v_mul_f32_e32 v98, 0xbfb8aa3b, v89
	v_exp_f32_e32 v100, v98
	v_rcp_f32_e32 v98, v99
	v_pk_mul_f32 v[92:93], v[92:93], v[96:97]
	v_mul_f32_e32 v96, 0xbfb8aa3b, v95
	v_pk_mul_f32 v[84:85], v[92:93], v[84:85]
	v_add_f32_e32 v92, 1.0, v100
	v_rcp_f32_e32 v99, v92
	v_mul_f32_e32 v93, 0xbfb8aa3b, v90
	v_mul_f32_e32 v92, 0xbfb8aa3b, v94
	v_exp_f32_e32 v93, v93
	v_exp_f32_e32 v92, v92
	v_exp_f32_e32 v97, v96
	v_mul_f32_e32 v96, 0xbfb8aa3b, v91
	v_pk_mul_f32 v[88:89], v[88:89], v[98:99]
	v_exp_f32_e32 v98, v96
	v_add_f32_e32 v93, 1.0, v93
	v_add_f32_e32 v92, 1.0, v92
	v_rcp_f32_e32 v96, v93
	v_add_f32_e32 v93, 1.0, v97
	v_rcp_f32_e32 v92, v92
	v_rcp_f32_e32 v93, v93
	v_add_f32_e32 v97, 1.0, v98
	v_rcp_f32_e32 v97, v97
	v_pk_mul_f32 v[88:89], v[88:89], v[80:81]
	v_pk_mul_f32 v[80:81], v[94:95], v[92:93]
	s_nop 0
	v_pk_mul_f32 v[86:87], v[80:81], v[86:87]
	v_pk_mul_f32 v[80:81], v[90:91], v[96:97]
	s_nop 0
	v_pk_mul_f32 v[90:91], v[80:81], v[82:83]
	v_cvt_pk_bf16_f32 v80, v84, v85
	v_or_b32_e32 v84, 32, v142
	v_mad_i64_i32 v[84:85], s[22:23], v84, s48, v[112:113]
	v_cvt_pk_bf16_f32 v81, v86, v87
	v_cvt_pk_bf16_f32 v82, v88, v89
	v_cvt_pk_bf16_f32 v83, v90, v91
	v_lshl_add_u64 v[84:85], v[84:85], 0, v[114:115]
	global_store_dwordx4 v[84:85], v[80:83], off
	s_nop 1
	v_mul_f32_e32 v80, 0xbfb8aa3b, v76
	v_mul_f32_e32 v81, 0xbfb8aa3b, v72
	v_mul_f32_e32 v82, 0xbfb8aa3b, v77
	v_exp_f32_e32 v80, v80
	v_exp_f32_e32 v81, v81
	v_exp_f32_e32 v82, v82
	v_add_f32_e32 v80, 1.0, v80
	v_add_f32_e32 v83, 1.0, v81
	v_add_f32_e32 v81, 1.0, v82
	v_rcp_f32_e32 v80, v80
	v_rcp_f32_e32 v81, v81
	v_mul_f32_e32 v82, 0xbfb8aa3b, v73
	v_exp_f32_e32 v84, v82
	v_rcp_f32_e32 v82, v83
	v_pk_mul_f32 v[76:77], v[76:77], v[80:81]
	v_mul_f32_e32 v80, 0xbfb8aa3b, v79
	v_pk_mul_f32 v[68:69], v[76:77], v[68:69]
	v_add_f32_e32 v76, 1.0, v84
	v_rcp_f32_e32 v83, v76
	v_mul_f32_e32 v77, 0xbfb8aa3b, v74
	v_mul_f32_e32 v76, 0xbfb8aa3b, v78
	v_exp_f32_e32 v77, v77
	v_exp_f32_e32 v76, v76
	v_exp_f32_e32 v81, v80
	v_mul_f32_e32 v80, 0xbfb8aa3b, v75
	v_pk_mul_f32 v[72:73], v[72:73], v[82:83]
	v_exp_f32_e32 v82, v80
	v_add_f32_e32 v77, 1.0, v77
	v_add_f32_e32 v76, 1.0, v76
	v_rcp_f32_e32 v80, v77
	v_add_f32_e32 v77, 1.0, v81
	v_rcp_f32_e32 v76, v76
	v_rcp_f32_e32 v77, v77
	v_add_f32_e32 v81, 1.0, v82
	v_rcp_f32_e32 v81, v81
	v_pk_mul_f32 v[72:73], v[72:73], v[64:65]
	v_pk_mul_f32 v[64:65], v[78:79], v[76:77]
	s_nop 0
	v_pk_mul_f32 v[70:71], v[64:65], v[70:71]
	v_pk_mul_f32 v[64:65], v[74:75], v[80:81]
	s_nop 0
	v_pk_mul_f32 v[74:75], v[64:65], v[66:67]
	v_cvt_pk_bf16_f32 v64, v68, v69
	v_or_b32_e32 v68, 48, v142
	v_mad_i64_i32 v[68:69], s[22:23], v68, s48, v[112:113]
	v_cvt_pk_bf16_f32 v65, v70, v71
	v_cvt_pk_bf16_f32 v66, v72, v73
	v_cvt_pk_bf16_f32 v67, v74, v75
	v_lshl_add_u64 v[68:69], v[68:69], 0, v[114:115]
	global_store_dwordx4 v[68:69], v[64:67], off
	v_add_u32_e32 v68, 0x80, v142
	s_nop 0
	v_mul_f32_e32 v64, 0xbfb8aa3b, v60
	v_mul_f32_e32 v65, 0xbfb8aa3b, v56
	v_mul_f32_e32 v66, 0xbfb8aa3b, v61
	v_exp_f32_e32 v64, v64
	v_exp_f32_e32 v65, v65
	v_exp_f32_e32 v66, v66
	v_add_f32_e32 v64, 1.0, v64
	v_add_f32_e32 v67, 1.0, v65
	v_add_f32_e32 v65, 1.0, v66
	v_rcp_f32_e32 v64, v64
	v_rcp_f32_e32 v65, v65
	v_mul_f32_e32 v66, 0xbfb8aa3b, v57
	v_exp_f32_e32 v69, v66
	v_rcp_f32_e32 v66, v67
	v_pk_mul_f32 v[60:61], v[60:61], v[64:65]
	v_mul_f32_e32 v64, 0xbfb8aa3b, v63
	v_pk_mul_f32 v[52:53], v[60:61], v[52:53]
	v_add_f32_e32 v60, 1.0, v69
	v_rcp_f32_e32 v67, v60
	v_mul_f32_e32 v61, 0xbfb8aa3b, v58
	v_mul_f32_e32 v60, 0xbfb8aa3b, v62
	v_exp_f32_e32 v61, v61
	v_exp_f32_e32 v60, v60
	v_exp_f32_e32 v65, v64
	v_mul_f32_e32 v64, 0xbfb8aa3b, v59
	v_pk_mul_f32 v[56:57], v[56:57], v[66:67]
	v_exp_f32_e32 v66, v64
	v_add_f32_e32 v61, 1.0, v61
	v_add_f32_e32 v60, 1.0, v60
	v_rcp_f32_e32 v64, v61
	v_add_f32_e32 v61, 1.0, v65
	v_rcp_f32_e32 v60, v60
	v_rcp_f32_e32 v61, v61
	v_add_f32_e32 v65, 1.0, v66
	v_rcp_f32_e32 v65, v65
	v_pk_mul_f32 v[56:57], v[56:57], v[48:49]
	v_pk_mul_f32 v[48:49], v[62:63], v[60:61]
	s_nop 0
	v_pk_mul_f32 v[54:55], v[48:49], v[54:55]
	v_pk_mul_f32 v[48:49], v[58:59], v[64:65]
	s_nop 0
	v_pk_mul_f32 v[58:59], v[48:49], v[50:51]
	v_cvt_pk_bf16_f32 v48, v52, v53
	v_mad_i64_i32 v[52:53], s[22:23], v68, s48, v[112:113]
	v_cvt_pk_bf16_f32 v49, v54, v55
	v_cvt_pk_bf16_f32 v50, v56, v57
	v_cvt_pk_bf16_f32 v51, v58, v59
	v_lshl_add_u64 v[52:53], v[52:53], 0, v[114:115]
	global_store_dwordx4 v[52:53], v[48:51], off
	s_nop 1
	v_mul_f32_e32 v48, 0xbfb8aa3b, v44
	v_mul_f32_e32 v49, 0xbfb8aa3b, v40
	v_mul_f32_e32 v50, 0xbfb8aa3b, v45
	v_exp_f32_e32 v48, v48
	v_exp_f32_e32 v49, v49
	v_exp_f32_e32 v50, v50
	v_add_f32_e32 v48, 1.0, v48
	v_add_f32_e32 v51, 1.0, v49
	v_add_f32_e32 v49, 1.0, v50
	v_rcp_f32_e32 v48, v48
	v_rcp_f32_e32 v49, v49
	v_mul_f32_e32 v50, 0xbfb8aa3b, v41
	v_exp_f32_e32 v52, v50
	v_rcp_f32_e32 v50, v51
	v_pk_mul_f32 v[44:45], v[44:45], v[48:49]
	v_mul_f32_e32 v48, 0xbfb8aa3b, v47
	v_pk_mul_f32 v[36:37], v[44:45], v[36:37]
	v_add_f32_e32 v44, 1.0, v52
	v_rcp_f32_e32 v51, v44
	v_mul_f32_e32 v45, 0xbfb8aa3b, v42
	v_mul_f32_e32 v44, 0xbfb8aa3b, v46
	v_exp_f32_e32 v45, v45
	v_exp_f32_e32 v44, v44
	v_exp_f32_e32 v49, v48
	v_mul_f32_e32 v48, 0xbfb8aa3b, v43
	v_pk_mul_f32 v[40:41], v[40:41], v[50:51]
	v_exp_f32_e32 v50, v48
	v_add_f32_e32 v45, 1.0, v45
	v_add_f32_e32 v44, 1.0, v44
	v_rcp_f32_e32 v48, v45
	v_add_f32_e32 v45, 1.0, v49
	v_rcp_f32_e32 v44, v44
	v_rcp_f32_e32 v45, v45
	v_add_f32_e32 v49, 1.0, v50
	v_rcp_f32_e32 v49, v49
	v_pk_mul_f32 v[40:41], v[40:41], v[32:33]
	v_pk_mul_f32 v[32:33], v[46:47], v[44:45]
	s_nop 0
	v_pk_mul_f32 v[38:39], v[32:33], v[38:39]
	v_pk_mul_f32 v[32:33], v[42:43], v[48:49]
	s_nop 0
	v_pk_mul_f32 v[42:43], v[32:33], v[34:35]
	v_cvt_pk_bf16_f32 v32, v36, v37
	v_add_u32_e32 v36, 0x90, v142
	v_mad_i64_i32 v[36:37], s[22:23], v36, s48, v[112:113]
	v_cvt_pk_bf16_f32 v33, v38, v39
	v_cvt_pk_bf16_f32 v34, v40, v41
	v_cvt_pk_bf16_f32 v35, v42, v43
	v_lshl_add_u64 v[36:37], v[36:37], 0, v[114:115]
	global_store_dwordx4 v[36:37], v[32:35], off
	s_nop 1
	v_mul_f32_e32 v32, 0xbfb8aa3b, v28
	v_mul_f32_e32 v33, 0xbfb8aa3b, v24
	v_mul_f32_e32 v34, 0xbfb8aa3b, v29
	v_exp_f32_e32 v32, v32
	v_exp_f32_e32 v33, v33
	v_exp_f32_e32 v34, v34
	v_add_f32_e32 v32, 1.0, v32
	v_add_f32_e32 v35, 1.0, v33
	v_add_f32_e32 v33, 1.0, v34
	v_rcp_f32_e32 v32, v32
	v_rcp_f32_e32 v33, v33
	v_mul_f32_e32 v34, 0xbfb8aa3b, v25
	v_exp_f32_e32 v36, v34
	v_rcp_f32_e32 v34, v35
	v_pk_mul_f32 v[28:29], v[28:29], v[32:33]
	v_mul_f32_e32 v32, 0xbfb8aa3b, v31
	v_pk_mul_f32 v[20:21], v[28:29], v[20:21]
	v_add_f32_e32 v28, 1.0, v36
	v_rcp_f32_e32 v35, v28
	v_mul_f32_e32 v29, 0xbfb8aa3b, v26
	v_mul_f32_e32 v28, 0xbfb8aa3b, v30
	v_exp_f32_e32 v29, v29
	v_exp_f32_e32 v28, v28
	v_exp_f32_e32 v33, v32
	v_mul_f32_e32 v32, 0xbfb8aa3b, v27
	v_pk_mul_f32 v[24:25], v[24:25], v[34:35]
	v_exp_f32_e32 v34, v32
	v_add_f32_e32 v29, 1.0, v29
	v_add_f32_e32 v28, 1.0, v28
	v_rcp_f32_e32 v32, v29
	v_add_f32_e32 v29, 1.0, v33
	v_rcp_f32_e32 v28, v28
	v_rcp_f32_e32 v29, v29
	v_add_f32_e32 v33, 1.0, v34
	v_rcp_f32_e32 v33, v33
	v_pk_mul_f32 v[24:25], v[24:25], v[16:17]
	v_pk_mul_f32 v[16:17], v[30:31], v[28:29]
	s_nop 0
	v_pk_mul_f32 v[22:23], v[16:17], v[22:23]
	v_pk_mul_f32 v[16:17], v[26:27], v[32:33]
	s_nop 0
	v_pk_mul_f32 v[26:27], v[16:17], v[18:19]
	v_cvt_pk_bf16_f32 v16, v20, v21
	v_add_u32_e32 v20, 0xa0, v142
	v_mad_i64_i32 v[20:21], s[22:23], v20, s48, v[112:113]
	v_cvt_pk_bf16_f32 v17, v22, v23
	v_cvt_pk_bf16_f32 v18, v24, v25
	v_cvt_pk_bf16_f32 v19, v26, v27
	v_lshl_add_u64 v[20:21], v[20:21], 0, v[114:115]
	global_store_dwordx4 v[20:21], v[16:19], off
	s_nop 1
	v_mul_f32_e32 v16, 0xbfb8aa3b, v12
	v_mul_f32_e32 v17, 0xbfb8aa3b, v8
	v_mul_f32_e32 v18, 0xbfb8aa3b, v13
	v_exp_f32_e32 v16, v16
	v_exp_f32_e32 v17, v17
	v_exp_f32_e32 v18, v18
	v_add_f32_e32 v16, 1.0, v16
	v_add_f32_e32 v19, 1.0, v17
	v_add_f32_e32 v17, 1.0, v18
	v_rcp_f32_e32 v16, v16
	v_rcp_f32_e32 v17, v17
	v_mul_f32_e32 v18, 0xbfb8aa3b, v9
	v_exp_f32_e32 v20, v18
	v_rcp_f32_e32 v18, v19
	v_pk_mul_f32 v[12:13], v[12:13], v[16:17]
	v_mul_f32_e32 v16, 0xbfb8aa3b, v15
	v_pk_mul_f32 v[4:5], v[12:13], v[4:5]
	v_add_f32_e32 v12, 1.0, v20
	v_rcp_f32_e32 v19, v12
	v_mul_f32_e32 v13, 0xbfb8aa3b, v10
	v_mul_f32_e32 v12, 0xbfb8aa3b, v14
	v_exp_f32_e32 v13, v13
	v_exp_f32_e32 v12, v12
	v_exp_f32_e32 v17, v16
	v_mul_f32_e32 v16, 0xbfb8aa3b, v11
	v_pk_mul_f32 v[8:9], v[8:9], v[18:19]
	v_exp_f32_e32 v18, v16
	v_add_f32_e32 v13, 1.0, v13
	v_add_f32_e32 v12, 1.0, v12
	v_rcp_f32_e32 v16, v13
	v_add_f32_e32 v13, 1.0, v17
	v_rcp_f32_e32 v12, v12
	v_rcp_f32_e32 v13, v13
	v_add_f32_e32 v17, 1.0, v18
	v_rcp_f32_e32 v17, v17
	v_pk_mul_f32 v[8:9], v[8:9], v[0:1]
	v_pk_mul_f32 v[0:1], v[14:15], v[12:13]
	s_nop 0
	v_pk_mul_f32 v[6:7], v[0:1], v[6:7]
	v_pk_mul_f32 v[0:1], v[10:11], v[16:17]
	s_nop 0
	v_pk_mul_f32 v[10:11], v[0:1], v[2:3]
	v_cvt_pk_bf16_f32 v0, v4, v5
	v_add_u32_e32 v4, 0xb0, v142
	v_mad_i64_i32 v[4:5], s[22:23], v4, s48, v[112:113]
	v_cvt_pk_bf16_f32 v1, v6, v7
	v_cvt_pk_bf16_f32 v2, v8, v9
	v_cvt_pk_bf16_f32 v3, v10, v11
	v_lshl_add_u64 v[4:5], v[4:5], 0, v[114:115]
	s_mov_b64 s[22:23], s[16:17]
	global_store_dwordx4 v[4:5], v[0:3], off
	s_cbranch_vccz .LBB0_1080
	s_waitcnt vmcnt(0)
	s_cmpk_gt_u32 s3, 0xff
	s_cbranch_scc1 .LBB0_1087
	s_barrier

.LBB0_1151:
	ds_read_b128 v[158:161], v153
	ds_read_b128 v[162:165], v153 offset:1024
	ds_read_b128 v[168:171], v153 offset:2048
	ds_read_b128 v[172:175], v153 offset:3072
	s_add_u32 s22, s20, 0xfff50080
	s_addc_u32 s23, s21, -1
	s_cmp_eq_u32 s64, 40
	s_cselect_b32 s25, s1, s23
	s_cselect_b32 s24, s0, s22
	s_cselect_b32 s23, s9, s63
	s_cselect_b32 s22, s8, s62
	v_lshl_add_u64 v[184:185], s[20:21], 0, v[136:137]
	s_add_i32 m0, s33, 0xc000
	ds_read_b128 v[176:179], v155
	ds_read_b128 v[180:183], v155 offset:1024
	ds_read_b128 v[188:191], v155 offset:2048
	ds_read_b128 v[192:195], v155 offset:3072
	ds_read_b128 v[196:199], v155 offset:4096
	ds_read_b128 v[200:203], v155 offset:5120
	ds_read_b128 v[204:207], v155 offset:6144
	ds_read_b128 v[208:211], v155 offset:7168
	global_load_lds_dwordx4 v[184:185], off
	v_lshl_add_u64 v[184:185], s[20:21], 0, v[138:139]
	s_add_i32 m0, s33, 0xe000
	s_nop 0
	global_load_lds_dwordx4 v[184:185], off
	s_waitcnt lgkmcnt(8)
	s_barrier
	s_nop 0
	s_setprio 1
	s_waitcnt lgkmcnt(7)
	v_mfma_f32_16x16x32_bf16 v[124:127], v[158:161], v[176:179], v[124:127]
	v_mfma_f32_16x16x32_bf16 v[120:123], v[168:171], v[176:179], v[120:123]
	s_waitcnt lgkmcnt(5)
	v_mfma_f32_16x16x32_bf16 v[116:119], v[158:161], v[188:191], v[116:119]
	v_mfma_f32_16x16x32_bf16 v[112:115], v[168:171], v[188:191], v[112:115]
	s_waitcnt lgkmcnt(3)
	v_mfma_f32_16x16x32_bf16 v[100:103], v[158:161], v[196:199], v[100:103]
	v_mfma_f32_16x16x32_bf16 v[96:99], v[168:171], v[196:199], v[96:99]
	s_waitcnt lgkmcnt(1)
	v_mfma_f32_16x16x32_bf16 v[84:87], v[158:161], v[204:207], v[84:87]
	v_mfma_f32_16x16x32_bf16 v[80:83], v[168:171], v[204:207], v[80:83]
	v_mfma_f32_16x16x32_bf16 v[124:127], v[162:165], v[180:183], v[124:127]
	v_mfma_f32_16x16x32_bf16 v[120:123], v[172:175], v[180:183], v[120:123]
	v_mfma_f32_16x16x32_bf16 v[116:119], v[162:165], v[192:195], v[116:119]
	v_mfma_f32_16x16x32_bf16 v[112:115], v[172:175], v[192:195], v[112:115]
	v_mfma_f32_16x16x32_bf16 v[100:103], v[162:165], v[200:203], v[100:103]
	v_mfma_f32_16x16x32_bf16 v[96:99], v[172:175], v[200:203], v[96:99]
	s_waitcnt lgkmcnt(0)
	v_mfma_f32_16x16x32_bf16 v[84:87], v[162:165], v[208:211], v[84:87]
	v_mfma_f32_16x16x32_bf16 v[80:83], v[172:175], v[208:211], v[80:83]
	s_setprio 0
	s_barrier
	s_add_i32 s28, s47, s26
	v_lshl_add_u64 v[184:185], s[22:23], 0, v[132:133]
	s_mov_b32 m0, s28
	ds_read_b128 v[212:215], v156
	ds_read_b128 v[216:219], v156 offset:1024
	ds_read_b128 v[220:223], v156 offset:2048
	ds_read_b128 v[224:227], v156 offset:3072
	global_load_lds_dwordx4 v[184:185], off
	v_lshl_add_u64 v[228:229], s[22:23], 0, v[128:129]
	s_add_i32 m0, s28, 0x2000
	s_nop 0
	global_load_lds_dwordx4 v[228:229], off
	s_barrier
	s_nop 0
	s_setprio 1
	s_waitcnt lgkmcnt(3)
	v_mfma_f32_16x16x32_bf16 v[108:111], v[212:215], v[176:179], v[108:111]
	s_waitcnt lgkmcnt(1)
	v_mfma_f32_16x16x32_bf16 v[104:107], v[220:223], v[176:179], v[104:107]
	v_mfma_f32_16x16x32_bf16 v[92:95], v[212:215], v[188:191], v[92:95]
	v_mfma_f32_16x16x32_bf16 v[88:91], v[220:223], v[188:191], v[88:91]
	v_mfma_f32_16x16x32_bf16 v[76:79], v[212:215], v[196:199], v[76:79]
	v_mfma_f32_16x16x32_bf16 v[72:75], v[220:223], v[196:199], v[72:75]
	v_mfma_f32_16x16x32_bf16 v[68:71], v[212:215], v[204:207], v[68:71]
	v_mfma_f32_16x16x32_bf16 v[64:67], v[220:223], v[204:207], v[64:67]
	v_mfma_f32_16x16x32_bf16 v[108:111], v[216:219], v[180:183], v[108:111]
	s_waitcnt lgkmcnt(0)
	v_mfma_f32_16x16x32_bf16 v[104:107], v[224:227], v[180:183], v[104:107]
	v_mfma_f32_16x16x32_bf16 v[92:95], v[216:219], v[192:195], v[92:95]
	v_mfma_f32_16x16x32_bf16 v[88:91], v[224:227], v[192:195], v[88:91]
	v_mfma_f32_16x16x32_bf16 v[76:79], v[216:219], v[200:203], v[76:79]
	v_mfma_f32_16x16x32_bf16 v[72:75], v[224:227], v[200:203], v[72:75]
	v_mfma_f32_16x16x32_bf16 v[68:71], v[216:219], v[208:211], v[68:71]
	v_mfma_f32_16x16x32_bf16 v[64:67], v[224:227], v[208:211], v[64:67]
	s_setprio 0
	s_mov_b32 m0, s33
	v_lshl_add_u64 v[230:231], s[24:25], 0, v[134:135]
	s_barrier
	ds_read_b128 v[176:179], v155 offset:16384
	ds_read_b128 v[180:183], v155 offset:17408
	ds_read_b128 v[188:191], v155 offset:18432
	ds_read_b128 v[192:195], v155 offset:19456
	ds_read_b128 v[196:199], v155 offset:20480
	ds_read_b128 v[200:203], v155 offset:21504
	ds_read_b128 v[204:207], v155 offset:22528
	ds_read_b128 v[208:211], v155 offset:23552
	global_load_lds_dwordx4 v[230:231], off
	v_lshl_add_u64 v[232:233], s[24:25], 0, v[130:131]
	s_mov_b32 m0, s38
	s_nop 0
	global_load_lds_dwordx4 v[232:233], off
	s_barrier
	s_nop 0
	s_setprio 1
	s_waitcnt lgkmcnt(7)
	v_mfma_f32_16x16x32_bf16 v[60:63], v[158:161], v[176:179], v[60:63]
	v_mfma_f32_16x16x32_bf16 v[56:59], v[168:171], v[176:179], v[56:59]
	s_waitcnt lgkmcnt(5)
	v_mfma_f32_16x16x32_bf16 v[52:55], v[158:161], v[188:191], v[52:55]
	v_mfma_f32_16x16x32_bf16 v[48:51], v[168:171], v[188:191], v[48:51]
	s_waitcnt lgkmcnt(3)
	v_mfma_f32_16x16x32_bf16 v[36:39], v[158:161], v[196:199], v[36:39]
	v_mfma_f32_16x16x32_bf16 v[32:35], v[168:171], v[196:199], v[32:35]
	s_waitcnt lgkmcnt(1)
	v_mfma_f32_16x16x32_bf16 v[20:23], v[158:161], v[204:207], v[20:23]
	v_mfma_f32_16x16x32_bf16 v[16:19], v[168:171], v[204:207], v[16:19]
	v_mfma_f32_16x16x32_bf16 v[60:63], v[162:165], v[180:183], v[60:63]
	v_mfma_f32_16x16x32_bf16 v[56:59], v[172:175], v[180:183], v[56:59]
	v_mfma_f32_16x16x32_bf16 v[52:55], v[162:165], v[192:195], v[52:55]
	v_mfma_f32_16x16x32_bf16 v[48:51], v[172:175], v[192:195], v[48:51]
	v_mfma_f32_16x16x32_bf16 v[36:39], v[162:165], v[200:203], v[36:39]
	v_mfma_f32_16x16x32_bf16 v[32:35], v[172:175], v[200:203], v[32:35]
	s_waitcnt lgkmcnt(0)
	v_mfma_f32_16x16x32_bf16 v[20:23], v[162:165], v[208:211], v[20:23]
	v_mfma_f32_16x16x32_bf16 v[16:19], v[172:175], v[208:211], v[16:19]
	s_setprio 0
	s_barrier
	s_add_u32 s28, s22, 0xb0000
	s_addc_u32 s29, s23, 0
	s_add_i32 s65, s48, s26
	v_lshl_add_u64 v[158:159], s[28:29], 0, v[132:133]
	s_mov_b32 m0, s65
	s_nop 0
	global_load_lds_dwordx4 v[158:159], off
	v_lshl_add_u64 v[158:159], s[28:29], 0, v[128:129]
	s_add_i32 m0, s65, 0x2000
	s_nop 0
	global_load_lds_dwordx4 v[158:159], off
	s_waitcnt vmcnt(6)
	s_barrier
	s_setprio 1
	v_mfma_f32_16x16x32_bf16 v[44:47], v[212:215], v[176:179], v[44:47]
	v_mfma_f32_16x16x32_bf16 v[40:43], v[220:223], v[176:179], v[40:43]
	v_mfma_f32_16x16x32_bf16 v[28:31], v[212:215], v[188:191], v[28:31]
	v_mfma_f32_16x16x32_bf16 v[24:27], v[220:223], v[188:191], v[24:27]
	v_mfma_f32_16x16x32_bf16 v[12:15], v[212:215], v[196:199], v[12:15]
	v_mfma_f32_16x16x32_bf16 v[8:11], v[220:223], v[196:199], v[8:11]
	v_mfma_f32_16x16x32_bf16 v[4:7], v[212:215], v[204:207], v[4:7]
	v_mfma_f32_16x16x32_bf16 v[0:3], v[220:223], v[204:207], v[0:3]
	v_mfma_f32_16x16x32_bf16 v[44:47], v[216:219], v[180:183], v[44:47]
	v_mfma_f32_16x16x32_bf16 v[40:43], v[224:227], v[180:183], v[40:43]
	v_mfma_f32_16x16x32_bf16 v[28:31], v[216:219], v[192:195], v[28:31]
	v_mfma_f32_16x16x32_bf16 v[24:27], v[224:227], v[192:195], v[24:27]
	v_mfma_f32_16x16x32_bf16 v[12:15], v[216:219], v[200:203], v[12:15]
	v_mfma_f32_16x16x32_bf16 v[8:11], v[224:227], v[200:203], v[8:11]
	v_mfma_f32_16x16x32_bf16 v[4:7], v[216:219], v[208:211], v[4:7]
	v_mfma_f32_16x16x32_bf16 v[0:3], v[224:227], v[208:211], v[0:3]
	s_setprio 0
	s_add_i32 s28, 0, 0x18000
	v_add_u32_e32 v157, s28, v146
	s_barrier
	ds_read_b128 v[158:161], v157
	ds_read_b128 v[162:165], v157 offset:1024
	ds_read_b128 v[168:171], v157 offset:2048
	ds_read_b128 v[172:175], v157 offset:3072
	s_add_u32 s24, s24, 0xb0000
	s_addc_u32 s25, s25, 0
	s_mov_b32 m0, s39
	v_lshl_add_u64 v[212:213], s[24:25], 0, v[134:135]
	ds_read_b128 v[176:179], v155 offset:32768
	ds_read_b128 v[180:183], v155 offset:33792
	ds_read_b128 v[188:191], v155 offset:34816
	ds_read_b128 v[192:195], v155 offset:35840
	ds_read_b128 v[196:199], v155 offset:36864
	ds_read_b128 v[200:203], v155 offset:37888
	ds_read_b128 v[204:207], v155 offset:38912
	ds_read_b128 v[208:211], v155 offset:39936
	global_load_lds_dwordx4 v[212:213], off
	v_lshl_add_u64 v[212:213], s[24:25], 0, v[130:131]
	s_mov_b32 m0, s40
	s_nop 0
	global_load_lds_dwordx4 v[212:213], off
	s_waitcnt lgkmcnt(8)
	s_barrier
	s_nop 0
	s_setprio 1
	s_waitcnt lgkmcnt(7)
	v_mfma_f32_16x16x32_bf16 v[124:127], v[158:161], v[176:179], v[124:127]
	v_mfma_f32_16x16x32_bf16 v[120:123], v[168:171], v[176:179], v[120:123]
	s_waitcnt lgkmcnt(5)
	v_mfma_f32_16x16x32_bf16 v[116:119], v[158:161], v[188:191], v[116:119]
	v_mfma_f32_16x16x32_bf16 v[112:115], v[168:171], v[188:191], v[112:115]
	s_waitcnt lgkmcnt(3)
	v_mfma_f32_16x16x32_bf16 v[100:103], v[158:161], v[196:199], v[100:103]
	v_mfma_f32_16x16x32_bf16 v[96:99], v[168:171], v[196:199], v[96:99]
	s_waitcnt lgkmcnt(1)
	v_mfma_f32_16x16x32_bf16 v[84:87], v[158:161], v[204:207], v[84:87]
	v_mfma_f32_16x16x32_bf16 v[80:83], v[168:171], v[204:207], v[80:83]
	v_mfma_f32_16x16x32_bf16 v[124:127], v[162:165], v[180:183], v[124:127]
	v_mfma_f32_16x16x32_bf16 v[120:123], v[172:175], v[180:183], v[120:123]
	v_mfma_f32_16x16x32_bf16 v[116:119], v[162:165], v[192:195], v[116:119]
	v_mfma_f32_16x16x32_bf16 v[112:115], v[172:175], v[192:195], v[112:115]
	v_mfma_f32_16x16x32_bf16 v[100:103], v[162:165], v[200:203], v[100:103]
	v_mfma_f32_16x16x32_bf16 v[96:99], v[172:175], v[200:203], v[96:99]
	s_waitcnt lgkmcnt(0)
	v_mfma_f32_16x16x32_bf16 v[84:87], v[162:165], v[208:211], v[84:87]
	v_mfma_f32_16x16x32_bf16 v[80:83], v[172:175], v[208:211], v[80:83]
	s_setprio 0
	s_barrier
	s_add_i32 s24, 0, 0x1c000
	s_add_i32 s25, s28, s26
	v_add_u32_e32 v157, s24, v146
	v_lshl_add_u64 v[184:185], v[184:185], 0, s[10:11]
	s_mov_b32 m0, s25
	ds_read_b128 v[212:215], v157
	ds_read_b128 v[216:219], v157 offset:1024
	ds_read_b128 v[220:223], v157 offset:2048
	ds_read_b128 v[224:227], v157 offset:3072
	global_load_lds_dwordx4 v[184:185], off
	v_lshl_add_u64 v[184:185], v[228:229], 0, s[10:11]
	s_add_i32 m0, s25, 0x2000
	s_nop 0
	global_load_lds_dwordx4 v[184:185], off
	s_barrier
	s_nop 0
	s_setprio 1
	s_waitcnt lgkmcnt(3)
	v_mfma_f32_16x16x32_bf16 v[108:111], v[212:215], v[176:179], v[108:111]
	s_waitcnt lgkmcnt(1)
	v_mfma_f32_16x16x32_bf16 v[104:107], v[220:223], v[176:179], v[104:107]
	v_mfma_f32_16x16x32_bf16 v[92:95], v[212:215], v[188:191], v[92:95]
	v_mfma_f32_16x16x32_bf16 v[88:91], v[220:223], v[188:191], v[88:91]
	v_mfma_f32_16x16x32_bf16 v[76:79], v[212:215], v[196:199], v[76:79]
	v_mfma_f32_16x16x32_bf16 v[72:75], v[220:223], v[196:199], v[72:75]
	v_mfma_f32_16x16x32_bf16 v[68:71], v[212:215], v[204:207], v[68:71]
	v_mfma_f32_16x16x32_bf16 v[64:67], v[220:223], v[204:207], v[64:67]
	v_mfma_f32_16x16x32_bf16 v[108:111], v[216:219], v[180:183], v[108:111]
	s_waitcnt lgkmcnt(0)
	v_mfma_f32_16x16x32_bf16 v[104:107], v[224:227], v[180:183], v[104:107]
	v_mfma_f32_16x16x32_bf16 v[92:95], v[216:219], v[192:195], v[92:95]
	v_mfma_f32_16x16x32_bf16 v[88:91], v[224:227], v[192:195], v[88:91]
	v_mfma_f32_16x16x32_bf16 v[76:79], v[216:219], v[200:203], v[76:79]
	v_mfma_f32_16x16x32_bf16 v[72:75], v[224:227], v[200:203], v[72:75]
	v_mfma_f32_16x16x32_bf16 v[68:71], v[216:219], v[208:211], v[68:71]
	v_mfma_f32_16x16x32_bf16 v[64:67], v[224:227], v[208:211], v[64:67]
	s_setprio 0
	s_mov_b32 m0, s43
	v_lshl_add_u64 v[184:185], v[230:231], 0, s[10:11]
	s_barrier
	ds_read_b128 v[176:179], v155 offset:49152
	ds_read_b128 v[180:183], v155 offset:50176
	ds_read_b128 v[188:191], v155 offset:51200
	ds_read_b128 v[192:195], v155 offset:52224
	ds_read_b128 v[196:199], v155 offset:53248
	ds_read_b128 v[200:203], v155 offset:54272
	ds_read_b128 v[204:207], v155 offset:55296
	ds_read_b128 v[208:211], v155 offset:56320
	global_load_lds_dwordx4 v[184:185], off
	v_lshl_add_u64 v[184:185], v[232:233], 0, s[10:11]
	s_mov_b32 m0, s44
	s_nop 0
	global_load_lds_dwordx4 v[184:185], off
	s_barrier
	s_nop 0
	s_setprio 1
	s_waitcnt lgkmcnt(7)
	v_mfma_f32_16x16x32_bf16 v[60:63], v[158:161], v[176:179], v[60:63]
	v_mfma_f32_16x16x32_bf16 v[56:59], v[168:171], v[176:179], v[56:59]
	s_waitcnt lgkmcnt(5)
	v_mfma_f32_16x16x32_bf16 v[52:55], v[158:161], v[188:191], v[52:55]
	v_mfma_f32_16x16x32_bf16 v[48:51], v[168:171], v[188:191], v[48:51]
	s_waitcnt lgkmcnt(3)
	v_mfma_f32_16x16x32_bf16 v[36:39], v[158:161], v[196:199], v[36:39]
	v_mfma_f32_16x16x32_bf16 v[32:35], v[168:171], v[196:199], v[32:35]
	s_waitcnt lgkmcnt(1)
	v_mfma_f32_16x16x32_bf16 v[20:23], v[158:161], v[204:207], v[20:23]
	v_mfma_f32_16x16x32_bf16 v[16:19], v[168:171], v[204:207], v[16:19]
	v_mfma_f32_16x16x32_bf16 v[60:63], v[162:165], v[180:183], v[60:63]
	v_mfma_f32_16x16x32_bf16 v[56:59], v[172:175], v[180:183], v[56:59]
	v_mfma_f32_16x16x32_bf16 v[52:55], v[162:165], v[192:195], v[52:55]
	v_mfma_f32_16x16x32_bf16 v[48:51], v[172:175], v[192:195], v[48:51]
	v_mfma_f32_16x16x32_bf16 v[36:39], v[162:165], v[200:203], v[36:39]
	v_mfma_f32_16x16x32_bf16 v[32:35], v[172:175], v[200:203], v[32:35]
	s_waitcnt lgkmcnt(0)
	v_mfma_f32_16x16x32_bf16 v[20:23], v[162:165], v[208:211], v[20:23]
	v_mfma_f32_16x16x32_bf16 v[16:19], v[172:175], v[208:211], v[16:19]
	s_setprio 0
	s_barrier
	s_add_u32 s22, s22, 0xb0080
	s_addc_u32 s23, s23, 0
	s_add_i32 s24, s24, s26
	v_lshl_add_u64 v[158:159], s[22:23], 0, v[132:133]
	s_mov_b32 m0, s24
	s_nop 0
	global_load_lds_dwordx4 v[158:159], off
	v_lshl_add_u64 v[158:159], s[22:23], 0, v[128:129]
	s_add_i32 m0, s24, 0x2000
	s_nop 0
	global_load_lds_dwordx4 v[158:159], off
	s_waitcnt vmcnt(6)
	s_barrier
	s_setprio 1
	v_mfma_f32_16x16x32_bf16 v[44:47], v[212:215], v[176:179], v[44:47]
	v_mfma_f32_16x16x32_bf16 v[40:43], v[220:223], v[176:179], v[40:43]
	v_mfma_f32_16x16x32_bf16 v[28:31], v[212:215], v[188:191], v[28:31]
	v_mfma_f32_16x16x32_bf16 v[24:27], v[220:223], v[188:191], v[24:27]
	v_mfma_f32_16x16x32_bf16 v[12:15], v[212:215], v[196:199], v[12:15]
	v_mfma_f32_16x16x32_bf16 v[8:11], v[220:223], v[196:199], v[8:11]
	v_mfma_f32_16x16x32_bf16 v[4:7], v[212:215], v[204:207], v[4:7]
	v_mfma_f32_16x16x32_bf16 v[0:3], v[220:223], v[204:207], v[0:3]
	v_mfma_f32_16x16x32_bf16 v[44:47], v[216:219], v[180:183], v[44:47]
	v_mfma_f32_16x16x32_bf16 v[40:43], v[224:227], v[180:183], v[40:43]
	v_mfma_f32_16x16x32_bf16 v[28:31], v[216:219], v[192:195], v[28:31]
	v_mfma_f32_16x16x32_bf16 v[24:27], v[224:227], v[192:195], v[24:27]
	v_mfma_f32_16x16x32_bf16 v[12:15], v[216:219], v[200:203], v[12:15]
	v_mfma_f32_16x16x32_bf16 v[8:11], v[224:227], v[200:203], v[8:11]
	v_mfma_f32_16x16x32_bf16 v[4:7], v[216:219], v[208:211], v[4:7]
	v_mfma_f32_16x16x32_bf16 v[0:3], v[224:227], v[208:211], v[0:3]
	s_setprio 0
	s_add_i32 s64, s64, 2
	s_add_u32 s62, s62, 0x100
	s_addc_u32 s63, s63, 0
	s_add_u32 s20, s20, 0x100
	s_addc_u32 s21, s21, 0
	s_cmp_gt_u32 s64, 41
	s_barrier
	s_cbranch_scc0 .LBB0_1151
	s_cmp_eq_u32 s54, 0
	s_cselect_b32 s20, s49, 0x19a22000
	s_add_u32 s20, s34, s20
	v_lshl_or_b32 v158, s61, 8, v151
	v_lshl_add_u32 v160, s56, 8, v145
	s_addc_u32 s21, s35, 0
	v_ashrrev_i32_e32 v159, 31, v158
	v_ashrrev_i32_e32 v161, 31, v160
	v_lshl_add_u64 v[158:159], v[158:159], 1, s[20:21]
	v_lshlrev_b64 v[162:163], 11, v[160:161]
	v_lshl_add_u64 v[162:163], v[158:159], 0, v[162:163]
	v_cvt_pk_bf16_f32 v60, v60, v61
	v_cvt_pk_bf16_f32 v61, v62, v63
	v_cvt_pk_bf16_f32 v62, v56, v57
	v_add_co_u32_e32 v56, vcc, s50, v162
	v_cvt_pk_bf16_f32 v68, v68, v69
	v_cvt_pk_bf16_f32 v69, v70, v71
	v_cvt_pk_bf16_f32 v70, v64, v65
	v_lshl_add_u64 v[64:65], v[162:163], 0, s[12:13]
	v_addc_co_u32_e32 v57, vcc, 0, v163, vcc
	v_cvt_pk_bf16_f32 v44, v44, v45
	v_cvt_pk_bf16_f32 v45, v46, v47
	v_cvt_pk_bf16_f32 v46, v40, v41
	v_cvt_pk_bf16_f32 v47, v42, v43
	global_store_dwordx4 v[64:65], v[44:47], off offset:256
	v_cvt_pk_bf16_f32 v108, v108, v109
	v_cvt_pk_bf16_f32 v109, v110, v111
	v_add_co_u32_e32 v46, vcc, s51, v162
	v_cvt_pk_bf16_f32 v110, v104, v105
	v_or_b32_e32 v104, 16, v160
	v_lshl_add_u64 v[44:45], v[162:163], 0, s[14:15]
	v_addc_co_u32_e32 v47, vcc, 0, v163, vcc
	v_cvt_pk_bf16_f32 v28, v28, v29
	v_cvt_pk_bf16_f32 v29, v30, v31
	v_cvt_pk_bf16_f32 v30, v24, v25
	v_cvt_pk_bf16_f32 v31, v26, v27
	v_ashrrev_i32_e32 v105, 31, v104
	v_cvt_pk_bf16_f32 v92, v92, v93
	v_cvt_pk_bf16_f32 v93, v94, v95
	v_cvt_pk_bf16_f32 v94, v88, v89
	v_or_b32_e32 v88, 32, v160
	global_store_dwordx4 v[44:45], v[28:31], off offset:256
	v_cvt_pk_bf16_f32 v111, v106, v107
	v_lshlrev_b64 v[104:105], 11, v[104:105]
	v_add_co_u32_e32 v30, vcc, s52, v162
	v_ashrrev_i32_e32 v89, 31, v88
	v_cvt_pk_bf16_f32 v76, v76, v77
	v_cvt_pk_bf16_f32 v77, v78, v79
	v_cvt_pk_bf16_f32 v78, v72, v73
	v_or_b32_e32 v72, 48, v160
	v_lshl_add_u64 v[28:29], v[162:163], 0, s[16:17]
	v_addc_co_u32_e32 v31, vcc, 0, v163, vcc
	v_cvt_pk_bf16_f32 v12, v12, v13
	v_cvt_pk_bf16_f32 v13, v14, v15
	v_cvt_pk_bf16_f32 v14, v8, v9
	v_cvt_pk_bf16_f32 v15, v10, v11
	global_store_dwordx4 v[162:163], v[108:111], off offset:256
	v_cvt_pk_bf16_f32 v95, v90, v91
	v_lshlrev_b64 v[88:89], 11, v[88:89]
	v_lshl_add_u64 v[108:109], v[158:159], 0, v[104:105]
	v_ashrrev_i32_e32 v73, 31, v72
	global_store_dwordx4 v[28:29], v[12:15], off offset:256
	global_store_dwordx4 v[108:109], v[92:95], off offset:256
	v_cvt_pk_bf16_f32 v79, v74, v75
	v_add_co_u32_e32 v14, vcc, s53, v162
	v_lshl_add_u64 v[92:93], v[158:159], 0, v[88:89]
	v_lshlrev_b64 v[72:73], 11, v[72:73]
	v_addc_co_u32_e32 v15, vcc, 0, v163, vcc
	v_cvt_pk_bf16_f32 v124, v124, v125
	v_cvt_pk_bf16_f32 v125, v126, v127
	v_cvt_pk_bf16_f32 v126, v120, v121
	v_cvt_pk_bf16_f32 v127, v122, v123
	v_cvt_pk_bf16_f32 v104, v116, v117
	v_cvt_pk_bf16_f32 v105, v118, v119
	v_cvt_pk_bf16_f32 v106, v112, v113
	v_cvt_pk_bf16_f32 v107, v114, v115
	v_cvt_pk_bf16_f32 v88, v100, v101
	v_cvt_pk_bf16_f32 v89, v102, v103
	v_cvt_pk_bf16_f32 v90, v96, v97
	v_cvt_pk_bf16_f32 v91, v98, v99
	global_store_dwordx4 v[92:93], v[76:79], off offset:256
	v_cvt_pk_bf16_f32 v74, v80, v81
	v_cvt_pk_bf16_f32 v75, v82, v83
	v_lshl_add_u64 v[76:77], v[158:159], 0, v[72:73]
	v_cvt_pk_bf16_f32 v72, v84, v85
	v_cvt_pk_bf16_f32 v73, v86, v87
	v_cvt_pk_bf16_f32 v71, v66, v67
	v_cvt_pk_bf16_f32 v63, v58, v59
	v_cvt_pk_bf16_f32 v40, v52, v53
	v_cvt_pk_bf16_f32 v41, v54, v55
	v_cvt_pk_bf16_f32 v42, v48, v49
	v_cvt_pk_bf16_f32 v43, v50, v51
	v_cvt_pk_bf16_f32 v24, v36, v37
	v_cvt_pk_bf16_f32 v25, v38, v39
	v_cvt_pk_bf16_f32 v26, v32, v33
	v_cvt_pk_bf16_f32 v27, v34, v35
	v_lshl_add_u64 v[12:13], v[162:163], 0, s[18:19]
	v_cvt_pk_bf16_f32 v8, v20, v21
	v_cvt_pk_bf16_f32 v9, v22, v23
	v_cvt_pk_bf16_f32 v10, v16, v17
	v_cvt_pk_bf16_f32 v11, v18, v19
	v_cvt_pk_bf16_f32 v4, v4, v5
	v_cvt_pk_bf16_f32 v5, v6, v7
	v_cvt_pk_bf16_f32 v6, v0, v1
	v_cvt_pk_bf16_f32 v7, v2, v3
	s_and_b64 vcc, exec, s[6:7]
	s_mov_b32 s54, s55
	s_mov_b32 s61, s57
	s_mov_b32 s56, s60
	s_mov_b64 s[20:21], s[8:9]
	s_mov_b64 s[22:23], s[0:1]
	global_store_dwordx4 v[162:163], v[124:127], off
	global_store_dwordx4 v[108:109], v[104:107], off
	global_store_dwordx4 v[92:93], v[88:91], off
	global_store_dwordx4 v[76:77], v[72:75], off
	global_store_dwordx4 v[76:77], v[68:71], off offset:256
	global_store_dwordx4 v[56:57], v[60:63], off
	global_store_dwordx4 v[46:47], v[40:43], off
	global_store_dwordx4 v[30:31], v[24:27], off
	global_store_dwordx4 v[14:15], v[8:11], off
	global_store_dwordx4 v[12:13], v[4:7], off offset:256
	s_cbranch_vccz .LBB0_1144
	s_waitcnt vmcnt(0)
	s_cmpk_gt_u32 s3, 0xff
	s_cbranch_scc1 .LBB0_1155
	s_barrier
